# lora phase: LDS-staged weights+params, 8-wave split, piece path folded into main path; P1 layer0 per-wave param loads
# speedup vs baseline: 1.0241x; 1.0241x over previous
.LBB0_124:
	s_or_b64 exec, exec, s[0:1]
	s_add_u32 s30, s14, 0x1670000
	s_addc_u32 s31, s15, 0
	s_add_u32 s0, s14, 0x1340000
	s_addc_u32 s1, s15, 0
	s_lshl_b32 s20, s13, 3
	s_abs_i32 s5, s20
	s_waitcnt lgkmcnt(0)
	v_cvt_f32_u32_e32 v0, s5
	v_writelane_b32 v250, s0, 6
	s_bfe_i32 s4, s13, 0x1001c
	s_mov_b32 s52, 0
	v_rcp_iflag_f32_e32 v1, v0
	v_writelane_b32 v250, s1, 7
	s_sub_i32 s0, 0, s5
	v_mov_b32_e32 v0, v154
	v_mul_f32_e32 v1, 0x4f7ffffe, v1
	v_cvt_u32_f32_e32 v1, v1
	s_movk_i32 s53, 0x4000
	s_barrier
	v_readfirstlane_b32 s1, v1
	s_mul_i32 s0, s0, s1
	s_mul_hi_u32 s0, s1, s0
	s_add_i32 s0, s1, s0
	v_writelane_b32 v250, s0, 8
	s_lshr_b32 s0, s0, 18
	s_mul_i32 s1, s0, s5
	s_sub_i32 s1, 0x4000, s1
	s_add_i32 s2, s0, 1
	s_sub_i32 s3, s1, s5
	s_cmp_ge_u32 s1, s5
	s_cselect_b32 s0, s2, s0
	s_cselect_b32 s1, s3, s1
	s_add_i32 s2, s0, 1
	s_cmp_ge_u32 s1, s5
	s_cselect_b32 s0, s2, s0
	s_xor_b32 s0, s0, s4
	v_writelane_b32 v250, s5, 10
	s_sub_i32 s21, s0, s4
	v_writelane_b32 v250, s4, 12
	s_cmp_gt_i32 s21, -1
	v_writelane_b32 v250, s0, 13
	s_cselect_b64 s[0:1], -1, 0
	v_writelane_b32 v250, s0, 14
	s_cmp_lt_i32 s21, 0
	s_nop 0
	v_writelane_b32 v250, s1, 15
	s_cbranch_scc1 .LBB0_154
	s_mul_i32 s1, s21, s20
	v_ashrrev_i32_e32 v1, 6, v0
	s_sub_i32 s0, 0x4280, s1
	v_mul_lo_u32 v2, v1, s13
	v_lshlrev_b32_e32 v0, 3, v0
	s_add_u32 s4, s74, 0x4500000
	v_add_u32_e32 v2, s91, v2
	v_and_b32_e32 v16, 0x1f8, v0
	s_addc_u32 s5, s75, 0
	v_cmp_gt_i32_e32 vcc, s0, v2
	v_add_u32_e32 v17, s1, v2
	v_mov_b32_e32 v19, 0
	v_or_b32_e32 v0, 4, v16
	v_or_b32_e32 v2, 0x200, v16
	v_or_b32_e32 v4, 0x204, v16
	s_add_u32 s6, s74, 0x4200000
	v_lshlrev_b32_e32 v18, 2, v16
	s_addc_u32 s7, s75, 0
	v_lshl_add_u64 v[20:21], s[38:39], 0, v[18:19]
	v_lshl_add_u64 v[22:23], s[24:25], 0, v[18:19]
	v_lshl_add_u32 v42, s91, 3, v1
	v_lshlrev_b32_e32 v42, 3, v42
	s_add_i32 s72, s21, 1
	s_mov_b64 s[8:9], 0
	s_movk_i32 s73, 0x4200
	s_movk_i32 s76, 0x7ff
	v_mov_b32_e32 v43, 0x358637bd
	s_mov_b32 s77, 0x800000
	s_movk_i32 s78, 0x6000
	s_mov_b64 s[22:23], 0x1000
	v_lshlrev_b32_e32 v24, 2, v0
	v_lshlrev_b32_e32 v26, 2, v2
	v_lshlrev_b32_e32 v28, 2, v4
	s_mov_b64 s[36:37], 0x400
	v_lshlrev_b32_e32 v18, 2, v16
	v_mov_b32_e32 v44, 0x3a800000
	s_branch .LBB0_127

.LBB0_129:
	v_mov_b32_e32 v0, 2
	s_and_saveexec_b64 s[42:43], s[0:1]
	s_cbranch_execz .LBB0_149
	v_cmp_gt_i32_e64 s[0:1], s73, v30
	s_and_saveexec_b64 s[2:3], s[0:1]
	s_xor_b64 s[48:49], exec, s[2:3]
	s_cbranch_execz .LBB0_146
	s_cmp_eq_u32 s52, 0
	s_cbranch_scc1 .Lp1_ld0
	s_cmp_lt_i32 s52, s21
	s_cbranch_scc1 .Lp1_skip0
.Lp1_ld0:
	v_add_u32_e32 v58, 0xffffc000, v30
	v_lshrrev_b32_e32 v58, 2, v58
	v_add_u32_e32 v58, 8, v58
	v_ashrrev_i32_e32 v59, 11, v30
	v_cmp_gt_i32_e64 s[96:97], s53, v30
	v_readlane_b32 s94, v250, 6
	v_readlane_b32 s95, v250, 7
	v_cndmask_b32_e64 v110, v58, v59, s[96:97]
	v_mov_b64_e32 v[58:59], s[94:95]
	v_mad_i64_i32 v[58:59], s[96:97], v110, s78, v[58:59]
	v_lshl_add_u64 v[58:59], v[58:59], 0, v[18:19]
	v_lshl_add_u64 v[60:61], v[58:59], 0, s[22:23]
	global_load_dwordx4 v[62:65], v[20:21], off
	global_load_dwordx4 v[66:69], v[20:21], off offset:16
	global_load_dwordx4 v[70:73], v[20:21], off offset:2048
	global_load_dwordx4 v[74:77], v[20:21], off offset:2064
	global_load_dwordx4 v[78:81], v[60:61], off
	global_load_dwordx4 v[82:85], v[60:61], off offset:16
	global_load_dwordx4 v[86:89], v[60:61], off offset:2048
	global_load_dwordx4 v[90:93], v[60:61], off offset:2064
	global_load_dwordx4 v[94:97], v[58:59], off
	global_load_dwordx4 v[98:101], v[58:59], off offset:16
	global_load_dwordx4 v[102:105], v[58:59], off offset:2048
	global_load_dwordx4 v[106:109], v[58:59], off offset:2064
.Lp1_skip0:
	v_add_u32_e32 v25, 0xffffc000, v30
	v_ashrrev_i32_e32 v31, 31, v30
	v_cmp_gt_i32_e64 s[0:1], s53, v30
	v_mov_b32_e32 v2, s19
	v_mov_b32_e32 v3, s17
	v_cndmask_b32_e64 v1, 0, v31, s[0:1]
	v_cndmask_b32_e64 v0, v25, v30, s[0:1]
	v_cndmask_b32_e64 v3, v2, v3, s[0:1]
	v_mov_b32_e32 v2, s18
	v_mov_b32_e32 v4, s16
	v_cndmask_b32_e64 v2, v2, v4, s[0:1]
	v_lshlrev_b64 v[0:1], 12, v[0:1]
	v_lshl_add_u64 v[0:1], v[2:3], 0, v[0:1]
	v_lshl_add_u64 v[0:1], v[0:1], 0, v[18:19]
	global_load_dwordx4 v[12:15], v[0:1], off
	global_load_dwordx4 v[8:11], v[0:1], off offset:16
	global_load_dwordx4 v[4:7], v[0:1], off offset:2048
	s_nop 0
	global_load_dwordx4 v[0:3], v[0:1], off offset:2064
	v_and_b32_e32 v32, 0x7ff, v30
	v_and_b32_e32 v33, 3, v30
	v_cmp_eq_u32_e64 s[2:3], s76, v32
	v_lshrrev_b32_e32 v25, 2, v25
	v_ashrrev_i32_e32 v27, 11, v30
	v_cndmask_b32_e64 v32, 0, 1, s[2:3]
	v_cmp_eq_u32_e64 s[2:3], 3, v33
	v_add_u32_e32 v25, 8, v25
	v_cndmask_b32_e64 v34, v25, v27, s[0:1]
	v_cndmask_b32_e64 v33, 0, 1, s[2:3]
	v_cndmask_b32_e64 v32, v33, v32, s[0:1]
	v_and_b32_e32 v25, 1, v32
	v_cmp_eq_u32_e64 s[2:3], 1, v25
	v_mov_b32_e32 v29, v19
	v_mov_b32_e32 v35, v19
	s_waitcnt vmcnt(3)
	v_mov_b32_e32 v36, v13
	s_waitcnt vmcnt(2)
	v_mov_b32_e32 v37, v9
	v_mov_b32_e32 v32, v12
	v_mov_b32_e32 v33, v8
	s_waitcnt vmcnt(1)
	v_mov_b32_e32 v48, v5
	s_waitcnt vmcnt(0)
	v_mov_b32_e32 v49, v1
	v_pk_mul_f32 v[36:37], v[36:37], v[36:37]
	v_mov_b32_e32 v38, v14
	v_mov_b32_e32 v39, v10
	v_mov_b32_e32 v46, v4
	v_mov_b32_e32 v47, v0
	v_pk_mul_f32 v[48:49], v[48:49], v[48:49]
	v_pk_fma_f32 v[32:33], v[32:33], v[32:33], v[36:37]
	v_mov_b32_e32 v40, v15
	v_mov_b32_e32 v41, v11
	v_mov_b32_e32 v50, v6
	v_mov_b32_e32 v51, v2
	v_pk_fma_f32 v[36:37], v[46:47], v[46:47], v[48:49]
	v_pk_fma_f32 v[32:33], v[38:39], v[38:39], v[32:33]
	v_mov_b32_e32 v52, v7
	v_mov_b32_e32 v53, v3
	v_pk_fma_f32 v[36:37], v[50:51], v[50:51], v[36:37]
	v_pk_fma_f32 v[32:33], v[40:41], v[40:41], v[32:33]
	v_pk_fma_f32 v[36:37], v[52:53], v[52:53], v[36:37]
	v_add_f32_e32 v25, v32, v33
	v_add_f32_e32 v25, v25, v36
	v_add_f32_e32 v25, v25, v37
	v_mov_b64_e32 v[32:33], 0
	s_nop 0
	v_add_f32_dpp v25, v25, v25 row_ror:8 row_mask:0xf bank_mask:0xf bound_ctrl:1
	s_nop 1
	v_add_f32_dpp v25, v25, v25 row_ror:4 row_mask:0xf bank_mask:0xf bound_ctrl:1
	s_nop 1
	v_add_f32_dpp v25, v25, v25 row_ror:2 row_mask:0xf bank_mask:0xf bound_ctrl:1
	s_nop 1
	v_add_f32_dpp v25, v25, v25 row_ror:1 row_mask:0xf bank_mask:0xf bound_ctrl:1
	s_nop 1
	v_mov_b32_dpp v29, v25 row_bcast:15 row_mask:0xa bank_mask:0xf
	v_add_f32_e32 v25, v25, v29
	s_nop 1
	v_mov_b32_dpp v35, v25 row_bcast:31 row_mask:0xc bank_mask:0xf
	v_add_f32_e32 v25, v25, v35
	s_nop 0
	v_readlane_b32 s12, v25, 63
	s_and_saveexec_b64 s[10:11], s[2:3]
	s_cbranch_execz .LBB0_137
	v_cmp_lt_i32_e64 s[0:1], 7, v34
	s_and_saveexec_b64 s[34:35], s[0:1]
	s_xor_b64 s[0:1], exec, s[34:35]
	v_add_u32_e32 v32, -8, v34
	v_mov_b32_e32 v33, v19
	v_lshlrev_b64 v[32:33], 12, v[32:33]
	v_lshl_add_u64 v[32:33], s[4:5], 0, v[32:33]
	s_andn2_saveexec_b64 s[0:1], s[0:1]
	v_ashrrev_i32_e32 v35, 31, v34
	v_lshlrev_b64 v[32:33], 12, v[34:35]
	v_lshl_add_u64 v[32:33], s[6:7], 0, v[32:33]
	s_or_b64 exec, exec, s[0:1]
.LBB0_137:
	s_or_b64 exec, exec, s[10:11]
	v_readlane_b32 s0, v250, 6
	v_readlane_b32 s1, v250, 7
	v_fma_f32 v25, s12, v44, v43
	v_mov_b64_e32 v[36:37], s[0:1]
	v_mad_i64_i32 v[36:37], s[0:1], v34, s78, v[36:37]
	v_lshl_add_u64 v[34:35], v[36:37], 0, s[22:23]
	v_lshl_add_u64 v[38:39], v[34:35], 0, v[18:19]
	v_lshl_add_u64 v[36:37], v[36:37], 0, v[18:19]
	v_mul_f32_e32 v27, 0x4b800000, v25
	v_cmp_gt_f32_e64 s[0:1], s77, v25
	v_pk_add_f32 v[40:41], v[80:81], 1.0 op_sel_hi:[1,0]
	v_cndmask_b32_e64 v25, v25, v27, s[0:1]
	v_rsq_f32_e32 v25, v25
	s_nop 0
	v_mul_f32_e32 v27, 0x45800000, v25
	v_cndmask_b32_e64 v38, v25, v27, s[0:1]
	v_pk_mul_f32 v[14:15], v[14:15], v[38:39] op_sel_hi:[1,0]
	v_pk_mul_f32 v[12:13], v[12:13], v[38:39] op_sel_hi:[1,0]
	v_pk_mul_f32 v[14:15], v[14:15], v[64:65]
	v_pk_mul_f32 v[12:13], v[12:13], v[62:63]
	v_pk_add_f32 v[46:47], v[78:79], 1.0 op_sel_hi:[1,0]
	v_pk_fma_f32 v[14:15], v[14:15], v[40:41], v[96:97]
	v_pk_fma_f32 v[12:13], v[12:13], v[46:47], v[94:95]
	s_and_saveexec_b64 s[0:1], s[2:3]
	s_cbranch_execz .LBB0_139
	v_lshl_add_u64 v[40:41], v[32:33], 0, v[18:19]
	global_store_dwordx4 v[40:41], v[12:15], off
.LBB0_139:
	s_or_b64 exec, exec, s[0:1]
	v_mov_b32_e32 v25, v19
	v_lshl_add_u64 v[40:41], v[34:35], 0, v[24:25]
	v_mov_b32_e32 v39, v38
	v_mov_b32_e32 v40, v38
	v_mov_b32_e32 v41, v38
	v_pk_mul_f32 v[10:11], v[10:11], v[40:41]
	v_pk_mul_f32 v[8:9], v[8:9], v[38:39]
	v_pk_mul_f32 v[10:11], v[10:11], v[68:69]
	v_pk_mul_f32 v[8:9], v[8:9], v[66:67]
	v_pk_add_f32 v[46:47], v[84:85], 1.0 op_sel_hi:[1,0]
	v_pk_add_f32 v[48:49], v[82:83], 1.0 op_sel_hi:[1,0]
	v_pk_fma_f32 v[10:11], v[10:11], v[46:47], v[100:101]
	v_pk_fma_f32 v[8:9], v[8:9], v[48:49], v[98:99]
	s_and_saveexec_b64 s[0:1], s[2:3]
	s_cbranch_execz .LBB0_141
	v_lshl_add_u64 v[46:47], v[32:33], 0, v[18:19]
	global_store_dwordx4 v[46:47], v[8:11], off offset:16
.LBB0_141:
	s_or_b64 exec, exec, s[0:1]
	v_mov_b32_e32 v27, v19
	v_lshl_add_u64 v[50:51], v[34:35], 0, v[26:27]
	s_nop 0
	v_pk_mul_f32 v[6:7], v[6:7], v[40:41]
	v_pk_mul_f32 v[4:5], v[4:5], v[38:39]
	v_pk_mul_f32 v[6:7], v[6:7], v[72:73]
	v_pk_mul_f32 v[4:5], v[4:5], v[70:71]
	v_pk_add_f32 v[40:41], v[88:89], 1.0 op_sel_hi:[1,0]
	v_pk_add_f32 v[46:47], v[86:87], 1.0 op_sel_hi:[1,0]
	v_pk_fma_f32 v[6:7], v[6:7], v[40:41], v[104:105]
	v_pk_fma_f32 v[4:5], v[4:5], v[46:47], v[102:103]
	s_and_saveexec_b64 s[0:1], s[2:3]
	s_cbranch_execz .LBB0_143
	v_lshl_add_u64 v[40:41], v[32:33], 0, v[18:19]
	global_store_dwordx4 v[40:41], v[4:7], off offset:2048
.LBB0_143:
	s_or_b64 exec, exec, s[0:1]
	v_mov_b32_e32 v29, v19
	v_lshl_add_u64 v[34:35], v[34:35], 0, v[28:29]
	s_nop 0
	v_mov_b32_e32 v40, v38
	v_mov_b32_e32 v41, v38
	v_pk_mul_f32 v[0:1], v[0:1], v[38:39]
	v_pk_mul_f32 v[2:3], v[2:3], v[40:41]
	v_pk_mul_f32 v[0:1], v[0:1], v[74:75]
	v_pk_mul_f32 v[2:3], v[2:3], v[76:77]
	v_pk_add_f32 v[38:39], v[92:93], 1.0 op_sel_hi:[1,0]
	v_pk_add_f32 v[40:41], v[90:91], 1.0 op_sel_hi:[1,0]
	v_pk_fma_f32 v[2:3], v[2:3], v[38:39], v[108:109]
	v_pk_fma_f32 v[0:1], v[0:1], v[40:41], v[106:107]
	s_and_saveexec_b64 s[0:1], s[2:3]
	s_cbranch_execz .LBB0_145
	v_lshl_add_u64 v[32:33], v[32:33], 0, v[18:19]
	global_store_dwordx4 v[32:33], v[0:3], off offset:2064

.LBB0_149:
	s_or_b64 exec, exec, s[42:43]
	v_cmp_gt_i32_e64 s[0:1], 4, v0
	s_mov_b64 s[2:3], -1
	s_mov_b64 s[10:11], -1
	s_and_saveexec_b64 s[34:35], s[0:1]
	v_cmp_eq_u32_e64 s[0:1], 0, v0
	s_orn2_b64 s[10:11], s[0:1], exec
	s_or_b64 exec, exec, s[34:35]
	s_and_saveexec_b64 s[0:1], s[10:11]
	s_cbranch_execz .LBB0_126
	s_add_i32 s52, s52, 1
	s_cmp_eq_u32 s72, s52
	s_cselect_b64 s[2:3], -1, 0
	v_add_u32_e32 v42, 1, v42
	s_orn2_b64 s[2:3], s[2:3], exec
	s_branch .LBB0_126

.LBB0_304:
	s_or_b64 exec, exec, s[0:1]
	s_waitcnt lgkmcnt(0)
	v_mov_b32_e32 v0, v154
	s_barrier
	s_nop 0
	v_readfirstlane_b32 s0, v154
	v_and_b32_e32 v1, 63, v154
	v_lshlrev_b32_e32 v1, 4, v1
	s_nop 3
	s_lshl_b32 s1, s0, 4
	v_add_u32_e32 v1, s1, v1
	s_add_u32 s2, s14, 0x1300000
	s_addc_u32 s3, s15, 0
	s_mov_b32 m0, s1
	s_nop 0
	global_load_lds_dwordx4 v1, s[2:3]
	s_add_u32 s2, s2, 0x2000
	s_addc_u32 s3, s3, 0
	s_add_u32 s1, s1, 0x2000
	s_mov_b32 m0, s1
	s_nop 0
	global_load_lds_dwordx4 v1, s[2:3]
	s_add_u32 s2, s2, 0x2000
	s_addc_u32 s3, s3, 0
	s_add_u32 s1, s1, 0x2000
	s_mov_b32 m0, s1
	s_nop 0
	global_load_lds_dwordx4 v1, s[2:3]
	s_add_u32 s2, s2, 0x2000
	s_addc_u32 s3, s3, 0
	s_add_u32 s1, s1, 0x2000
	s_mov_b32 m0, s1
	s_nop 0
	global_load_lds_dwordx4 v1, s[2:3]
	s_add_u32 s2, s2, 0x2000
	s_addc_u32 s3, s3, 0
	s_add_u32 s1, s1, 0x2000
	s_mov_b32 m0, s1
	s_nop 0
	global_load_lds_dwordx4 v1, s[2:3]
	s_add_u32 s2, s2, 0x2000
	s_addc_u32 s3, s3, 0
	s_add_u32 s1, s1, 0x2000
	s_mov_b32 m0, s1
	s_nop 0
	global_load_lds_dwordx4 v1, s[2:3]
	s_add_u32 s2, s2, 0x2000
	s_addc_u32 s3, s3, 0
	s_add_u32 s1, s1, 0x2000
	s_mov_b32 m0, s1
	s_nop 0
	global_load_lds_dwordx4 v1, s[2:3]
	s_add_u32 s2, s2, 0x2000
	s_addc_u32 s3, s3, 0
	s_add_u32 s1, s1, 0x2000
	s_mov_b32 m0, s1
	s_nop 0
	global_load_lds_dwordx4 v1, s[2:3]
	s_add_u32 s2, s2, 0x12000
	s_addc_u32 s3, s3, 0
	s_add_u32 s1, s1, 0x2000
	s_mov_b32 m0, s1
	s_nop 0
	global_load_lds_dwordx4 v1, s[2:3]
	s_add_u32 s2, s2, 0x2000
	s_addc_u32 s3, s3, 0
	s_add_u32 s1, s1, 0x2000
	s_mov_b32 m0, s1
	s_nop 0
	global_load_lds_dwordx4 v1, s[2:3]
	s_add_u32 s2, s2, 0x2000
	s_addc_u32 s3, s3, 0
	s_add_u32 s1, s1, 0x2000
	s_mov_b32 m0, s1
	s_nop 0
	global_load_lds_dwordx4 v1, s[2:3]
	s_add_u32 s2, s2, 0x2000
	s_addc_u32 s3, s3, 0
	s_add_u32 s1, s1, 0x2000
	s_mov_b32 m0, s1
	s_nop 0
	global_load_lds_dwordx4 v1, s[2:3]
	s_add_u32 s2, s2, 0x2000
	s_addc_u32 s3, s3, 0
	s_add_u32 s1, s1, 0x2000
	s_mov_b32 m0, s1
	s_nop 0
	global_load_lds_dwordx4 v1, s[2:3]
	s_add_u32 s2, s2, 0x2000
	s_addc_u32 s3, s3, 0
	s_add_u32 s1, s1, 0x2000
	s_mov_b32 m0, s1
	s_nop 0
	global_load_lds_dwordx4 v1, s[2:3]
	s_add_u32 s2, s2, 0x2000
	s_addc_u32 s3, s3, 0
	s_add_u32 s1, s1, 0x2000
	s_mov_b32 m0, s1
	s_nop 0
	global_load_lds_dwordx4 v1, s[2:3]
	s_add_u32 s2, s2, 0x2000
	s_addc_u32 s3, s3, 0
	s_add_u32 s1, s1, 0x2000
	s_mov_b32 m0, s1
	s_nop 0
	global_load_lds_dwordx4 v1, s[2:3]
	v_lshlrev_b32_e32 v2, 2, v154
	global_load_dword v3, v2, s[46:47] offset:0
	global_load_dword v4, v2, s[50:51] offset:0
	global_load_dword v5, v2, s[54:55] offset:0
	global_load_dword v6, v2, s[44:45] offset:2048
	global_load_dword v7, v2, s[56:57] offset:0
	v_add_u32_e32 v2, 0x21000, v2
	s_waitcnt vmcnt(0)
	ds_write_b32 v2, v3
	ds_write_b32 v2, v4 offset:2048
	ds_write_b32 v2, v5 offset:4096
	ds_write_b32 v2, v6 offset:6144
	ds_write_b32 v2, v7 offset:8192
	s_waitcnt lgkmcnt(0)
	s_barrier
	v_ashrrev_i32_e32 v0, 6, v0
	v_cmp_lt_i32_e32 vcc, 3, v0
	s_and_saveexec_b64 s[0:1], vcc
	s_xor_b64 s[2:3], exec, s[0:1]
	s_cbranch_execz .LBB0_313
	v_cmp_eq_u32_e32 vcc, -1, v0
	s_and_saveexec_b64 s[4:5], vcc
	s_cbranch_execz .LBB0_312
	s_lshl_b32 s0, s13, 2
	s_ashr_i32 s1, s91, 3
	s_add_i32 s0, s0, s1
	s_cmpk_gt_i32 s0, 0x41f
	s_cbranch_scc1 .LBB0_312
	v_mov_b32_e32 v42, v154
	s_nop 0
	v_and_b32_e32 v43, 15, v42
	v_lshl_or_b32 v40, s0, 4, v43
	s_movk_i32 s0, 0x3fff
	v_cmp_lt_i32_e32 vcc, s0, v40
	v_add_u32_e32 v1, -1, v40
	s_and_saveexec_b64 s[0:1], vcc
	s_xor_b64 s[0:1], exec, s[0:1]
	v_add_u32_e32 v2, 0xffffc000, v40
	v_and_b32_e32 v0, 3, v42
	v_lshrrev_b32_e32 v2, 2, v2
	v_add_u32_e32 v2, 0x4200, v2
	v_cmp_eq_u32_e32 vcc, 0, v0
	s_nop 1
	v_cndmask_b32_e32 v0, v1, v2, vcc
	s_andn2_saveexec_b64 s[0:1], s[0:1]
	v_and_b32_e32 v0, 0x7ff, v40
	v_cmp_ne_u32_e32 vcc, 0, v0
	s_nop 1
	v_cndmask_b32_e32 v0, -1, v1, vcc
	s_or_b64 exec, exec, s[0:1]
	v_cmp_lt_i32_e32 vcc, -1, v0
	s_movk_i32 s6, 0x1d00
	v_mov_b64_e32 v[2:3], s[22:23]
	v_cndmask_b32_e32 v0, 0, v0, vcc
	v_mad_i64_i32 v[34:35], s[0:1], v40, s6, v[2:3]
	v_mad_u64_u32 v[28:29], s[0:1], v0, s6, v[2:3]
	v_bfe_u32 v55, v42, 4, 2
	s_mov_b64 s[0:1], 0x1000
	s_mov_b64 s[6:7], 0x1080
	v_lshl_add_u64 v[8:9], v[34:35], 0, s[0:1]
	v_lshl_add_u64 v[10:11], v[34:35], 0, s[6:7]
	v_lshl_add_u64 v[12:13], v[28:29], 0, s[0:1]
	v_lshlrev_b32_e32 v52, 4, v55
	v_mov_b32_e32 v53, 0
	v_lshl_add_u64 v[14:15], v[28:29], 0, s[6:7]
	v_lshl_add_u64 v[0:1], v[8:9], 0, v[52:53]
	v_lshl_add_u64 v[2:3], v[10:11], 0, v[52:53]
	v_lshl_add_u64 v[16:17], v[12:13], 0, v[52:53]
	v_lshl_add_u64 v[18:19], v[14:15], 0, v[52:53]
	global_load_dwordx4 v[4:7], v[2:3], off
	global_load_dwordx4 v[20:23], v[0:1], off
	s_nop 0
	global_load_dwordx4 v[0:3], v[18:19], off
	global_load_dwordx4 v[44:47], v[16:17], off
	v_lshlrev_b32_e32 v16, 5, v55
	v_mov_b32_e32 v17, v53
	v_lshl_add_u64 v[36:37], s[44:45], 0, v[16:17]
	s_movk_i32 s0, 0x2000
	v_cndmask_b32_e64 v54, 0, 1.0, vcc
	v_add_co_u32_e32 v38, vcc, s0, v36
	s_mov_b64 s[0:1], 0x2000
	s_nop 0
	v_addc_co_u32_e32 v39, vcc, 0, v37, vcc
	global_load_dwordx4 v[48:51], v[38:39], off
	global_load_dwordx4 v[56:59], v[38:39], off offset:256
	v_lshl_add_u64 v[16:17], v[36:37], 0, s[0:1]
	global_load_dwordx4 v[60:63], v[16:17], off offset:16
	s_mov_b64 s[0:1], 0x2100
	v_lshl_add_u64 v[18:19], v[36:37], 0, s[0:1]
	global_load_dwordx4 v[64:67], v[18:19], off offset:16
	v_mov_b32_e32 v17, v53
	v_or_b32_e32 v16, 64, v52
	v_lshl_add_u64 v[8:9], v[8:9], 0, v[16:17]
	v_lshl_add_u64 v[10:11], v[10:11], 0, v[16:17]
	v_lshl_add_u64 v[30:31], v[12:13], 0, v[16:17]
	v_lshl_add_u64 v[16:17], v[14:15], 0, v[16:17]
	global_load_dwordx4 v[12:15], v[10:11], off
	s_nop 0
	global_load_dwordx4 v[8:11], v[8:9], off
	s_nop 0
	global_load_dwordx4 v[24:27], v[38:39], off offset:128
	s_nop 0
	global_load_dwordx4 v[16:19], v[16:17], off
	s_nop 0
	global_load_dwordx4 v[30:33], v[30:31], off
	s_mov_b64 s[0:1], 0x2080
	s_mov_b64 s[6:7], 0x1320000
	v_ashrrev_i32_e32 v41, 31, v40
	v_lshlrev_b64 v[40:41], 11, v[40:41]
	s_waitcnt vmcnt(12)
	v_cvt_f32_f16_e32 v68, v4
	v_cvt_f32_f16_sdwa v69, v4 dst_sel:DWORD dst_unused:UNUSED_PAD src0_sel:WORD_1
	v_cvt_f32_f16_e32 v70, v5
	v_cvt_f32_f16_sdwa v71, v5 dst_sel:DWORD dst_unused:UNUSED_PAD src0_sel:WORD_1
	s_waitcnt vmcnt(9)
	v_fma_mix_f32 v72, v54, v44, -v20 op_sel_hi:[0,1,1]
	v_fma_mix_f32 v73, v54, v44, -v20 op_sel:[0,1,1] op_sel_hi:[0,1,1]
	v_cvt_f32_f16_e32 v4, v0
	v_cvt_f32_f16_sdwa v5, v0 dst_sel:DWORD dst_unused:UNUSED_PAD src0_sel:WORD_1
	v_fma_mix_f32 v0, v54, v45, -v21 op_sel_hi:[0,1,1]
	v_fma_mix_f32 v74, v54, v45, -v21 op_sel:[0,1,1] op_sel_hi:[0,1,1]
	v_cvt_f32_f16_e32 v44, v1
	v_cvt_f32_f16_sdwa v45, v1 dst_sel:DWORD dst_unused:UNUSED_PAD src0_sel:WORD_1
	s_waitcnt vmcnt(8)
	v_fma_mix_f32 v1, v48, v72, v20 op_sel_hi:[0,0,1]
	v_fma_mix_f32 v20, v73, v49, v20 op_sel:[0,0,1] op_sel_hi:[0,0,1]
	v_fma_mix_f32 v0, v0, v50, v21 op_sel_hi:[0,0,1]
	v_fma_mix_f32 v21, v74, v51, v21 op_sel:[0,0,1] op_sel_hi:[0,0,1]
	v_add_f32_e32 v1, v1, v1
	v_add_f32_e32 v20, v20, v20
	v_add_f32_e32 v0, v0, v0
	v_add_f32_e32 v21, v21, v21
	v_mul_f32_e32 v1, 0x3fb8aa3b, v1
	v_mul_f32_e32 v20, 0x3fb8aa3b, v20
	v_mul_f32_e32 v48, 0x3fb8aa3b, v0
	v_mul_f32_e32 v21, 0x3fb8aa3b, v21
	v_exp_f32_e32 v49, v1
	v_exp_f32_e32 v20, v20
	v_pk_fma_f32 v[0:1], v[54:55], v[4:5], v[68:69] op_sel_hi:[0,1,1] neg_lo:[0,0,1] neg_hi:[0,0,1]
	v_exp_f32_e32 v4, v48
	v_exp_f32_e32 v5, v21
	v_add_f32_e32 v21, 1.0, v49
	v_add_f32_e32 v20, 1.0, v20
	v_add_f32_e32 v48, 1.0, v4
	v_add_f32_e32 v49, 1.0, v5
	v_rcp_f32_e32 v4, v21
	v_rcp_f32_e32 v5, v20
	v_rcp_f32_e32 v20, v48
	v_rcp_f32_e32 v21, v49
	s_waitcnt vmcnt(7)
	v_pk_fma_f32 v[0:1], v[56:57], v[0:1], v[68:69]
	v_pk_fma_f32 v[4:5], v[4:5], 2.0, 1.0 op_sel_hi:[1,0,0] neg_lo:[1,0,0] neg_hi:[1,0,0]
	v_cvt_pk_f16_f32 v0, v0, v1
	v_pk_fma_f32 v[20:21], v[20:21], 2.0, 1.0 op_sel_hi:[1,0,0] neg_lo:[1,0,0] neg_hi:[1,0,0]
	v_fma_mix_f32 v1, v54, v46, -v22 op_sel_hi:[0,1,1]
	v_cvt_pk_f16_f32 v4, v4, v5
	v_cvt_pk_f16_f32 v5, v20, v21
	v_pk_fma_f32 v[20:21], v[54:55], v[44:45], v[70:71] op_sel_hi:[0,1,1] neg_lo:[0,0,1] neg_hi:[0,0,1]
	s_waitcnt vmcnt(6)
	v_fma_mix_f32 v1, v1, v60, v22 op_sel_hi:[0,0,1]
	v_fma_mix_f32 v44, v54, v46, -v22 op_sel:[0,1,1] op_sel_hi:[0,1,1]
	v_add_f32_e32 v1, v1, v1
	v_fma_mix_f32 v22, v44, v61, v22 op_sel:[0,0,1] op_sel_hi:[0,0,1]
	v_mul_f32_e32 v1, 0x3fb8aa3b, v1
	v_add_f32_e32 v22, v22, v22
	v_exp_f32_e32 v1, v1
	v_mul_f32_e32 v22, 0x3fb8aa3b, v22
	v_exp_f32_e32 v22, v22
	v_pk_fma_f32 v[20:21], v[20:21], v[58:59], v[70:71]
	v_add_f32_e32 v1, 1.0, v1
	v_rcp_f32_e32 v44, v1
	v_add_f32_e32 v1, 1.0, v22
	v_rcp_f32_e32 v45, v1
	v_cvt_f32_f16_e32 v48, v6
	v_cvt_f32_f16_sdwa v49, v6 dst_sel:DWORD dst_unused:UNUSED_PAD src0_sel:WORD_1
	v_cvt_f32_f16_e32 v50, v2
	v_cvt_f32_f16_sdwa v51, v2 dst_sel:DWORD dst_unused:UNUSED_PAD src0_sel:WORD_1
	v_cvt_pk_f16_f32 v1, v20, v21
	v_pk_fma_f32 v[20:21], v[44:45], 2.0, 1.0 op_sel_hi:[1,0,0] neg_lo:[1,0,0] neg_hi:[1,0,0]
	v_fma_mix_f32 v2, v54, v47, -v23 op_sel_hi:[0,1,1]
	v_fma_mix_f32 v22, v54, v47, -v23 op_sel:[0,1,1] op_sel_hi:[0,1,1]
	global_load_dwordx4 v[44:47], v[38:39], off offset:384
	v_cvt_pk_f16_f32 v6, v20, v21
	v_pk_fma_f32 v[20:21], v[54:55], v[50:51], v[48:49] op_sel_hi:[0,1,1] neg_lo:[0,0,1] neg_hi:[0,0,1]
	s_waitcnt vmcnt(6)
	v_pk_fma_f32 v[20:21], v[20:21], v[64:65], v[48:49]
	v_lshl_add_u64 v[48:49], v[36:37], 0, s[0:1]
	global_load_dwordx4 v[48:51], v[48:49], off offset:16
	v_fma_mix_f32 v2, v2, v62, v23 op_sel_hi:[0,0,1]
	v_add_f32_e32 v2, v2, v2
	v_fma_mix_f32 v22, v22, v63, v23 op_sel:[0,0,1] op_sel_hi:[0,0,1]
	v_mul_f32_e32 v2, 0x3fb8aa3b, v2
	v_add_f32_e32 v22, v22, v22
	v_exp_f32_e32 v2, v2
	v_mul_f32_e32 v22, 0x3fb8aa3b, v22
	v_exp_f32_e32 v23, v22
	v_cvt_f32_f16_e32 v56, v3
	v_add_f32_e32 v2, 1.0, v2
	v_rcp_f32_e32 v22, v2
	v_add_f32_e32 v2, 1.0, v23
	v_rcp_f32_e32 v23, v2
	v_cvt_f32_f16_sdwa v57, v3 dst_sel:DWORD dst_unused:UNUSED_PAD src0_sel:WORD_1
	s_waitcnt vmcnt(2)
	v_fma_mix_f32 v3, v54, v30, -v8 op_sel_hi:[0,1,1]
	v_fma_mix_f32 v3, v24, v3, v8 op_sel_hi:[0,0,1]
	v_add_f32_e32 v3, v3, v3
	v_mul_f32_e32 v3, 0x3fb8aa3b, v3
	v_cvt_pk_f16_f32 v2, v20, v21
	v_pk_fma_f32 v[20:21], v[22:23], 2.0, 1.0 op_sel_hi:[1,0,0] neg_lo:[1,0,0] neg_hi:[1,0,0]
	v_exp_f32_e32 v22, v3
	v_fma_mix_f32 v3, v54, v30, -v8 op_sel:[0,1,1] op_sel_hi:[0,1,1]
	v_fma_mix_f32 v3, v3, v25, v8 op_sel:[0,0,1] op_sel_hi:[0,0,1]
	v_cvt_f32_f16_e32 v38, v7
	v_cvt_f32_f16_sdwa v39, v7 dst_sel:DWORD dst_unused:UNUSED_PAD src0_sel:WORD_1
	v_add_f32_e32 v3, v3, v3
	v_mul_f32_e32 v3, 0x3fb8aa3b, v3
	v_exp_f32_e32 v8, v3
	v_cvt_pk_f16_f32 v7, v20, v21
	v_pk_fma_f32 v[20:21], v[54:55], v[56:57], v[38:39] op_sel_hi:[0,1,1] neg_lo:[0,0,1] neg_hi:[0,0,1]
	v_pk_fma_f32 v[20:21], v[20:21], v[66:67], v[38:39]
	v_add_f32_e32 v8, 1.0, v8
	v_cvt_pk_f16_f32 v3, v20, v21
	v_add_f32_e32 v20, 1.0, v22
	v_rcp_f32_e32 v20, v20
	v_rcp_f32_e32 v21, v8
	s_mov_b64 s[0:1], 0x2180
	v_lshl_add_u64 v[22:23], v[36:37], 0, s[0:1]
	global_load_dwordx4 v[36:39], v[22:23], off offset:16
	v_lshl_add_u64 v[22:23], s[14:15], 0, v[52:53]
	s_mov_b64 s[0:1], 0x1300000
	v_pk_fma_f32 v[20:21], v[20:21], 2.0, 1.0 op_sel_hi:[1,0,0] neg_lo:[1,0,0] neg_hi:[1,0,0]
	v_lshl_add_u64 v[60:61], v[22:23], 0, s[0:1]
	s_lshl_b32 s0, s91, 6
	v_cvt_pk_f16_f32 v8, v20, v21
	v_cvt_f32_f16_e32 v20, v12
	v_cvt_f32_f16_sdwa v21, v12 dst_sel:DWORD dst_unused:UNUSED_PAD src0_sel:WORD_1
	v_fma_mix_f32 v12, v54, v31, -v9 op_sel_hi:[0,1,1]
	s_and_b32 s1, s0, 0x1c0
	v_fma_mix_f32 v12, v12, v26, v9 op_sel_hi:[0,0,1]
	v_or_b32_e32 v26, s1, v43
	v_lshlrev_b32_e32 v52, 7, v26
	v_lshl_add_u64 v[62:63], v[22:23], 0, s[6:7]
	v_lshl_add_u64 v[22:23], v[62:63], 0, v[52:53]
	v_cvt_f32_f16_e32 v24, v16
	v_cvt_f32_f16_sdwa v25, v16 dst_sel:DWORD dst_unused:UNUSED_PAD src0_sel:WORD_1
	v_fma_mix_f32 v16, v54, v31, -v9 op_sel:[0,1,1] op_sel_hi:[0,1,1]
	v_lshl_add_u64 v[30:31], v[60:61], 0, v[52:53]
	global_load_dwordx4 v[72:75], v[22:23], off
	global_load_dwordx4 v[82:85], v[22:23], off offset:64
	global_load_dwordx4 v[56:59], v[30:31], off
	global_load_dwordx4 v[76:79], v[30:31], off offset:64
	v_fma_mix_f32 v9, v16, v27, v9 op_sel:[0,0,1] op_sel_hi:[0,0,1]
	v_add_f32_e32 v12, v12, v12
	v_add_f32_e32 v9, v9, v9
	v_mul_f32_e32 v12, 0x3fb8aa3b, v12
	v_mul_f32_e32 v9, 0x3fb8aa3b, v9
	v_exp_f32_e32 v12, v12
	v_exp_f32_e32 v9, v9
	v_pk_fma_f32 v[22:23], v[54:55], v[24:25], v[20:21] op_sel_hi:[0,1,1] neg_lo:[0,0,1] neg_hi:[0,0,1]
	v_lshlrev_b32_e32 v55, 2, v55
	v_add_f32_e32 v12, 1.0, v12
	v_add_f32_e32 v9, 1.0, v9
	v_rcp_f32_e32 v26, v12
	v_rcp_f32_e32 v27, v9
	s_waitcnt vmcnt(6)
	v_pk_fma_f32 v[20:21], v[44:45], v[22:23], v[20:21]
	v_mov_b32_e32 v23, v53
	v_cvt_pk_f16_f32 v12, v20, v21
	v_pk_fma_f32 v[20:21], v[26:27], 2.0, 1.0 op_sel_hi:[1,0,0] neg_lo:[1,0,0] neg_hi:[1,0,0]
	v_fma_mix_f32 v24, v54, v32, -v10 op_sel_hi:[0,1,1]
	v_cvt_pk_f16_f32 v9, v20, v21
	v_cvt_f32_f16_e32 v20, v13
	v_cvt_f32_f16_sdwa v21, v13 dst_sel:DWORD dst_unused:UNUSED_PAD src0_sel:WORD_1
	v_or_b32_e32 v13, s1, v55
	v_lshlrev_b32_e32 v22, 1, v13
	v_lshl_add_u64 v[68:69], v[34:35], 0, v[22:23]
	global_load_dwordx2 v[64:65], v[68:69], off offset:1024
	s_waitcnt vmcnt(6)
	v_fma_mix_f32 v24, v24, v48, v10 op_sel_hi:[0,0,1]
	v_add_f32_e32 v24, v24, v24
	v_cvt_f32_f16_e32 v16, v17
	v_cvt_f32_f16_sdwa v17, v17 dst_sel:DWORD dst_unused:UNUSED_PAD src0_sel:WORD_1
	v_mul_f32_e32 v24, 0x3fb8aa3b, v24
	v_lshl_add_u64 v[70:71], v[28:29], 0, v[22:23]
	v_exp_f32_e32 v24, v24
	global_load_dwordx2 v[66:67], v[70:71], off offset:1024
	v_pk_fma_f32 v[16:17], v[54:55], v[16:17], v[20:21] op_sel_hi:[0,1,1] neg_lo:[0,0,1] neg_hi:[0,0,1]
	v_pk_fma_f32 v[16:17], v[16:17], v[46:47], v[20:21]
	v_add_f32_e32 v20, 1.0, v24
	v_fma_mix_f32 v21, v54, v32, -v10 op_sel:[0,1,1] op_sel_hi:[0,1,1]
	v_lshlrev_b32_e32 v80, 2, v13
	v_fma_mix_f32 v10, v21, v49, v10 op_sel:[0,0,1] op_sel_hi:[0,0,1]
	v_rcp_f32_e32 v34, v20
	global_load_dwordx4 v[28:31], v80, s[44:45] offset:2048
	global_load_dwordx4 v[24:27], v80, s[46:47]
	global_load_dwordx4 v[20:23], v80, s[50:51]
	v_add_f32_e32 v10, v10, v10
	v_mul_f32_e32 v10, 0x3fb8aa3b, v10
	v_cvt_f32_f16_e32 v44, v14
	v_cvt_f32_f16_sdwa v45, v14 dst_sel:DWORD dst_unused:UNUSED_PAD src0_sel:WORD_1
	v_cvt_f32_f16_e32 v46, v18
	v_cvt_f32_f16_sdwa v47, v18 dst_sel:DWORD dst_unused:UNUSED_PAD src0_sel:WORD_1
	v_fma_mix_f32 v14, v54, v33, -v11 op_sel_hi:[0,1,1]
	v_fma_mix_f32 v18, v54, v33, -v11 op_sel:[0,1,1] op_sel_hi:[0,1,1]
	v_exp_f32_e32 v10, v10
	v_fma_mix_f32 v14, v14, v50, v11 op_sel_hi:[0,0,1]
	v_fma_mix_f32 v11, v18, v51, v11 op_sel:[0,0,1] op_sel_hi:[0,0,1]
	v_add_f32_e32 v14, v14, v14
	v_add_f32_e32 v11, v11, v11
	v_mul_f32_e32 v14, 0x3fb8aa3b, v14
	v_mul_f32_e32 v11, 0x3fb8aa3b, v11
	v_exp_f32_e32 v14, v14
	v_exp_f32_e32 v11, v11
	v_add_f32_e32 v10, 1.0, v10
	v_rcp_f32_e32 v35, v10
	v_add_f32_e32 v14, 1.0, v14
	v_add_f32_e32 v11, 1.0, v11
	v_rcp_f32_e32 v32, v14
	v_rcp_f32_e32 v33, v11
	v_cvt_pk_f16_f32 v13, v16, v17
	v_pk_fma_f32 v[16:17], v[34:35], 2.0, 1.0 op_sel_hi:[1,0,0] neg_lo:[1,0,0] neg_hi:[1,0,0]
	v_cvt_f32_f16_e32 v34, v15
	v_cvt_f32_f16_sdwa v35, v15 dst_sel:DWORD dst_unused:UNUSED_PAD src0_sel:WORD_1
	v_cvt_f32_f16_e32 v18, v19
	v_cvt_f32_f16_sdwa v19, v19 dst_sel:DWORD dst_unused:UNUSED_PAD src0_sel:WORD_1
	v_cvt_pk_f16_f32 v10, v16, v17
	v_pk_fma_f32 v[16:17], v[54:55], v[46:47], v[44:45] op_sel_hi:[0,1,1] neg_lo:[0,0,1] neg_hi:[0,0,1]
	s_waitcnt vmcnt(9)
	v_pk_fma_f32 v[16:17], v[16:17], v[36:37], v[44:45]
	s_mov_b32 s0, 0x3f1b4598
	v_cvt_pk_f16_f32 v14, v16, v17
	v_pk_fma_f32 v[16:17], v[32:33], 2.0, 1.0 op_sel_hi:[1,0,0] neg_lo:[1,0,0] neg_hi:[1,0,0]
	s_waitcnt vmcnt(4)
	v_cvt_f32_f16_e32 v90, v64
	v_cvt_pk_f16_f32 v11, v16, v17
	v_pk_fma_f32 v[16:17], v[54:55], v[18:19], v[34:35] op_sel_hi:[0,1,1] neg_lo:[0,0,1] neg_hi:[0,0,1]
	v_pk_fma_f32 v[16:17], v[16:17], v[38:39], v[34:35]
	v_mfma_f32_16x16x32_f16 v[36:39], v[56:59], v[4:7], 0
	v_cvt_pk_f16_f32 v15, v16, v17
	v_and_b32_e32 v16, 16, v42
	v_lshl_add_u64 v[56:57], s[30:31], 0, v[40:41]
	v_mfma_f32_16x16x32_f16 v[42:45], v[72:75], v[0:3], 0
	v_lshl_add_u64 v[58:59], s[14:15], 0, v[40:41]
	v_add_u32_e32 v17, 12, v55
	v_cmp_eq_u32_e32 vcc, 0, v16
	v_mfma_f32_16x16x32_f16 v[40:43], v[82:85], v[12:15], v[42:45]
	v_cvt_f32_f16_sdwa v91, v64 dst_sel:DWORD dst_unused:UNUSED_PAD src0_sel:WORD_1
	v_cndmask_b32_e32 v55, v17, v55, vcc
	global_load_dwordx4 v[16:19], v80, s[54:55]
	global_load_dwordx4 v[32:35], v80, s[56:57]
	v_or_b32_e32 v44, 0x800, v52
	v_mov_b32_e32 v45, v53
	v_mfma_f32_16x16x32_f16 v[36:39], v[76:79], v[8:11], v[36:39]
	v_lshl_add_u64 v[76:77], v[60:61], 0, v[44:45]
	global_load_dwordx4 v[48:51], v[76:77], off
	v_lshl_add_u64 v[78:79], v[62:63], 0, v[44:45]
	global_load_dwordx4 v[44:47], v[78:79], off
	global_load_dwordx2 v[72:73], v[68:69], off offset:1056
	global_load_dwordx2 v[74:75], v[68:69], off offset:1088
	s_nop 0
	global_load_dwordx2 v[68:69], v[68:69], off offset:1120
	v_cvt_f32_f16_e32 v92, v65
	v_cvt_f32_f16_sdwa v93, v65 dst_sel:DWORD dst_unused:UNUSED_PAD src0_sel:WORD_1
	global_load_dwordx4 v[82:85], v[76:77], off offset:64
	s_nop 0
	global_load_dwordx4 v[76:79], v[78:79], off offset:64
	s_nop 0
	global_load_dwordx2 v[102:103], v[70:71], off offset:1056
	global_load_dwordx2 v[114:115], v[70:71], off offset:1088
	global_load_dwordx2 v[64:65], v[70:71], off offset:1120
	s_waitcnt vmcnt(15)
	v_cvt_f32_f16_e32 v86, v67
	v_cvt_f32_f16_sdwa v87, v67 dst_sel:DWORD dst_unused:UNUSED_PAD src0_sel:WORD_1
	v_cvt_f32_f16_e32 v70, v66
	v_cvt_f32_f16_sdwa v71, v66 dst_sel:DWORD dst_unused:UNUSED_PAD src0_sel:WORD_1
	v_xor_b32_e32 v66, 0x80000000, v92
	v_xor_b32_e32 v67, 0x80000000, v93
	v_pk_fma_f32 v[66:67], v[54:55], v[86:87], v[66:67] op_sel_hi:[0,1,1]
	v_xor_b32_e32 v86, 0x80000000, v90
	v_xor_b32_e32 v87, 0x80000000, v91
	v_pk_fma_f32 v[70:71], v[54:55], v[70:71], v[86:87] op_sel_hi:[0,1,1]
	global_load_dwordx4 v[86:89], v80, s[44:45] offset:2112
	s_waitcnt vmcnt(14)
	v_pk_add_f32 v[26:27], v[38:39], v[26:27]
	v_pk_add_f32 v[24:25], v[36:37], v[24:25]
	s_waitcnt vmcnt(13)
	v_pk_add_f32 v[22:23], v[42:43], v[22:23]
	v_pk_add_f32 v[20:21], v[40:41], v[20:21]
	global_load_dwordx4 v[36:39], v80, s[46:47] offset:64
	global_load_dwordx4 v[40:43], v80, s[50:51] offset:64
	v_mul_f32_e32 v24, 0xbfb8aa3b, v24
	v_exp_f32_e32 v24, v24
	v_mul_f32_e32 v25, 0xbfb8aa3b, v25
	v_exp_f32_e32 v25, v25
	v_pk_fma_f32 v[66:67], v[30:31], v[66:67], v[92:93]
	v_add_f32_e32 v24, 1.0, v24
	v_rcp_f32_e32 v30, v24
	v_add_f32_e32 v24, 1.0, v25
	v_mul_f32_e32 v25, 0xbfb8aa3b, v26
	v_exp_f32_e32 v25, v25
	v_mul_f32_e32 v26, 0xbfb8aa3b, v27
	v_mul_f32_e32 v20, 0xbfb8aa3b, v20
	v_exp_f32_e32 v26, v26
	v_exp_f32_e32 v20, v20
	v_mul_f32_e32 v21, 0xbfb8aa3b, v21
	v_exp_f32_e32 v21, v21
	v_rcp_f32_e32 v31, v24
	v_add_f32_e32 v24, 1.0, v25
	v_pk_fma_f32 v[28:29], v[28:29], v[70:71], v[90:91]
	v_rcp_f32_e32 v70, v24
	v_add_f32_e32 v24, 1.0, v26
	v_add_f32_e32 v20, 1.0, v20
	v_rcp_f32_e32 v71, v24
	v_rcp_f32_e32 v24, v20
	v_add_f32_e32 v20, 1.0, v21
	v_mul_f32_e32 v21, 0xbfb8aa3b, v22
	v_exp_f32_e32 v21, v21
	v_mul_f32_e32 v22, 0xbfb8aa3b, v23
	v_exp_f32_e32 v22, v22
	v_rcp_f32_e32 v25, v20
	v_add_f32_e32 v20, 1.0, v21
	v_rcp_f32_e32 v26, v20
	v_add_f32_e32 v20, 1.0, v22
	v_rcp_f32_e32 v27, v20
	v_pk_mul_f32 v[20:21], v[70:71], s[0:1] op_sel_hi:[1,0]
	v_pk_mul_f32 v[22:23], v[30:31], s[0:1] op_sel_hi:[1,0]
	v_pk_add_f32 v[70:71], v[24:25], -1.0 op_sel_hi:[1,0]
	v_pk_add_f32 v[30:31], v[26:27], -1.0 op_sel_hi:[1,0]
	v_cvt_pk_f16_f32 v21, v20, v21
	v_cvt_pk_f16_f32 v20, v22, v23
	global_load_dwordx4 v[90:93], v80, s[54:55] offset:64
	global_load_dwordx4 v[94:97], v80, s[56:57] offset:64
	s_waitcnt vmcnt(15)
	v_pk_fma_f32 v[30:31], v[34:35], v[30:31], 1.0 op_sel_hi:[1,1,0]
	v_pk_fma_f32 v[32:33], v[32:33], v[70:71], 1.0 op_sel_hi:[1,1,0]
	v_pk_mul_f32 v[34:35], v[30:31], v[66:67]
	v_pk_mul_f32 v[32:33], v[32:33], v[28:29]
	v_pk_mul_f32 v[30:31], v[16:17], v[28:29]
	v_pk_mul_f32 v[28:29], v[18:19], v[66:67]
	v_cvt_pk_f16_f32 v17, v34, v35
	v_cvt_pk_f16_f32 v16, v32, v33
	s_waitcnt vmcnt(14)
	v_mfma_f32_16x16x32_f16 v[32:35], v[48:51], v[4:7], 0
	v_mul_f32_e64 v18, v28, v28
	v_mul_f32_e64 v19, v29, v29
	v_pk_mul_f32 v[22:23], v[30:31], v[30:31]
	s_nop 0
	v_pk_mov_b32 v[50:51], v[22:23], v[18:19] op_sel:[1,0]
	v_mov_b32_e32 v23, v19
	v_or_b32_e32 v18, 0x1000, v52
	v_mov_b32_e32 v19, v53
	v_lshl_add_u64 v[66:67], v[60:61], 0, v[18:19]
	v_lshl_add_u64 v[18:19], v[62:63], 0, v[18:19]
	s_waitcnt vmcnt(13)
	v_mfma_f32_16x16x32_f16 v[46:49], v[44:47], v[0:3], 0
	global_load_dwordx4 v[98:101], v[66:67], off
	v_pk_add_f32 v[22:23], v[50:51], v[22:23]
	s_waitcnt vmcnt(13)
	v_cvt_f32_f16_e32 v50, v73
	s_waitcnt vmcnt(10)
	v_mfma_f32_16x16x32_f16 v[32:35], v[82:85], v[8:11], v[32:35]
	global_load_dwordx4 v[82:85], v[18:19], off
	v_pk_add_f32 v[44:45], v[22:23], v[22:23] op_sel:[0,1] op_sel_hi:[1,0]
	v_cvt_f32_f16_e32 v22, v72
	s_waitcnt vmcnt(10)
	v_mfma_f32_16x16x32_f16 v[46:49], v[76:79], v[12:15], v[46:49]
	global_load_dwordx4 v[76:79], v[66:67], off offset:64
	v_cvt_f32_f16_sdwa v23, v72 dst_sel:DWORD dst_unused:UNUSED_PAD src0_sel:WORD_1
	v_cvt_f32_f16_sdwa v51, v73 dst_sel:DWORD dst_unused:UNUSED_PAD src0_sel:WORD_1
	global_load_dwordx4 v[70:73], v[18:19], off offset:64
	s_waitcnt vmcnt(7)
	v_pk_add_f32 v[32:33], v[32:33], v[36:37]
	v_pk_add_f32 v[34:35], v[34:35], v[38:39]
	s_waitcnt vmcnt(6)
	v_pk_add_f32 v[36:37], v[48:49], v[42:43]
	v_pk_add_f32 v[38:39], v[46:47], v[40:41]
	global_load_dwordx4 v[40:43], v80, s[44:45] offset:2176
	global_load_dwordx4 v[46:49], v80, s[46:47] offset:128
	v_cvt_f32_f16_e32 v66, v103
	v_cvt_f32_f16_sdwa v67, v103 dst_sel:DWORD dst_unused:UNUSED_PAD src0_sel:WORD_1
	v_cvt_f32_f16_e32 v18, v102
	v_cvt_f32_f16_sdwa v19, v102 dst_sel:DWORD dst_unused:UNUSED_PAD src0_sel:WORD_1
	v_xor_b32_e32 v102, 0x80000000, v50
	v_xor_b32_e32 v103, 0x80000000, v51
	v_pk_fma_f32 v[66:67], v[54:55], v[66:67], v[102:103] op_sel_hi:[0,1,1]
	v_xor_b32_e32 v102, 0x80000000, v22
	v_xor_b32_e32 v103, 0x80000000, v23
	v_pk_fma_f32 v[18:19], v[54:55], v[18:19], v[102:103] op_sel_hi:[0,1,1]
	v_pk_fma_f32 v[18:19], v[86:87], v[18:19], v[22:23]
	v_pk_fma_f32 v[22:23], v[88:89], v[66:67], v[50:51]
	global_load_dwordx4 v[86:89], v80, s[50:51] offset:128
	v_mul_f32_e32 v32, 0xbfb8aa3b, v32
	v_exp_f32_e32 v32, v32
	v_mul_f32_e32 v33, 0xbfb8aa3b, v33
	v_exp_f32_e32 v33, v33
	v_or_b32_e32 v52, 0x1800, v52
	v_add_f32_e32 v32, 1.0, v32
	v_rcp_f32_e32 v50, v32
	v_mul_f32_e32 v32, 0xbfb8aa3b, v34
	v_add_f32_e32 v33, 1.0, v33
	v_exp_f32_e32 v32, v32
	v_rcp_f32_e32 v51, v33
	v_mul_f32_e32 v33, 0xbfb8aa3b, v35
	v_exp_f32_e32 v33, v33
	v_mul_f32_e32 v34, 0xbfb8aa3b, v38
	v_exp_f32_e32 v34, v34
	v_add_f32_e32 v32, 1.0, v32
	v_rcp_f32_e32 v66, v32
	v_add_f32_e32 v32, 1.0, v33
	v_rcp_f32_e32 v67, v32
	v_add_f32_e32 v32, 1.0, v34
	v_mul_f32_e32 v34, 0xbfb8aa3b, v36
	v_mul_f32_e32 v35, 0xbfb8aa3b, v37
	v_mul_f32_e32 v33, 0xbfb8aa3b, v39
	v_exp_f32_e32 v34, v34
	v_exp_f32_e32 v35, v35
	v_exp_f32_e32 v33, v33
	v_rcp_f32_e32 v32, v32
	v_add_f32_e32 v34, 1.0, v34
	v_add_f32_e32 v35, 1.0, v35
	v_add_f32_e32 v33, 1.0, v33
	v_rcp_f32_e32 v34, v34
	v_rcp_f32_e32 v35, v35
	v_rcp_f32_e32 v33, v33
	v_pk_mul_f32 v[50:51], v[50:51], s[0:1] op_sel_hi:[1,0]
	v_pk_mul_f32 v[66:67], v[66:67], s[0:1] op_sel_hi:[1,0]
	v_pk_add_f32 v[36:37], v[34:35], -1.0 op_sel_hi:[1,0]
	v_pk_add_f32 v[38:39], v[32:33], -1.0 op_sel_hi:[1,0]
	s_waitcnt vmcnt(7)
	v_pk_fma_f32 v[36:37], v[96:97], v[36:37], 1.0 op_sel_hi:[1,1,0]
	v_pk_fma_f32 v[38:39], v[94:95], v[38:39], 1.0 op_sel_hi:[1,1,0]
	v_pk_mul_f32 v[106:107], v[36:37], v[22:23]
	v_pk_mul_f32 v[36:37], v[92:93], v[22:23]
	v_cvt_pk_f16_f32 v22, v50, v51
	v_lshl_add_u64 v[50:51], v[62:63], 0, v[52:53]
	v_pk_mul_f32 v[108:109], v[38:39], v[18:19]
	v_pk_mul_f32 v[38:39], v[90:91], v[18:19]
	v_cvt_pk_f16_f32 v23, v66, v67
	global_load_dwordx4 v[90:93], v80, s[54:55] offset:128
	global_load_dwordx4 v[94:97], v80, s[56:57] offset:128
	v_lshl_add_u64 v[66:67], v[60:61], 0, v[52:53]
	global_load_dwordx4 v[60:63], v[50:51], off
	global_load_dwordx4 v[110:113], v[50:51], off offset:64
	global_load_dwordx4 v[102:105], v[66:67], off
	v_cvt_pk_f16_f32 v19, v106, v107
	s_waitcnt vmcnt(11)
	v_mfma_f32_16x16x32_f16 v[98:101], v[98:101], v[4:7], 0
	v_cvt_pk_f16_f32 v18, v108, v109
	v_pk_mul_f32 v[116:117], v[36:37], v[36:37]
	global_load_dwordx4 v[106:109], v[66:67], off offset:64
	s_waitcnt vmcnt(11)
	v_mfma_f32_16x16x32_f16 v[82:85], v[82:85], v[0:3], 0
	v_mul_f32_e64 v66, v38, v38
	v_mul_f32_e64 v67, v39, v39
	v_permlane16_swap_b32_e32 v20, v22
	v_pk_mov_b32 v[118:119], v[66:67], v[116:117] op_sel:[1,0]
	v_mov_b32_e32 v67, v117
	v_pk_add_f32 v[50:51], v[118:119], v[66:67]
	s_waitcnt vmcnt(10)
	v_mfma_f32_16x16x32_f16 v[76:79], v[76:79], v[8:11], v[98:101]
	v_add_f32_e64 v66, v50, v51
	v_add_f32_e64 v67, v51, v50
	v_cvt_f32_f16_e32 v50, v74
	v_cvt_f32_f16_sdwa v51, v74 dst_sel:DWORD dst_unused:UNUSED_PAD src0_sel:WORD_1
	v_cvt_f32_f16_e32 v74, v75
	v_cvt_f32_f16_sdwa v75, v75 dst_sel:DWORD dst_unused:UNUSED_PAD src0_sel:WORD_1
	s_waitcnt vmcnt(9)
	v_mfma_f32_16x16x32_f16 v[70:73], v[70:73], v[12:15], v[82:85]
	v_cvt_f32_f16_e32 v98, v114
	v_cvt_f32_f16_sdwa v99, v114 dst_sel:DWORD dst_unused:UNUSED_PAD src0_sel:WORD_1
	v_xor_b32_e32 v100, 0x80000000, v50
	v_cvt_f32_f16_e32 v82, v115
	v_cvt_f32_f16_sdwa v83, v115 dst_sel:DWORD dst_unused:UNUSED_PAD src0_sel:WORD_1
	v_xor_b32_e32 v84, 0x80000000, v74
	v_xor_b32_e32 v85, 0x80000000, v75
	v_xor_b32_e32 v101, 0x80000000, v51
	v_pk_fma_f32 v[114:115], v[54:55], v[82:83], v[84:85] op_sel_hi:[0,1,1]
	v_pk_fma_f32 v[116:117], v[54:55], v[98:99], v[100:101] op_sel_hi:[0,1,1]
	s_waitcnt vmcnt(8)
	v_pk_fma_f32 v[116:117], v[40:41], v[116:117], v[50:51]
	v_pk_fma_f32 v[114:115], v[42:43], v[114:115], v[74:75]
	s_waitcnt vmcnt(7)
	v_pk_add_f32 v[40:41], v[76:77], v[46:47]
	global_load_dwordx4 v[74:77], v80, s[50:51] offset:192
	global_load_dwordx4 v[82:85], v80, s[44:45] offset:2240
	global_load_dwordx4 v[98:101], v80, s[46:47] offset:192
	v_mul_f32_e32 v40, 0xbfb8aa3b, v40
	v_exp_f32_e32 v40, v40
	v_mul_f32_e32 v41, 0xbfb8aa3b, v41
	v_exp_f32_e32 v41, v41
	v_pk_add_f32 v[42:43], v[78:79], v[48:49]
	v_add_f32_e32 v40, 1.0, v40
	v_mul_f32_e32 v42, 0xbfb8aa3b, v42
	v_exp_f32_e32 v42, v42
	v_rcp_f32_e32 v78, v40
	v_add_f32_e32 v40, 1.0, v41
	v_mul_f32_e32 v41, 0xbfb8aa3b, v43
	v_exp_f32_e32 v41, v41
	s_waitcnt vmcnt(9)
	v_pk_add_f32 v[48:49], v[70:71], v[86:87]
	v_rcp_f32_e32 v79, v40
	v_add_f32_e32 v40, 1.0, v42
	v_pk_add_f32 v[46:47], v[72:73], v[88:89]
	v_mul_f32_e32 v42, 0xbfb8aa3b, v48
	v_rcp_f32_e32 v86, v40
	v_add_f32_e32 v40, 1.0, v41
	v_mul_f32_e32 v41, 0xbfb8aa3b, v49
	global_load_dwordx4 v[48:51], v80, s[54:55] offset:192
	global_load_dwordx4 v[70:73], v80, s[56:57] offset:192
	v_exp_f32_e32 v42, v42
	v_rcp_f32_e32 v87, v40
	v_exp_f32_e32 v41, v41
	v_mul_f32_e32 v43, 0xbfb8aa3b, v47
	v_add_f32_e32 v40, 1.0, v42
	v_mul_f32_e32 v42, 0xbfb8aa3b, v46
	v_exp_f32_e32 v42, v42
	v_exp_f32_e32 v43, v43
	v_add_f32_e32 v41, 1.0, v41
	v_rcp_f32_e32 v40, v40
	v_add_f32_e32 v42, 1.0, v42
	v_add_f32_e32 v43, 1.0, v43
	v_rcp_f32_e32 v41, v41
	s_waitcnt vmcnt(8)
	v_mfma_f32_16x16x32_f16 v[0:3], v[60:63], v[0:3], 0
	v_rcp_f32_e32 v42, v42
	v_rcp_f32_e32 v43, v43
	v_pk_mul_f32 v[88:89], v[78:79], s[0:1] op_sel_hi:[1,0]
	v_pk_add_f32 v[78:79], v[40:41], -1.0 op_sel_hi:[1,0]
	s_waitcnt vmcnt(7)
	v_mfma_f32_16x16x32_f16 v[0:3], v[110:113], v[12:15], v[0:3]
	v_add_f32_e64 v46, v42, -1.0
	v_add_f32_e64 v47, v43, -1.0
	v_pk_fma_f32 v[78:79], v[94:95], v[78:79], 1.0 op_sel_hi:[1,1,0]
	v_pk_fma_f32 v[46:47], v[96:97], v[46:47], 1.0 op_sel_hi:[1,1,0]
	v_pk_mul_f32 v[96:97], v[78:79], v[116:117]
	s_waitcnt vmcnt(6)
	v_mfma_f32_16x16x32_f16 v[78:81], v[102:105], v[4:7], 0
	v_cvt_f32_f16_e32 v14, v69
	v_cvt_f32_f16_sdwa v15, v69 dst_sel:DWORD dst_unused:UNUSED_PAD src0_sel:WORD_1
	v_cvt_f32_f16_e32 v12, v68
	s_waitcnt vmcnt(5)
	v_mfma_f32_16x16x32_f16 v[8:11], v[106:109], v[8:11], v[78:81]
	v_cvt_f32_f16_sdwa v13, v68 dst_sel:DWORD dst_unused:UNUSED_PAD src0_sel:WORD_1
	v_cvt_f32_f16_e32 v68, v65
	v_cvt_f32_f16_sdwa v69, v65 dst_sel:DWORD dst_unused:UNUSED_PAD src0_sel:WORD_1
	v_pk_mul_f32 v[4:5], v[92:93], v[114:115]
	v_xor_b32_e32 v65, 0x80000000, v15
	v_pk_mul_f32 v[62:63], v[4:5], v[4:5]
	v_pk_mul_f32 v[94:95], v[46:47], v[114:115]
	v_add_f32_e32 v80, v62, v63
	v_cvt_f32_f16_e32 v62, v64
	v_cvt_f32_f16_sdwa v63, v64 dst_sel:DWORD dst_unused:UNUSED_PAD src0_sel:WORD_1
	v_xor_b32_e32 v64, 0x80000000, v14
	v_pk_fma_f32 v[64:65], v[54:55], v[68:69], v[64:65] op_sel_hi:[0,1,1]
	v_xor_b32_e32 v68, 0x80000000, v12
	v_xor_b32_e32 v69, 0x80000000, v13
	v_pk_fma_f32 v[62:63], v[54:55], v[62:63], v[68:69] op_sel_hi:[0,1,1]
	v_pk_mul_f32 v[46:47], v[90:91], v[116:117]
	v_pk_mul_f32 v[86:87], v[86:87], s[0:1] op_sel_hi:[1,0]
	s_waitcnt vmcnt(4)
	v_pk_add_f32 v[0:1], v[0:1], v[74:75]
	v_pk_add_f32 v[2:3], v[2:3], v[76:77]
	v_mul_f32_e32 v0, 0xbfb8aa3b, v0
	v_exp_f32_e32 v0, v0
	s_waitcnt vmcnt(2)
	v_pk_add_f32 v[10:11], v[10:11], v[100:101]
	v_pk_fma_f32 v[14:15], v[84:85], v[64:65], v[14:15]
	v_pk_add_f32 v[8:9], v[8:9], v[98:99]
	v_add_f32_e32 v0, 1.0, v0
	v_mul_f32_e32 v10, 0xbfb8aa3b, v10
	v_mul_f32_e32 v11, 0xbfb8aa3b, v11
	v_rcp_f32_e32 v64, v0
	v_mul_f32_e32 v0, 0xbfb8aa3b, v1
	v_mul_f32_e32 v1, 0xbfb8aa3b, v2
	v_mul_f32_e32 v8, 0xbfb8aa3b, v8
	v_mul_f32_e32 v9, 0xbfb8aa3b, v9
	v_exp_f32_e32 v10, v10
	v_exp_f32_e32 v11, v11
	v_exp_f32_e32 v0, v0
	v_exp_f32_e32 v1, v1
	v_mul_f32_e32 v2, 0xbfb8aa3b, v3
	v_exp_f32_e32 v8, v8
	v_exp_f32_e32 v9, v9
	v_exp_f32_e32 v2, v2
	v_add_f32_e32 v10, 1.0, v10
	v_add_f32_e32 v11, 1.0, v11
	v_add_f32_e32 v0, 1.0, v0
	v_add_f32_e32 v1, 1.0, v1
	v_add_f32_e32 v8, 1.0, v8
	v_add_f32_e32 v9, 1.0, v9
	v_rcp_f32_e32 v10, v10
	v_rcp_f32_e32 v11, v11
	v_rcp_f32_e32 v68, v1
	v_add_f32_e32 v1, 1.0, v2
	v_rcp_f32_e32 v65, v0
	v_rcp_f32_e32 v8, v8
	v_rcp_f32_e32 v9, v9
	v_rcp_f32_e32 v69, v1
	v_pk_mul_f32 v[0:1], v[10:11], s[0:1] op_sel_hi:[1,0]
	v_pk_add_f32 v[10:11], v[64:65], -1.0 op_sel_hi:[1,0]
	v_pk_fma_f32 v[12:13], v[82:83], v[62:63], v[12:13]
	v_pk_mul_f32 v[2:3], v[8:9], s[0:1] op_sel_hi:[1,0]
	v_pk_add_f32 v[8:9], v[68:69], -1.0 op_sel_hi:[1,0]
	s_waitcnt vmcnt(0)
	v_pk_fma_f32 v[10:11], v[70:71], v[10:11], 1.0 op_sel_hi:[1,1,0]
	v_pk_fma_f32 v[8:9], v[72:73], v[8:9], 1.0 op_sel_hi:[1,1,0]
	v_pk_mul_f32 v[10:11], v[10:11], v[12:13]
	v_pk_mul_f32 v[12:13], v[48:49], v[12:13]
	v_pk_mul_f32 v[48:49], v[50:51], v[14:15]
	v_pk_mul_f32 v[78:79], v[46:47], v[46:47]
	v_pk_mul_f32 v[62:63], v[8:9], v[14:15]
	v_cvt_pk_f16_f32 v9, v0, v1
	v_cvt_pk_f16_f32 v8, v2, v3
	v_pk_mul_f32 v[0:1], v[48:49], v[48:49]
	v_pk_mul_f32 v[2:3], v[12:13], v[12:13]
	v_add_f32_e32 v78, v78, v79
	v_mov_b32_e32 v45, v2
	v_mov_b32_e32 v67, v3
	v_mov_b32_e32 v79, v0
	v_mov_b32_e32 v81, v1
	v_pk_add_f32 v[2:3], v[44:45], v[66:67]
	v_pk_add_f32 v[0:1], v[78:79], v[80:81]
	v_cvt_pk_f16_f32 v7, v86, v87
	v_pk_add_f32 v[0:1], v[2:3], v[0:1]
	v_cvt_pk_f16_f32 v6, v88, v89
	v_add_f32_e32 v2, v0, v1
	v_or_b32_e32 v0, s1, v55
	v_lshlrev_b32_e32 v52, 1, v0
	v_lshl_add_u64 v[44:45], v[58:59], 0, v[52:53]
	s_mov_b64 s[0:1], 0xb078000
	v_lshl_add_u64 v[0:1], v[44:45], 0, s[0:1]
	s_mov_b64 s[0:1], 0xb078040
	v_permlane16_swap_b32_e32 v21, v23
	global_store_dwordx4 v[0:1], v[20:23], off sc1
	s_nop 1
	v_lshl_add_u64 v[0:1], v[44:45], 0, s[0:1]
	v_permlane16_swap_b32_e32 v6, v8
	v_permlane16_swap_b32_e32 v7, v9
	global_store_dwordx4 v[0:1], v[6:9], off sc1
	s_nop 1
	v_mbcnt_lo_u32_b32 v0, -1, 0
	v_mbcnt_hi_u32_b32 v0, -1, v0
	v_and_b32_e32 v3, 64, v0
	v_xor_b32_e32 v1, 16, v0
	v_add_u32_e32 v3, 64, v3
	v_cmp_lt_i32_e32 vcc, v1, v3
	s_mov_b64 s[0:1], 0xb078400
	v_permlane16_swap_b32_e32 v16, v18
	v_cndmask_b32_e32 v1, v0, v1, vcc
	v_lshlrev_b32_e32 v1, 2, v1
	ds_bpermute_b32 v1, v1, v2
	v_permlane16_swap_b32_e32 v17, v19
	v_cvt_pk_f16_f32 v61, v94, v95
	v_cvt_pk_f16_f32 v60, v96, v97
	s_waitcnt lgkmcnt(0)
	v_add_f32_e32 v2, v2, v1
	v_xor_b32_e32 v1, 32, v0
	v_cmp_lt_i32_e32 vcc, v1, v3
	v_cvt_pk_f16_f32 v63, v62, v63
	v_cvt_pk_f16_f32 v62, v10, v11
	v_cndmask_b32_e32 v0, v0, v1, vcc
	v_lshlrev_b32_e32 v0, 2, v0
	ds_bpermute_b32 v3, v0, v2
	v_lshl_add_u64 v[0:1], v[44:45], 0, s[0:1]
	global_store_dwordx4 v[0:1], v[16:19], off sc1
	s_nop 1
	s_mov_b32 s0, 0xf800000
	v_permlane16_swap_b32_e32 v60, v62
	s_waitcnt lgkmcnt(0)
	v_add_f32_e32 v0, v2, v3
	v_mul_f32_e32 v1, 0x4f800000, v0
	v_cmp_gt_f32_e32 vcc, s0, v0
	v_permlane16_swap_b32_e32 v61, v63
	s_nop 0
	v_cndmask_b32_e32 v0, v0, v1, vcc
	v_sqrt_f32_e32 v1, v0
	s_nop 0
	v_add_u32_e32 v2, -1, v1
	v_fma_f32 v3, -v2, v1, v0
	v_cmp_ge_f32_e64 s[0:1], 0, v3
	v_add_u32_e32 v3, 1, v1
	s_nop 0
	v_cndmask_b32_e64 v2, v1, v2, s[0:1]
	v_fma_f32 v1, -v3, v1, v0
	v_cmp_lt_f32_e64 s[0:1], 0, v1
	s_nop 1
	v_cndmask_b32_e64 v1, v2, v3, s[0:1]
	v_mul_f32_e32 v2, 0x37800000, v1
	v_cndmask_b32_e32 v1, v1, v2, vcc
	v_mov_b32_e32 v2, 0x260
	v_cmp_class_f32_e32 vcc, v0, v2
	s_nop 1
	v_cndmask_b32_e32 v0, v1, v0, vcc
	v_max_f32_e32 v2, 0x2b8cbccc, v0
	v_div_scale_f32 v3, s[0:1], v2, v2, 1.0
	v_rcp_f32_e32 v6, v3
	s_mov_b64 s[0:1], 0xb078440
	v_lshl_add_u64 v[0:1], v[44:45], 0, s[0:1]
	global_store_dwordx4 v[0:1], v[60:63], off sc1
	s_nop 1
	v_fma_f32 v0, -v3, v6, 1.0
	v_fmac_f32_e32 v6, v0, v6
	v_div_scale_f32 v0, vcc, 1.0, v2, 1.0
	v_mul_f32_e32 v1, v0, v6
	v_fma_f32 v7, -v3, v1, v0
	v_fmac_f32_e32 v1, v7, v6
	v_fma_f32 v0, -v3, v1, v0
	v_div_fmas_f32 v0, v0, v6, v1
	v_div_fixup_f32 v16, v0, v2, 1.0
	v_pk_mul_f32 v[2:3], v[30:31], v[16:17] op_sel_hi:[1,0]
	v_pk_mul_f32 v[6:7], v[28:29], v[16:17] op_sel_hi:[1,0]
	v_pk_mul_f32 v[0:1], v[24:25], v[2:3]
	v_pk_mul_f32 v[8:9], v[26:27], v[6:7]
	v_cvt_pk_f16_f32 v0, v0, v1
	v_cvt_pk_f16_f32 v1, v8, v9
	v_pk_mul_f32 v[10:11], v[38:39], v[16:17] op_sel_hi:[1,0]
	v_pk_mul_f32 v[8:9], v[36:37], v[16:17] op_sel_hi:[1,0]
	v_cvt_pk_f16_f32 v7, v6, v7
	v_cvt_pk_f16_f32 v6, v2, v3
	v_pk_mul_f32 v[2:3], v[32:33], v[10:11]
	v_pk_mul_f32 v[14:15], v[34:35], v[8:9]
	v_pk_mul_f32 v[18:19], v[46:47], v[16:17] op_sel_hi:[1,0]
	v_pk_mul_f32 v[4:5], v[4:5], v[16:17] op_sel_hi:[1,0]
	v_cvt_pk_f16_f32 v2, v2, v3
	v_cvt_pk_f16_f32 v3, v14, v15
	v_cvt_pk_f16_f32 v9, v8, v9
	v_cvt_pk_f16_f32 v8, v10, v11
	v_pk_mul_f32 v[10:11], v[40:41], v[18:19]
	v_pk_mul_f32 v[14:15], v[42:43], v[4:5]
	v_cvt_pk_f16_f32 v10, v10, v11
	v_cvt_pk_f16_f32 v11, v14, v15
	v_cvt_pk_f16_f32 v15, v4, v5
	v_pk_mul_f32 v[4:5], v[12:13], v[16:17] op_sel_hi:[1,0]
	v_pk_mul_f32 v[16:17], v[48:49], v[16:17] op_sel_hi:[1,0]
	v_cvt_pk_f16_f32 v14, v18, v19
	v_pk_mul_f32 v[12:13], v[64:65], v[4:5]
	v_pk_mul_f32 v[18:19], v[68:69], v[16:17]
	v_cvt_pk_f16_f32 v17, v16, v17
	v_cvt_pk_f16_f32 v16, v4, v5
	v_permlane16_swap_b32_e32 v6, v8
	v_permlane16_swap_b32_e32 v7, v9
	v_lshl_add_u64 v[4:5], v[56:57], 0, v[52:53]
	global_store_dwordx4 v[4:5], v[6:9], off sc1
	s_nop 1
	v_permlane16_swap_b32_e32 v14, v16
	v_permlane16_swap_b32_e32 v15, v17
	v_lshl_add_u64 v[4:5], v[4:5], 0, 64
	global_store_dwordx4 v[4:5], v[14:17], off sc1
	s_nop 1
	s_mov_b64 s[0:1], 0x1670400
	v_cvt_pk_f16_f32 v12, v12, v13
	v_cvt_pk_f16_f32 v13, v18, v19
	v_permlane16_swap_b32_e32 v0, v2
	v_permlane16_swap_b32_e32 v1, v3
	v_lshl_add_u64 v[4:5], v[44:45], 0, s[0:1]
	global_store_dwordx4 v[4:5], v[0:3], off sc1
	s_nop 1
	s_mov_b64 s[0:1], 0x1670440
	v_permlane16_swap_b32_e32 v10, v12
	v_permlane16_swap_b32_e32 v11, v13
	v_lshl_add_u64 v[0:1], v[44:45], 0, s[0:1]
	global_store_dwordx4 v[0:1], v[10:13], off sc1
	s_nop 1

.LBB0_313:
	s_mov_b64 exec, -1
	s_mov_b64 s[2:3], 0
	v_bfe_u32 v0, v154, 6, 2
	s_mov_b32 m0, 0
	v_mul_lo_u32 v0, v0, s13
	v_add_u32_e32 v0, s91, v0
.Llora_pass_0:
	s_movk_i32 s0, 0x420
	v_cmp_gt_i32_e32 vcc, s0, v0
	s_and_saveexec_b64 s[4:5], vcc
	s_cbranch_execz .LBB0_321
	v_mov_b32_e32 v38, v154
	v_lshlrev_b32_e32 v0, 4, v0
	s_movk_i32 s0, 0x3fff
	v_and_or_b32 v24, v38, 15, v0
	v_cmp_lt_i32_e32 vcc, s0, v24
	v_add_u32_e32 v1, -1, v24
	s_and_saveexec_b64 s[0:1], vcc
	s_xor_b64 s[0:1], exec, s[0:1]
	v_add_u32_e32 v2, 0xffffc000, v24
	v_and_b32_e32 v0, 3, v38
	v_lshrrev_b32_e32 v2, 2, v2
	v_add_u32_e32 v2, 0x4200, v2
	v_cmp_eq_u32_e32 vcc, 0, v0
	s_nop 1
	v_cndmask_b32_e32 v0, v1, v2, vcc
	s_andn2_saveexec_b64 s[0:1], s[0:1]
	v_and_b32_e32 v0, 0x7ff, v24
	v_cmp_ne_u32_e32 vcc, 0, v0
	s_nop 1
	v_cndmask_b32_e32 v0, -1, v1, vcc
	s_or_b64 exec, exec, s[0:1]
	v_cmp_lt_i32_e32 vcc, -1, v0
	s_movk_i32 s10, 0x1d00
	v_mov_b64_e32 v[2:3], s[22:23]
	v_cndmask_b32_e32 v28, 0, v0, vcc
	v_mad_i64_i32 v[4:5], s[0:1], v24, s10, v[2:3]
	v_mad_u64_u32 v[0:1], s[0:1], v28, s10, v[2:3]
	v_bfe_u32 v33, v38, 4, 2
	s_mov_b64 s[0:1], 0x1000
	s_mov_b64 s[6:7], 0x1080
	v_mov_b32_e32 v35, 0
	v_lshl_add_u64 v[16:17], v[4:5], 0, s[0:1]
	v_lshl_add_u64 v[18:19], v[4:5], 0, s[6:7]
	v_lshl_add_u64 v[20:21], v[0:1], 0, s[0:1]
	v_lshl_add_u64 v[22:23], v[0:1], 0, s[6:7]
	v_lshlrev_b32_e32 v34, 4, v33
	v_lshlrev_b32_e32 v26, 5, v33
	v_mov_b32_e32 v27, v35
	v_lshl_add_u64 v[4:5], v[16:17], 0, v[34:35]
	v_lshl_add_u64 v[0:1], v[18:19], 0, v[34:35]
	v_lshl_add_u64 v[12:13], v[20:21], 0, v[34:35]
	v_lshl_add_u64 v[6:7], v[22:23], 0, v[34:35]
	v_lshl_add_u64 v[30:31], s[44:45], 0, v[26:27]
	s_movk_i32 s0, 0x2000
	v_cndmask_b32_e64 v32, 0, 1.0, vcc
	global_load_dwordx4 v[0:3], v[0:1], off
	s_nop 0
	global_load_dwordx4 v[8:11], v[4:5], off
	s_nop 0
	global_load_dwordx4 v[4:7], v[6:7], off
	s_nop 0
	global_load_dwordx4 v[12:15], v[12:13], off
	v_add_co_u32_e32 v36, vcc, s0, v30
	s_mov_b64 s[6:7], 0x2000
	s_nop 0
	v_addc_co_u32_e32 v37, vcc, 0, v31, vcc
	global_load_dwordx4 v[40:43], v[36:37], off
	global_load_dwordx4 v[44:47], v[36:37], off offset:256
	v_lshl_add_u64 v[26:27], v[30:31], 0, s[6:7]
	global_load_dwordx4 v[48:51], v[26:27], off offset:16
	s_mov_b64 s[0:1], 0x2100
	v_lshl_add_u64 v[52:53], v[30:31], 0, s[0:1]
	global_load_dwordx4 v[52:55], v[52:53], off offset:16
	v_mov_b32_e32 v57, v35
	v_or_b32_e32 v56, 64, v34
	v_lshl_add_u64 v[58:59], v[16:17], 0, v[56:57]
	v_lshl_add_u64 v[16:17], v[18:19], 0, v[56:57]
	v_lshl_add_u64 v[64:65], v[20:21], 0, v[56:57]
	v_lshl_add_u64 v[20:21], v[22:23], 0, v[56:57]
	global_load_dwordx4 v[16:19], v[16:17], off
	s_nop 0
	global_load_dwordx4 v[56:59], v[58:59], off
	s_nop 0
	global_load_dwordx4 v[60:63], v[36:37], off offset:128
	s_nop 0
	global_load_dwordx4 v[20:23], v[20:21], off
	s_nop 0
	global_load_dwordx4 v[64:67], v[64:65], off
	s_mov_b64 s[0:1], 0x2080
	v_ashrrev_i32_e32 v25, 31, v24
	v_mad_i64_i32 v[26:27], s[8:9], v24, s10, 0
	v_lshlrev_b32_e32 v74, 3, v33
	v_mad_u64_u32 v[28:29], s[8:9], v28, s10, 0
	v_or_b32_e32 v26, v26, v74
	v_or_b32_e32 v28, v28, v74
	s_mov_b64 s[8:9], 0
	s_mov_b32 s10, 0x37f0000
	s_mov_b32 s36, 0x3f1b4598
	s_mov_b32 s11, 0x1301000
	s_mov_b32 s34, 0x1321000
	s_mov_b32 s35, 0xf800000
	v_mov_b32_e32 v84, 0x260
	s_mov_b64 s[42:43], s[56:57]
	s_mov_b64 s[48:49], s[44:45]
	s_mov_b64 s[52:53], s[54:55]
	s_mov_b64 s[72:73], s[50:51]
	s_mov_b64 s[78:79], s[46:47]
	s_waitcnt vmcnt(12)
	v_cvt_f32_f16_e32 v68, v0
	v_cvt_f32_f16_sdwa v69, v0 dst_sel:DWORD dst_unused:UNUSED_PAD src0_sel:WORD_1
	s_waitcnt vmcnt(10)
	v_cvt_f32_f16_e32 v72, v4
	s_waitcnt vmcnt(9)
	v_fma_mix_f32 v0, v32, v12, -v8 op_sel_hi:[0,1,1]
	v_fma_mix_f32 v12, v32, v12, -v8 op_sel:[0,1,1] op_sel_hi:[0,1,1]
	v_cvt_f32_f16_sdwa v73, v4 dst_sel:DWORD dst_unused:UNUSED_PAD src0_sel:WORD_1
	v_fma_mix_f32 v4, v32, v13, -v9 op_sel_hi:[0,1,1]
	v_fma_mix_f32 v13, v32, v13, -v9 op_sel:[0,1,1] op_sel_hi:[0,1,1]
	s_waitcnt vmcnt(8)
	v_fma_mix_f32 v0, v40, v0, v8 op_sel_hi:[0,0,1]
	v_fma_mix_f32 v8, v12, v41, v8 op_sel:[0,0,1] op_sel_hi:[0,0,1]
	v_add_f32_e32 v0, v0, v0
	v_add_f32_e32 v8, v8, v8
	v_mul_f32_e32 v0, 0x3fb8aa3b, v0
	v_mul_f32_e32 v8, 0x3fb8aa3b, v8
	v_fma_mix_f32 v4, v4, v42, v9 op_sel_hi:[0,0,1]
	v_fma_mix_f32 v9, v13, v43, v9 op_sel:[0,0,1] op_sel_hi:[0,0,1]
	v_exp_f32_e32 v0, v0
	v_exp_f32_e32 v13, v8
	v_add_f32_e32 v4, v4, v4
	v_add_f32_e32 v9, v9, v9
	v_mul_f32_e32 v4, 0x3fb8aa3b, v4
	v_mul_f32_e32 v12, 0x3fb8aa3b, v9
	v_exp_f32_e32 v4, v4
	v_exp_f32_e32 v39, v12
	v_add_f32_e32 v0, 1.0, v0
	v_add_f32_e32 v13, 1.0, v13
	v_rcp_f32_e32 v12, v0
	v_rcp_f32_e32 v13, v13
	v_add_f32_e32 v4, 1.0, v4
	v_add_f32_e32 v0, 1.0, v39
	v_rcp_f32_e32 v40, v4
	v_rcp_f32_e32 v41, v0
	v_pk_fma_f32 v[12:13], v[12:13], 2.0, 1.0 op_sel_hi:[1,0,0] neg_lo:[1,0,0] neg_hi:[1,0,0]
	v_cvt_f32_f16_e32 v70, v1
	v_cvt_pk_f16_f32 v0, v12, v13
	v_cvt_f32_f16_sdwa v71, v1 dst_sel:DWORD dst_unused:UNUSED_PAD src0_sel:WORD_1
	v_cvt_f32_f16_e32 v12, v5
	v_cvt_f32_f16_sdwa v13, v5 dst_sel:DWORD dst_unused:UNUSED_PAD src0_sel:WORD_1
	v_pk_fma_f32 v[8:9], v[32:33], v[72:73], v[68:69] op_sel_hi:[0,1,1] neg_lo:[0,0,1] neg_hi:[0,0,1]
	s_waitcnt vmcnt(7)
	v_pk_fma_f32 v[8:9], v[44:45], v[8:9], v[68:69]
	v_lshl_add_u64 v[44:45], v[30:31], 0, s[0:1]
	v_cvt_pk_f16_f32 v4, v8, v9
	v_pk_fma_f32 v[8:9], v[40:41], 2.0, 1.0 op_sel_hi:[1,0,0] neg_lo:[1,0,0] neg_hi:[1,0,0]
	global_load_dwordx4 v[40:43], v[36:37], off offset:384
	v_cvt_pk_f16_f32 v1, v8, v9
	v_pk_fma_f32 v[8:9], v[32:33], v[12:13], v[70:71] op_sel_hi:[0,1,1] neg_lo:[0,0,1] neg_hi:[0,0,1]
	v_fma_mix_f32 v5, v32, v14, -v10 op_sel_hi:[0,1,1]
	v_pk_fma_f32 v[8:9], v[8:9], v[46:47], v[70:71]
	global_load_dwordx4 v[44:47], v[44:45], off offset:16
	s_waitcnt vmcnt(8)
	v_fma_mix_f32 v5, v5, v48, v10 op_sel_hi:[0,0,1]
	v_fma_mix_f32 v12, v32, v14, -v10 op_sel:[0,1,1] op_sel_hi:[0,1,1]
	v_add_f32_e32 v5, v5, v5
	v_fma_mix_f32 v10, v12, v49, v10 op_sel:[0,0,1] op_sel_hi:[0,0,1]
	v_mul_f32_e32 v5, 0x3fb8aa3b, v5
	v_add_f32_e32 v10, v10, v10
	v_exp_f32_e32 v5, v5
	v_mul_f32_e32 v10, 0x3fb8aa3b, v10
	v_exp_f32_e32 v10, v10
	v_cvt_f32_f16_e32 v48, v6
	v_add_f32_e32 v5, 1.0, v5
	v_cvt_f32_f16_sdwa v49, v6 dst_sel:DWORD dst_unused:UNUSED_PAD src0_sel:WORD_1
	v_fma_mix_f32 v6, v32, v15, -v11 op_sel_hi:[0,1,1]
	v_rcp_f32_e32 v12, v5
	v_add_f32_e32 v5, 1.0, v10
	v_fma_mix_f32 v6, v6, v50, v11 op_sel_hi:[0,0,1]
	v_fma_mix_f32 v10, v32, v15, -v11 op_sel:[0,1,1] op_sel_hi:[0,1,1]
	v_add_f32_e32 v6, v6, v6
	v_fma_mix_f32 v10, v10, v51, v11 op_sel:[0,0,1] op_sel_hi:[0,0,1]
	v_mul_f32_e32 v6, 0x3fb8aa3b, v6
	v_add_f32_e32 v10, v10, v10
	v_exp_f32_e32 v6, v6
	v_mul_f32_e32 v10, 0x3fb8aa3b, v10
	v_exp_f32_e32 v11, v10
	v_rcp_f32_e32 v13, v5
	v_cvt_f32_f16_e32 v36, v2
	v_cvt_f32_f16_sdwa v37, v2 dst_sel:DWORD dst_unused:UNUSED_PAD src0_sel:WORD_1
	v_add_f32_e32 v6, 1.0, v6
	v_rcp_f32_e32 v10, v6
	v_add_f32_e32 v6, 1.0, v11
	v_rcp_f32_e32 v11, v6
	v_cvt_pk_f16_f32 v5, v8, v9
	v_pk_fma_f32 v[8:9], v[12:13], 2.0, 1.0 op_sel_hi:[1,0,0] neg_lo:[1,0,0] neg_hi:[1,0,0]
	s_mov_b64 s[0:1], 0x2180
	v_cvt_pk_f16_f32 v2, v8, v9
	v_pk_fma_f32 v[8:9], v[32:33], v[48:49], v[36:37] op_sel_hi:[0,1,1] neg_lo:[0,0,1] neg_hi:[0,0,1]
	s_waitcnt vmcnt(7)
	v_pk_fma_f32 v[8:9], v[8:9], v[52:53], v[36:37]
	v_cvt_f32_f16_e32 v14, v7
	v_cvt_pk_f16_f32 v6, v8, v9
	v_pk_fma_f32 v[8:9], v[10:11], 2.0, 1.0 op_sel_hi:[1,0,0] neg_lo:[1,0,0] neg_hi:[1,0,0]
	v_lshl_add_u64 v[10:11], v[30:31], 0, s[0:1]
	global_load_dwordx4 v[48:51], v[10:11], off offset:16
	v_cvt_f32_f16_sdwa v15, v7 dst_sel:DWORD dst_unused:UNUSED_PAD src0_sel:WORD_1
	s_waitcnt vmcnt(3)
	v_fma_mix_f32 v7, v32, v64, -v56 op_sel_hi:[0,1,1]
	v_fma_mix_f32 v7, v60, v7, v56 op_sel_hi:[0,0,1]
	v_fma_mix_f32 v10, v32, v64, -v56 op_sel:[0,1,1] op_sel_hi:[0,1,1]
	v_add_f32_e32 v7, v7, v7
	v_fma_mix_f32 v10, v10, v61, v56 op_sel:[0,0,1] op_sel_hi:[0,0,1]
	v_mul_f32_e32 v7, 0x3fb8aa3b, v7
	v_add_f32_e32 v10, v10, v10
	v_exp_f32_e32 v7, v7
	v_mul_f32_e32 v10, 0x3fb8aa3b, v10
	v_exp_f32_e32 v11, v10
	v_cvt_f32_f16_e32 v12, v3
	v_cvt_f32_f16_sdwa v13, v3 dst_sel:DWORD dst_unused:UNUSED_PAD src0_sel:WORD_1
	v_add_f32_e32 v7, 1.0, v7
	v_rcp_f32_e32 v10, v7
	v_add_f32_e32 v7, 1.0, v11
	v_rcp_f32_e32 v11, v7
	v_cvt_pk_f16_f32 v3, v8, v9
	v_pk_fma_f32 v[8:9], v[32:33], v[14:15], v[12:13] op_sel_hi:[0,1,1] neg_lo:[0,0,1] neg_hi:[0,0,1]
	v_pk_fma_f32 v[8:9], v[8:9], v[54:55], v[12:13]
	v_cvt_f32_f16_e32 v12, v16
	v_cvt_f32_f16_sdwa v13, v16 dst_sel:DWORD dst_unused:UNUSED_PAD src0_sel:WORD_1
	v_cvt_f32_f16_e32 v14, v20
	v_cvt_f32_f16_sdwa v15, v20 dst_sel:DWORD dst_unused:UNUSED_PAD src0_sel:WORD_1
	v_cvt_pk_f16_f32 v7, v8, v9
	v_pk_fma_f32 v[8:9], v[10:11], 2.0, 1.0 op_sel_hi:[1,0,0] neg_lo:[1,0,0] neg_hi:[1,0,0]
	v_cvt_f32_f16_e32 v16, v17
	v_cvt_pk_f16_f32 v8, v8, v9
	v_fma_mix_f32 v9, v32, v65, -v57 op_sel_hi:[0,1,1]
	v_pk_fma_f32 v[10:11], v[32:33], v[14:15], v[12:13] op_sel_hi:[0,1,1] neg_lo:[0,0,1] neg_hi:[0,0,1]
	v_fma_mix_f32 v9, v9, v62, v57 op_sel_hi:[0,0,1]
	v_fma_mix_f32 v14, v32, v65, -v57 op_sel:[0,1,1] op_sel_hi:[0,1,1]
	v_add_f32_e32 v9, v9, v9
	v_fma_mix_f32 v14, v14, v63, v57 op_sel:[0,0,1] op_sel_hi:[0,0,1]
	v_mul_f32_e32 v9, 0x3fb8aa3b, v9
	v_add_f32_e32 v14, v14, v14
	v_exp_f32_e32 v9, v9
	v_mul_f32_e32 v14, 0x3fb8aa3b, v14
	v_exp_f32_e32 v15, v14
	s_waitcnt vmcnt(2)
	v_pk_fma_f32 v[10:11], v[40:41], v[10:11], v[12:13]
	v_add_f32_e32 v9, 1.0, v9
	v_rcp_f32_e32 v14, v9
	v_add_f32_e32 v9, 1.0, v15
	v_rcp_f32_e32 v15, v9
	v_fma_mix_f32 v13, v32, v66, -v58 op_sel_hi:[0,1,1]
	v_cvt_pk_f16_f32 v12, v10, v11
	s_waitcnt vmcnt(1)
	v_fma_mix_f32 v13, v13, v44, v58 op_sel_hi:[0,0,1]
	v_pk_fma_f32 v[10:11], v[14:15], 2.0, 1.0 op_sel_hi:[1,0,0] neg_lo:[1,0,0] neg_hi:[1,0,0]
	v_fma_mix_f32 v14, v32, v66, -v58 op_sel:[0,1,1] op_sel_hi:[0,1,1]
	v_add_f32_e32 v13, v13, v13
	v_fma_mix_f32 v14, v14, v45, v58 op_sel:[0,0,1] op_sel_hi:[0,0,1]
	v_mul_f32_e32 v13, 0x3fb8aa3b, v13
	v_add_f32_e32 v14, v14, v14
	v_exp_f32_e32 v13, v13
	v_mul_f32_e32 v14, 0x3fb8aa3b, v14
	v_exp_f32_e32 v15, v14
	v_cvt_f32_f16_sdwa v17, v17 dst_sel:DWORD dst_unused:UNUSED_PAD src0_sel:WORD_1
	v_cvt_f32_f16_e32 v20, v21
	v_cvt_f32_f16_sdwa v21, v21 dst_sel:DWORD dst_unused:UNUSED_PAD src0_sel:WORD_1
	v_add_f32_e32 v13, 1.0, v13
	v_rcp_f32_e32 v14, v13
	v_add_f32_e32 v13, 1.0, v15
	v_rcp_f32_e32 v15, v13
	v_cvt_pk_f16_f32 v9, v10, v11
	v_pk_fma_f32 v[10:11], v[32:33], v[20:21], v[16:17] op_sel_hi:[0,1,1] neg_lo:[0,0,1] neg_hi:[0,0,1]
	v_pk_fma_f32 v[10:11], v[10:11], v[42:43], v[16:17]
	v_cvt_f32_f16_e32 v16, v18
	v_cvt_pk_f16_f32 v13, v10, v11
	v_pk_fma_f32 v[10:11], v[14:15], 2.0, 1.0 op_sel_hi:[1,0,0] neg_lo:[1,0,0] neg_hi:[1,0,0]
	v_cvt_f32_f16_sdwa v17, v18 dst_sel:DWORD dst_unused:UNUSED_PAD src0_sel:WORD_1
	v_cvt_pk_f16_f32 v10, v10, v11
	v_fma_mix_f32 v11, v32, v67, -v59 op_sel_hi:[0,1,1]
	v_fma_mix_f32 v11, v11, v46, v59 op_sel_hi:[0,0,1]
	v_fma_mix_f32 v18, v32, v67, -v59 op_sel:[0,1,1] op_sel_hi:[0,1,1]
	v_add_f32_e32 v11, v11, v11
	v_fma_mix_f32 v18, v18, v47, v59 op_sel:[0,0,1] op_sel_hi:[0,0,1]
	v_mul_f32_e32 v11, 0x3fb8aa3b, v11
	v_add_f32_e32 v18, v18, v18
	v_cvt_f32_f16_e32 v20, v22
	v_cvt_f32_f16_sdwa v21, v22 dst_sel:DWORD dst_unused:UNUSED_PAD src0_sel:WORD_1
	v_exp_f32_e32 v11, v11
	v_mul_f32_e32 v18, 0x3fb8aa3b, v18
	v_exp_f32_e32 v18, v18
	v_pk_fma_f32 v[14:15], v[32:33], v[20:21], v[16:17] op_sel_hi:[0,1,1] neg_lo:[0,0,1] neg_hi:[0,0,1]
	v_add_f32_e32 v11, 1.0, v11
	s_waitcnt vmcnt(0)
	v_pk_fma_f32 v[14:15], v[14:15], v[48:49], v[16:17]
	v_rcp_f32_e32 v16, v11
	v_add_f32_e32 v11, 1.0, v18
	v_rcp_f32_e32 v17, v11
	v_cvt_f32_f16_e32 v18, v19
	v_cvt_f32_f16_sdwa v19, v19 dst_sel:DWORD dst_unused:UNUSED_PAD src0_sel:WORD_1
	v_cvt_f32_f16_e32 v20, v23
	v_cvt_f32_f16_sdwa v21, v23 dst_sel:DWORD dst_unused:UNUSED_PAD src0_sel:WORD_1
	v_pk_fma_f32 v[16:17], v[16:17], 2.0, 1.0 op_sel_hi:[1,0,0] neg_lo:[1,0,0] neg_hi:[1,0,0]
	v_cvt_pk_f16_f32 v14, v14, v15
	v_cvt_pk_f16_f32 v11, v16, v17
	v_pk_fma_f32 v[16:17], v[32:33], v[20:21], v[18:19] op_sel_hi:[0,1,1] neg_lo:[0,0,1] neg_hi:[0,0,1]
	v_pk_fma_f32 v[16:17], v[16:17], v[50:51], v[18:19]
	v_and_b32_e32 v20, 15, v38
	v_cvt_pk_f16_f32 v15, v16, v17
	v_lshlrev_b32_e32 v16, 2, v33
	v_and_b32_e32 v17, 16, v38
	v_add_u32_e32 v18, 12, v16
	v_cmp_eq_u32_e32 vcc, 0, v17
	v_lshlrev_b32_e32 v20, 7, v20
	v_mov_b32_e32 v21, v35
	v_cndmask_b32_e32 v22, v18, v16, vcc
	v_lshlrev_b64 v[16:17], 11, v[24:25]
	v_lshl_add_u64 v[18:19], s[30:31], 0, v[16:17]
	v_lshl_add_u64 v[16:17], s[14:15], 0, v[16:17]
	v_lshl_add_u64 v[38:39], s[14:15], 0, v[20:21]
	v_lshlrev_b32_e32 v20, 1, v22
	v_lshl_add_u64 v[16:17], v[16:17], 0, v[20:21]
	s_mov_b64 s[0:1], 0x1670400
	v_lshl_add_u64 v[44:45], v[16:17], 0, s[0:1]
	s_mov_b64 s[0:1], 0xb078400
	v_lshl_add_u64 v[48:49], v[16:17], 0, s[0:1]
	s_mov_b64 s[0:1], 0xb078000
	v_lshl_add_u64 v[50:51], v[16:17], 0, s[0:1]
	v_mbcnt_lo_u32_b32 v16, -1, 0
	v_mov_b32_e32 v33, v32
	v_mov_b32_e32 v36, v32
	v_mov_b32_e32 v37, v32
	v_lshl_add_u64 v[40:41], s[14:15], 0, v[26:27]
	v_lshl_add_u64 v[42:43], s[14:15], 0, v[28:29]
	v_lshl_add_u64 v[46:47], v[18:19], 0, v[20:21]
	v_mbcnt_hi_u32_b32 v85, -1, v16
	v_readfirstlane_b32 s0, v154
	s_nop 3
	s_bfe_u32 s0, s0, 0x10008
	s_lshl_b32 s0, s0, 2
	s_mov_b32 s1, 4
	s_cmp_eq_u32 m0, 0
	s_cbranch_scc1 .Llora_set_0
	s_and_b32 s0, s91, 7
	s_mov_b32 s1, 1
.Llora_set_0:
	s_lshl_b32 s8, s0, 7
	s_add_u32 s1, s1, s0
	s_lshl_b32 s101, s1, 7
	s_lshl_b32 s1, s0, 8
	s_add_u32 s78, s78, s1
	s_addc_u32 s79, s79, 0
	s_add_u32 s72, s72, s1
	s_addc_u32 s73, s73, 0
	s_add_u32 s52, s52, s1
	s_addc_u32 s53, s53, 0
	s_add_u32 s48, s48, s1
	s_addc_u32 s49, s49, 0
	s_add_u32 s42, s42, s1
	s_addc_u32 s43, s43, 0
	s_lshl_b32 s0, s0, 13
	s_mov_b32 s1, 0
	v_lshl_add_u64 v[38:39], v[38:39], 0, s[0:1]
.LBB0_320:
	v_and_b32_e32 v246, 15, v85
	v_lshl_add_u32 v246, v246, 7, v34
	s_lshl_b32 s0, s8, 6
	v_add_u32_e32 v246, s0, v246
	v_add_u32_e32 v247, 0x10000, v246
	s_lshl_b32 s0, s8, 1
	s_add_u32 s0, s0, 0x21000
	v_add_u32_e32 v245, s0, v34
	v_lshl_add_u64 v[16:17], v[40:41], 0, s[8:9]
	v_add_co_u32_e64 v138, s[0:1], s10, v16
	v_lshl_add_u64 v[18:19], v[42:43], 0, s[8:9]
	s_nop 0
	v_addc_co_u32_e64 v139, s[0:1], 0, v17, s[0:1]
	v_add_co_u32_e64 v140, s[0:1], s10, v18
	v_lshl_add_u64 v[52:53], v[38:39], 0, v[34:35]
	s_nop 0
	v_addc_co_u32_e64 v141, s[0:1], 0, v19, s[0:1]
	v_add_co_u32_e64 v160, s[0:1], s11, v52
	v_and_b32_e32 v64, 64, v85
	s_nop 0
	v_addc_co_u32_e64 v161, s[0:1], 0, v53, s[0:1]
	v_add_co_u32_e64 v168, s[0:1], s34, v52
	v_xor_b32_e32 v155, 16, v85
	s_nop 0
	v_addc_co_u32_e64 v169, s[0:1], 0, v53, s[0:1]
	v_add_u32_e32 v173, 64, v64
	v_xor_b32_e32 v172, 32, v85
	v_add_co_u32_e32 v82, vcc, 0x1300000, v52
	v_cmp_lt_i32_e64 s[0:1], v155, v173
	v_lshl_add_u64 v[24:25], s[78:79], 0, v[34:35]
	v_lshl_add_u64 v[26:27], s[72:73], 0, v[34:35]
	v_lshl_add_u64 v[28:29], s[52:53], 0, v[34:35]
	v_lshl_add_u64 v[30:31], s[48:49], 0, v[34:35]
	v_addc_co_u32_e32 v83, vcc, 0, v53, vcc
	v_cndmask_b32_e64 v155, v85, v155, s[0:1]
	v_cmp_lt_i32_e64 s[0:1], v172, v173
	v_lshl_add_u64 v[54:55], s[42:43], 0, v[34:35]
	ds_read_b128 v[86:89], v245 offset:0
	ds_read_b128 v[90:93], v245 offset:64
	ds_read_b128 v[94:97], v245 offset:2048
	ds_read_b128 v[98:101], v245 offset:2112
	ds_read_b128 v[70:73], v245 offset:4096
	ds_read_b128 v[74:77], v245 offset:4160
	ds_read_b128 v[78:81], v245 offset:6144
	ds_read_b128 v[102:105], v245 offset:6208
	ds_read_b128 v[20:23], v245 offset:8192
	ds_read_b128 v[16:19], v245 offset:8256
	ds_read_b128 v[106:109], v245 offset:128
	ds_read_b128 v[110:113], v245 offset:192
	ds_read_b128 v[114:117], v245 offset:2176
	ds_read_b128 v[118:121], v245 offset:2240
	ds_read_b128 v[122:125], v245 offset:4224
	ds_read_b128 v[126:129], v245 offset:4288
	ds_read_b128 v[130:133], v245 offset:6272
	ds_read_b128 v[134:137], v245 offset:6336
	s_nop 0
	ds_read_b128 v[28:31], v245 offset:8320
	ds_read_b128 v[24:27], v245 offset:8384
	global_load_dwordx2 v[204:205], v[138:139], off offset:1024
	global_load_dwordx2 v[206:207], v[140:141], off offset:1024
	global_load_dwordx2 v[208:209], v[138:139], off offset:1056
	global_load_dwordx2 v[210:211], v[140:141], off offset:1056
	global_load_dwordx2 v[212:213], v[138:139], off offset:1088
	global_load_dwordx2 v[214:215], v[140:141], off offset:1088
	global_load_dwordx2 v[216:217], v[138:139], off offset:1120
	global_load_dwordx2 v[218:219], v[140:141], off offset:1120
	s_nop 0
	ds_read_b128 v[138:141], v246 offset:4096
	ds_read_b128 v[142:145], v247 offset:4096
	ds_read_b128 v[146:149], v246 offset:4160
	ds_read_b128 v[150:153], v247 offset:4160
	ds_read_b128 v[156:159], v246 offset:6144
	s_nop 0
	ds_read_b128 v[160:163], v246 offset:6208
	s_nop 0
	ds_read_b128 v[164:167], v247 offset:6144
	s_nop 0
	ds_read_b128 v[168:171], v247 offset:6208
	v_cndmask_b32_e64 v188, v85, v172, s[0:1]
	ds_read_b128 v[172:175], v246 offset:0
	v_add_co_u32_e32 v52, vcc, 0x1320000, v52
	ds_read_b128 v[176:179], v246 offset:2048
	ds_read_b128 v[180:183], v246 offset:64
	ds_read_b128 v[184:187], v246 offset:2112
	v_addc_co_u32_e32 v53, vcc, 0, v53, vcc
	v_lshlrev_b32_e32 v248, 2, v188
	ds_read_b128 v[188:191], v247 offset:0
	ds_read_b128 v[192:195], v247 offset:2048
	ds_read_b128 v[196:199], v247 offset:64
	ds_read_b128 v[200:203], v247 offset:2112
	v_lshlrev_b32_e32 v155, 2, v155
	v_lshl_add_u64 v[56:57], v[50:51], 0, s[8:9]
	v_lshl_add_u64 v[68:69], v[56:57], 0, 64
	v_lshl_add_u64 v[58:59], v[48:49], 0, s[8:9]
	v_lshl_add_u64 v[66:67], v[58:59], 0, 64
	v_lshl_add_u64 v[60:61], v[46:47], 0, s[8:9]
	v_lshl_add_u64 v[62:63], v[44:45], 0, s[8:9]
	s_add_u32 s8, s8, 0x80
	s_addc_u32 s9, s9, 0
	s_add_u32 s78, s78, 0x100
	s_addc_u32 s79, s79, 0
	s_add_u32 s72, s72, 0x100
	s_addc_u32 s73, s73, 0
	s_add_u32 s52, s52, 0x100
	s_addc_u32 s53, s53, 0
	v_lshl_add_u64 v[64:65], v[60:61], 0, 64
	s_add_u32 s48, s48, 0x100
	s_addc_u32 s49, s49, 0
	v_lshl_add_u64 v[54:55], v[62:63], 0, 64
	s_add_u32 s42, s42, 0x100
	s_addc_u32 s43, s43, 0
	s_cmp_eq_u32 s8, s101
	v_lshl_add_u64 v[38:39], v[38:39], 0, s[6:7]
	s_waitcnt vmcnt(0) lgkmcnt(0)
	v_mfma_f32_16x16x32_f16 v[142:145], v[142:145], v[4:7], 0
	v_cvt_f32_f16_e32 v52, v204
	v_cvt_f32_f16_sdwa v53, v204 dst_sel:DWORD dst_unused:UNUSED_PAD src0_sel:WORD_1
	v_cvt_f32_f16_e32 v82, v205
	v_cvt_f32_f16_sdwa v83, v205 dst_sel:DWORD dst_unused:UNUSED_PAD src0_sel:WORD_1
	v_cvt_f32_f16_e32 v220, v208
	v_cvt_f32_f16_sdwa v221, v208 dst_sel:DWORD dst_unused:UNUSED_PAD src0_sel:WORD_1
	v_cvt_f32_f16_e32 v208, v209
	v_cvt_f32_f16_sdwa v209, v209 dst_sel:DWORD dst_unused:UNUSED_PAD src0_sel:WORD_1
	v_cvt_f32_f16_e32 v204, v206
	v_cvt_f32_f16_sdwa v205, v206 dst_sel:DWORD dst_unused:UNUSED_PAD src0_sel:WORD_1
	v_cvt_f32_f16_e32 v206, v207
	v_cvt_f32_f16_sdwa v207, v207 dst_sel:DWORD dst_unused:UNUSED_PAD src0_sel:WORD_1
	v_cvt_f32_f16_e32 v222, v210
	v_cvt_f32_f16_sdwa v223, v210 dst_sel:DWORD dst_unused:UNUSED_PAD src0_sel:WORD_1
	v_cvt_f32_f16_e32 v210, v211
	v_cvt_f32_f16_sdwa v211, v211 dst_sel:DWORD dst_unused:UNUSED_PAD src0_sel:WORD_1
	v_cvt_f32_f16_e32 v224, v212
	v_cvt_f32_f16_sdwa v225, v212 dst_sel:DWORD dst_unused:UNUSED_PAD src0_sel:WORD_1
	v_cvt_f32_f16_e32 v212, v213
	v_cvt_f32_f16_sdwa v213, v213 dst_sel:DWORD dst_unused:UNUSED_PAD src0_sel:WORD_1
	v_cvt_f32_f16_e32 v228, v216
	v_cvt_f32_f16_sdwa v229, v216 dst_sel:DWORD dst_unused:UNUSED_PAD src0_sel:WORD_1
	v_cvt_f32_f16_e32 v216, v217
	v_cvt_f32_f16_sdwa v217, v217 dst_sel:DWORD dst_unused:UNUSED_PAD src0_sel:WORD_1
	v_cvt_f32_f16_e32 v226, v214
	v_cvt_f32_f16_sdwa v227, v214 dst_sel:DWORD dst_unused:UNUSED_PAD src0_sel:WORD_1
	v_cvt_f32_f16_e32 v214, v215
	v_cvt_f32_f16_sdwa v215, v215 dst_sel:DWORD dst_unused:UNUSED_PAD src0_sel:WORD_1
	v_cvt_f32_f16_e32 v230, v218
	v_cvt_f32_f16_sdwa v231, v218 dst_sel:DWORD dst_unused:UNUSED_PAD src0_sel:WORD_1
	v_cvt_f32_f16_e32 v218, v219
	v_cvt_f32_f16_sdwa v219, v219 dst_sel:DWORD dst_unused:UNUSED_PAD src0_sel:WORD_1
	v_xor_b32_e32 v232, 0x80000000, v82
	v_xor_b32_e32 v233, 0x80000000, v83
	v_xor_b32_e32 v234, 0x80000000, v52
	v_mfma_f32_16x16x32_f16 v[138:141], v[138:141], v[0:3], 0
	v_xor_b32_e32 v235, 0x80000000, v53
	v_xor_b32_e32 v236, 0x80000000, v208
	v_xor_b32_e32 v237, 0x80000000, v209
	v_xor_b32_e32 v238, 0x80000000, v220
	v_xor_b32_e32 v239, 0x80000000, v221
	v_xor_b32_e32 v240, 0x80000000, v212
	s_waitcnt vmcnt(0)
	v_mfma_f32_16x16x32_f16 v[156:159], v[156:159], v[0:3], 0
	v_xor_b32_e32 v241, 0x80000000, v213
	v_xor_b32_e32 v242, 0x80000000, v224
	v_xor_b32_e32 v243, 0x80000000, v225
	s_waitcnt vmcnt(0)
	v_mfma_f32_16x16x32_f16 v[164:167], v[164:167], v[4:7], 0
	v_xor_b32_e32 v244, 0x80000000, v216
	v_xor_b32_e32 v245, 0x80000000, v217
	v_pk_fma_f32 v[206:207], v[36:37], v[206:207], v[232:233]
	s_waitcnt vmcnt(0)
	v_mfma_f32_16x16x32_f16 v[172:175], v[172:175], v[0:3], 0
	v_fma_f32 v204, v32, v204, v234
	v_fma_f32 v205, v33, v205, v235
	v_pk_fma_f32 v[210:211], v[36:37], v[210:211], v[236:237]
	v_pk_fma_f32 v[222:223], v[32:33], v[222:223], v[238:239]
	s_waitcnt vmcnt(0)
	v_mfma_f32_16x16x32_f16 v[176:179], v[176:179], v[0:3], 0
	v_xor_b32_e32 v246, 0x80000000, v228
	v_xor_b32_e32 v247, 0x80000000, v229
	v_pk_fma_f32 v[214:215], v[36:37], v[214:215], v[240:241]
	v_pk_fma_f32 v[226:227], v[32:33], v[226:227], v[242:243]
	v_pk_fma_f32 v[218:219], v[36:37], v[218:219], v[244:245]
	v_pk_fma_f32 v[204:205], v[78:79], v[204:205], v[52:53]
	v_pk_fma_f32 v[206:207], v[80:81], v[206:207], v[82:83]
	s_waitcnt vmcnt(0)
	v_mfma_f32_16x16x32_f16 v[192:195], v[192:195], v[4:7], 0
	v_fma_f32 v220, v102, v222, v220
	v_fma_f32 v221, v103, v223, v221
	v_pk_fma_f32 v[208:209], v[104:105], v[210:211], v[208:209]
	v_pk_fma_f32 v[230:231], v[32:33], v[230:231], v[246:247]
	v_pk_fma_f32 v[210:211], v[130:131], v[226:227], v[224:225]
	v_pk_fma_f32 v[212:213], v[132:133], v[214:215], v[212:213]
	v_pk_fma_f32 v[216:217], v[136:137], v[218:219], v[216:217]
	v_pk_mul_f32 v[52:53], v[70:71], v[204:205]
	v_pk_mul_f32 v[70:71], v[72:73], v[206:207]
	v_pk_mul_f32 v[72:73], v[74:75], v[220:221]
	v_pk_mul_f32 v[74:75], v[76:77], v[208:209]
	v_mfma_f32_16x16x32_f16 v[188:191], v[188:191], v[4:7], 0
	v_fma_f32 v214, v134, v230, v228
	v_fma_f32 v215, v135, v231, v229
	v_pk_mul_f32 v[76:77], v[122:123], v[210:211]
	v_pk_mul_f32 v[78:79], v[124:125], v[212:213]
	v_mfma_f32_16x16x32_f16 v[102:105], v[146:149], v[8:11], v[138:141]
	v_mul_f32_e64 v82, v128, v216
	v_mul_f32_e64 v83, v129, v217
	v_pk_mul_f32 v[146:147], v[52:53], v[52:53]
	v_pk_mul_f32 v[80:81], v[126:127], v[214:215]
	v_mfma_f32_16x16x32_f16 v[122:125], v[150:153], v[12:15], v[142:145]
	v_mul_f32_e64 v138, v70, v70
	v_mul_f32_e64 v139, v71, v71
	v_pk_mul_f32 v[150:151], v[72:73], v[72:73]
	v_pk_mul_f32 v[148:149], v[76:77], v[76:77]
	v_pk_mul_f32 v[142:143], v[74:75], v[74:75]
	v_mfma_f32_16x16x32_f16 v[126:129], v[160:163], v[8:11], v[156:159]
	v_mul_f32_e64 v152, v82, v82
	v_mul_f32_e64 v153, v83, v83
	v_pk_mov_b32 v[160:161], v[150:151], v[142:143] op_sel:[1,0]
	v_mov_b32_e32 v151, v143
	v_mfma_f32_16x16x32_f16 v[130:133], v[168:171], v[12:15], v[164:167]
	v_pk_mov_b32 v[158:159], v[146:147], v[138:139] op_sel:[1,0]
	v_mov_b32_e32 v147, v139
	v_add_f32_e32 v162, v148, v149
	v_mfma_f32_16x16x32_f16 v[134:137], v[180:183], v[8:11], v[172:175]
	v_mov_b32_e32 v163, v152
	v_mov_b32_e32 v165, v153
	v_pk_add_f32 v[152:153], v[158:159], v[146:147]
	v_mfma_f32_16x16x32_f16 v[138:141], v[184:187], v[8:11], v[176:179]
	v_add_f32_e64 v150, v160, v150
	v_add_f32_e64 v151, v161, v151
	v_pk_mul_f32 v[144:145], v[78:79], v[78:79]
	v_pk_mul_f32 v[156:157], v[80:81], v[80:81]
	s_waitcnt vmcnt(0)
	v_mfma_f32_16x16x32_f16 v[146:149], v[200:203], v[12:15], v[192:195]
	v_pk_add_f32 v[152:153], v[152:153], v[152:153] op_sel:[0,1] op_sel_hi:[1,0]
	v_pk_add_f32 v[150:151], v[150:151], v[150:151] op_sel:[0,1] op_sel_hi:[1,0]
	v_add_f32_e32 v164, v144, v145
	v_mfma_f32_16x16x32_f16 v[142:145], v[196:199], v[12:15], v[188:191]
	v_add_f32_e64 v102, v102, v106
	v_add_f32_e64 v103, v103, v107
	v_mov_b32_e32 v153, v156
	v_mov_b32_e32 v151, v157
	v_pk_add_f32 v[158:159], v[162:163], v[164:165]
	v_pk_add_f32 v[104:105], v[104:105], v[108:109]
	v_pk_add_f32 v[106:107], v[124:125], v[116:117]
	v_pk_add_f32 v[108:109], v[122:123], v[114:115]
	v_pk_add_f32 v[112:113], v[128:129], v[112:113]
	v_pk_add_f32 v[110:111], v[126:127], v[110:111]
	v_pk_add_f32 v[114:115], v[132:133], v[120:121]
	v_pk_add_f32 v[116:117], v[130:131], v[118:119]
	v_pk_add_f32 v[88:89], v[136:137], v[88:89]
	v_pk_add_f32 v[86:87], v[134:135], v[86:87]
	v_pk_add_f32 v[90:91], v[138:139], v[90:91]
	v_mul_f32_e32 v118, 0xbfb8aa3b, v102
	v_mul_f32_e32 v119, 0xbfb8aa3b, v103
	v_pk_add_f32 v[102:103], v[152:153], v[150:151]
	v_pk_add_f32 v[92:93], v[140:141], v[92:93]
	v_mul_f32_e32 v104, 0xbfb8aa3b, v104
	v_mul_f32_e32 v105, 0xbfb8aa3b, v105
	v_mul_f32_e32 v108, 0xbfb8aa3b, v108
	v_mul_f32_e32 v109, 0xbfb8aa3b, v109
	v_mul_f32_e32 v106, 0xbfb8aa3b, v106
	v_mul_f32_e32 v107, 0xbfb8aa3b, v107
	v_mul_f32_e32 v110, 0xbfb8aa3b, v110
	v_mul_f32_e32 v111, 0xbfb8aa3b, v111
	v_mul_f32_e32 v112, 0xbfb8aa3b, v112
	v_mul_f32_e32 v113, 0xbfb8aa3b, v113
	v_mul_f32_e32 v116, 0xbfb8aa3b, v116
	v_mul_f32_e32 v117, 0xbfb8aa3b, v117
	v_mul_f32_e32 v114, 0xbfb8aa3b, v114
	v_mul_f32_e32 v115, 0xbfb8aa3b, v115
	v_mul_f32_e32 v120, 0xbfb8aa3b, v86
	v_mul_f32_e32 v121, 0xbfb8aa3b, v87
	v_mul_f32_e32 v122, 0xbfb8aa3b, v88
	v_mul_f32_e32 v123, 0xbfb8aa3b, v89
	v_pk_add_f32 v[88:89], v[146:147], v[98:99]
	v_mul_f32_e32 v98, 0xbfb8aa3b, v90
	v_mul_f32_e32 v99, 0xbfb8aa3b, v91
	v_pk_add_f32 v[90:91], v[102:103], v[158:159]
	v_pk_add_f32 v[86:87], v[148:149], v[100:101]
	v_mul_f32_e32 v92, 0xbfb8aa3b, v92
	v_mul_f32_e32 v93, 0xbfb8aa3b, v93
	v_exp_f32_e32 v100, v118
	v_exp_f32_e32 v101, v119
	v_exp_f32_e32 v104, v104
	v_exp_f32_e32 v105, v105
	v_exp_f32_e32 v108, v108
	v_exp_f32_e32 v109, v109
	v_exp_f32_e32 v106, v106
	v_exp_f32_e32 v107, v107
	v_exp_f32_e32 v110, v110
	v_exp_f32_e32 v111, v111
	v_exp_f32_e32 v112, v112
	v_exp_f32_e32 v113, v113
	v_exp_f32_e32 v116, v116
	v_exp_f32_e32 v117, v117
	v_exp_f32_e32 v114, v114
	v_exp_f32_e32 v115, v115
	v_exp_f32_e32 v102, v120
	v_exp_f32_e32 v103, v121
	v_exp_f32_e32 v98, v98
	v_exp_f32_e32 v99, v99
	v_add_f32_e32 v120, v90, v91
	v_pk_add_f32 v[94:95], v[142:143], v[94:95]
	v_exp_f32_e32 v118, v122
	v_exp_f32_e32 v119, v123
	v_exp_f32_e32 v92, v92
	v_exp_f32_e32 v93, v93
	v_mul_f32_e32 v89, 0xbfb8aa3b, v89
	ds_bpermute_b32 v129, v155, v120
	v_pk_add_f32 v[96:97], v[144:145], v[96:97]
	v_mul_f32_e32 v94, 0xbfb8aa3b, v94
	v_mul_f32_e32 v86, 0xbfb8aa3b, v86
	v_exp_f32_e32 v126, v89
	v_mul_f32_e32 v95, 0xbfb8aa3b, v95
	v_mul_f32_e32 v96, 0xbfb8aa3b, v96
	v_mul_f32_e32 v97, 0xbfb8aa3b, v97
	v_mul_f32_e32 v88, 0xbfb8aa3b, v88
	v_mul_f32_e32 v87, 0xbfb8aa3b, v87
	v_exp_f32_e32 v121, v94
	v_exp_f32_e32 v127, v86
	v_exp_f32_e32 v122, v95
	v_exp_f32_e32 v123, v96
	v_exp_f32_e32 v124, v97
	v_exp_f32_e32 v125, v88
	v_exp_f32_e32 v128, v87
	v_add_f32_e32 v86, 1.0, v100
	v_add_f32_e32 v87, 1.0, v101
	v_add_f32_e32 v88, 1.0, v104
	v_add_f32_e32 v89, 1.0, v105
	v_add_f32_e32 v90, 1.0, v108
	v_add_f32_e32 v91, 1.0, v109
	v_add_f32_e32 v94, 1.0, v106
	v_add_f32_e32 v95, 1.0, v107
	v_add_f32_e32 v96, 1.0, v110
	v_add_f32_e32 v97, 1.0, v111
	v_add_f32_e32 v100, 1.0, v112
	v_add_f32_e32 v101, 1.0, v113
	v_add_f32_e32 v104, 1.0, v116
	v_add_f32_e32 v105, 1.0, v117
	v_add_f32_e32 v106, 1.0, v114
	v_add_f32_e32 v107, 1.0, v115
	v_add_f32_e32 v102, 1.0, v102
	v_add_f32_e32 v103, 1.0, v103
	v_add_f32_e32 v110, 1.0, v98
	v_add_f32_e32 v111, 1.0, v99
	v_add_f32_e32 v108, 1.0, v118
	v_add_f32_e32 v109, 1.0, v119
	v_add_f32_e32 v112, 1.0, v92
	v_add_f32_e32 v113, 1.0, v93
	v_rcp_f32_e32 v86, v86
	v_rcp_f32_e32 v87, v87
	v_rcp_f32_e32 v88, v88
	v_rcp_f32_e32 v89, v89
	v_rcp_f32_e32 v90, v90
	v_rcp_f32_e32 v91, v91
	v_rcp_f32_e32 v92, v94
	v_rcp_f32_e32 v93, v95
	v_rcp_f32_e32 v94, v96
	v_rcp_f32_e32 v95, v97
	v_rcp_f32_e32 v96, v100
	v_rcp_f32_e32 v97, v101
	v_rcp_f32_e32 v98, v104
	v_rcp_f32_e32 v99, v105
	v_rcp_f32_e32 v100, v106
	v_rcp_f32_e32 v101, v107
	v_rcp_f32_e32 v102, v102
	v_rcp_f32_e32 v103, v103
	v_rcp_f32_e32 v106, v110
	v_rcp_f32_e32 v107, v111
	v_rcp_f32_e32 v104, v108
	v_rcp_f32_e32 v105, v109
	v_rcp_f32_e32 v108, v112
	v_rcp_f32_e32 v109, v113
	v_add_f32_e32 v119, 1.0, v126
	s_waitcnt lgkmcnt(0)
	v_add_f32_e32 v126, v120, v129
	v_add_f32_e32 v114, 1.0, v121
	v_add_f32_e32 v121, 1.0, v127
	ds_bpermute_b32 v127, v248, v126
	v_add_f32_e32 v115, 1.0, v122
	v_add_f32_e32 v116, 1.0, v123
	v_add_f32_e32 v117, 1.0, v124
	v_add_f32_e32 v122, 1.0, v128
	v_add_f32_e32 v118, 1.0, v125
	v_rcp_f32_e32 v112, v116
	v_rcp_f32_e32 v113, v117
	v_rcp_f32_e32 v116, v121
	v_rcp_f32_e32 v117, v122
	v_pk_mul_f32 v[88:89], v[88:89], s[36:37] op_sel_hi:[1,0]
	v_pk_mul_f32 v[86:87], v[86:87], s[36:37] op_sel_hi:[1,0]
	v_pk_add_f32 v[120:121], v[90:91], -1.0 op_sel_hi:[1,0]
	v_pk_add_f32 v[122:123], v[100:101], -1.0 op_sel_hi:[1,0]
	v_pk_add_f32 v[124:125], v[98:99], -1.0 op_sel_hi:[1,0]
	v_pk_mul_f32 v[102:103], v[102:103], s[36:37] op_sel_hi:[1,0]
	v_pk_mul_f32 v[106:107], v[106:107], s[36:37] op_sel_hi:[1,0]
	v_rcp_f32_e32 v110, v114
	v_rcp_f32_e32 v111, v115
	v_rcp_f32_e32 v114, v118
	v_rcp_f32_e32 v115, v119
	v_pk_mul_f32 v[104:105], v[104:105], s[36:37] op_sel_hi:[1,0]
	v_pk_mul_f32 v[108:109], v[108:109], s[36:37] op_sel_hi:[1,0]
	v_pk_fma_f32 v[120:121], v[28:29], v[120:121], 1.0 op_sel_hi:[1,1,0]
	v_cvt_pk_f16_f32 v28, v86, v87
	v_cvt_pk_f16_f32 v29, v88, v89
	v_pk_fma_f32 v[86:87], v[26:27], v[122:123], 1.0 op_sel_hi:[1,1,0]
	v_pk_fma_f32 v[88:89], v[24:25], v[124:125], 1.0 op_sel_hi:[1,1,0]
	v_cvt_pk_f16_f32 v24, v102, v103
	v_cvt_pk_f16_f32 v26, v106, v107
	v_cvt_pk_f16_f32 v25, v104, v105
	v_cvt_pk_f16_f32 v27, v108, v109
	v_permlane16_swap_b32_e32 v24, v26
	s_nop 0
	v_permlane16_swap_b32_e32 v25, v27
	global_store_dwordx4 v[56:57], v[24:27], off sc1
	s_nop 1
	s_waitcnt lgkmcnt(0)
	v_add_f32_e32 v24, v126, v127
	v_pk_add_f32 v[118:119], v[92:93], -1.0 op_sel_hi:[1,0]
	v_pk_mul_f32 v[96:97], v[96:97], s[36:37] op_sel_hi:[1,0]
	v_pk_mul_f32 v[94:95], v[94:95], s[36:37] op_sel_hi:[1,0]
	v_mul_f32_e32 v25, 0x4f800000, v24
	v_cmp_gt_f32_e32 vcc, s35, v24
	v_pk_fma_f32 v[118:119], v[30:31], v[118:119], 1.0 op_sel_hi:[1,1,0]
	v_cvt_pk_f16_f32 v30, v94, v95
	v_cvt_pk_f16_f32 v31, v96, v97
	v_pk_add_f32 v[94:95], v[112:113], -1.0 op_sel_hi:[1,0]
	v_pk_add_f32 v[96:97], v[110:111], -1.0 op_sel_hi:[1,0]
	v_pk_add_f32 v[102:103], v[116:117], -1.0 op_sel_hi:[1,0]
	v_pk_add_f32 v[104:105], v[114:115], -1.0 op_sel_hi:[1,0]
	v_cndmask_b32_e32 v24, v24, v25, vcc
	v_pk_mul_f32 v[86:87], v[86:87], v[216:217]
	v_pk_mul_f32 v[88:89], v[88:89], v[214:215]
	v_pk_fma_f32 v[22:23], v[22:23], v[94:95], 1.0 op_sel_hi:[1,1,0]
	v_pk_fma_f32 v[20:21], v[20:21], v[96:97], 1.0 op_sel_hi:[1,1,0]
	v_pk_fma_f32 v[94:95], v[18:19], v[102:103], 1.0 op_sel_hi:[1,1,0]
	v_pk_fma_f32 v[96:97], v[16:17], v[104:105], 1.0 op_sel_hi:[1,1,0]
	v_sqrt_f32_e32 v25, v24
	v_pk_mul_f32 v[108:109], v[120:121], v[210:211]
	v_cvt_pk_f16_f32 v18, v88, v89
	v_cvt_pk_f16_f32 v19, v86, v87
	v_pk_mul_f32 v[22:23], v[22:23], v[206:207]
	v_pk_mul_f32 v[20:21], v[20:21], v[204:205]
	v_pk_mul_f32 v[86:87], v[94:95], v[208:209]
	v_pk_mul_f32 v[88:89], v[96:97], v[220:221]
	v_pk_mul_f32 v[106:107], v[118:119], v[212:213]
	v_permlane16_swap_b32_e32 v28, v30
	v_permlane16_swap_b32_e32 v29, v31
	v_cvt_pk_f16_f32 v16, v108, v109
	v_cvt_pk_f16_f32 v20, v20, v21
	v_cvt_pk_f16_f32 v21, v22, v23
	v_cvt_pk_f16_f32 v22, v88, v89
	v_cvt_pk_f16_f32 v23, v86, v87
	global_store_dwordx4 v[68:69], v[28:31], off sc1
	s_nop 1
	v_cvt_pk_f16_f32 v17, v106, v107
	v_permlane16_swap_b32_e32 v16, v18
	v_permlane16_swap_b32_e32 v20, v22
	v_permlane16_swap_b32_e32 v21, v23
	global_store_dwordx4 v[58:59], v[20:23], off sc1
	s_nop 1
	v_permlane16_swap_b32_e32 v17, v19
	global_store_dwordx4 v[66:67], v[16:19], off sc1
	s_nop 1
	v_add_u32_e32 v16, -1, v25
	v_add_u32_e32 v17, 1, v25
	v_fma_f32 v18, -v16, v25, v24
	v_fma_f32 v19, -v17, v25, v24
	v_cmp_ge_f32_e64 s[0:1], 0, v18
	s_nop 1
	v_cndmask_b32_e64 v16, v25, v16, s[0:1]
	v_cmp_lt_f32_e64 s[0:1], 0, v19
	s_nop 1
	v_cndmask_b32_e64 v16, v16, v17, s[0:1]
	v_mul_f32_e32 v17, 0x37800000, v16
	v_cndmask_b32_e32 v16, v16, v17, vcc
	v_cmp_class_f32_e32 vcc, v24, v84
	s_nop 1
	v_cndmask_b32_e32 v16, v16, v24, vcc
	v_max_f32_e32 v16, 0x2b8cbccc, v16
	v_div_scale_f32 v17, s[0:1], v16, v16, 1.0
	v_rcp_f32_e32 v19, v17
	v_div_scale_f32 v18, vcc, 1.0, v16, 1.0
	v_fma_f32 v20, -v17, v19, 1.0
	v_fmac_f32_e32 v19, v20, v19
	v_mul_f32_e32 v20, v18, v19
	v_fma_f32 v21, -v17, v20, v18
	v_fmac_f32_e32 v20, v21, v19
	v_fma_f32 v17, -v17, v20, v18
	v_div_fmas_f32 v17, v17, v19, v20
	v_div_fixup_f32 v16, v17, v16, 1.0
	v_pk_mul_f32 v[18:19], v[52:53], v[16:17] op_sel_hi:[1,0]
	v_pk_mul_f32 v[20:21], v[70:71], v[16:17] op_sel_hi:[1,0]
	v_pk_mul_f32 v[22:23], v[72:73], v[16:17] op_sel_hi:[1,0]
	v_pk_mul_f32 v[24:25], v[74:75], v[16:17] op_sel_hi:[1,0]
	v_pk_mul_f32 v[26:27], v[76:77], v[16:17] op_sel_hi:[1,0]
	v_pk_mul_f32 v[28:29], v[78:79], v[16:17] op_sel_hi:[1,0]
	v_pk_mul_f32 v[30:31], v[80:81], v[16:17] op_sel_hi:[1,0]
	v_pk_mul_f32 v[52:53], v[82:83], v[16:17] op_sel_hi:[1,0]
	v_pk_mul_f32 v[56:57], v[110:111], v[18:19]
	v_cvt_pk_f16_f32 v16, v18, v19
	v_cvt_pk_f16_f32 v17, v20, v21
	v_cvt_pk_f16_f32 v18, v22, v23
	v_cvt_pk_f16_f32 v19, v24, v25
	v_pk_mul_f32 v[58:59], v[112:113], v[20:21]
	v_pk_mul_f32 v[66:67], v[114:115], v[22:23]
	v_pk_mul_f32 v[68:69], v[116:117], v[24:25]
	v_cvt_pk_f16_f32 v20, v26, v27
	v_cvt_pk_f16_f32 v21, v28, v29
	v_cvt_pk_f16_f32 v22, v30, v31
	v_cvt_pk_f16_f32 v23, v52, v53
	v_permlane16_swap_b32_e32 v16, v18
	v_permlane16_swap_b32_e32 v17, v19
	global_store_dwordx4 v[60:61], v[16:19], off sc1
	s_nop 1
	v_pk_mul_f32 v[70:71], v[90:91], v[26:27]
	v_pk_mul_f32 v[72:73], v[92:93], v[28:29]
	v_pk_mul_f32 v[74:75], v[98:99], v[30:31]
	v_pk_mul_f32 v[76:77], v[100:101], v[52:53]
	v_cvt_pk_f16_f32 v24, v56, v57
	v_cvt_pk_f16_f32 v25, v58, v59
	v_cvt_pk_f16_f32 v26, v66, v67
	v_cvt_pk_f16_f32 v27, v68, v69
	v_permlane16_swap_b32_e32 v20, v22
	v_permlane16_swap_b32_e32 v21, v23
	global_store_dwordx4 v[64:65], v[20:23], off sc1
	s_nop 1
	v_cvt_pk_f16_f32 v28, v70, v71
	v_cvt_pk_f16_f32 v29, v72, v73
	v_cvt_pk_f16_f32 v30, v74, v75
	v_cvt_pk_f16_f32 v31, v76, v77
	v_permlane16_swap_b32_e32 v24, v26
	v_permlane16_swap_b32_e32 v25, v27
	global_store_dwordx4 v[62:63], v[24:27], off sc1
	s_nop 1
	v_permlane16_swap_b32_e32 v28, v30
	v_permlane16_swap_b32_e32 v29, v31
	global_store_dwordx4 v[54:55], v[28:31], off sc1
	s_nop 1
	s_cbranch_scc0 .LBB0_320
.LBB0_321:
	s_or_b64 exec, exec, s[4:5]
	s_cmp_lg_u32 m0, 0
	s_cbranch_scc1 .Llora_done_0
	v_readfirstlane_b32 s0, v154
	s_nop 3
	s_lshr_b32 s0, s0, 6
	s_cmp_lg_u32 s0, 4
	s_cbranch_scc1 .Llora_done_0
	s_mov_b32 m0, 1
	s_lshr_b32 s0, s91, 3
	s_add_u32 s0, s0, 0x400
	v_mov_b32_e32 v0, s0
	s_branch .Llora_pass_0
.Llora_done_0:
.LBB0_322:
	s_or_b64 exec, exec, s[2:3]
	s_barrier
	s_cmpk_lt_i32 s91, 0x300
	s_cselect_b64 s[0:1], -1, 0
	v_writelane_b32 v250, s0, 19
	s_cmpk_gt_i32 s91, 0x2ff
	v_mbcnt_lo_u32_b32 v152, -1, 0
	v_writelane_b32 v250, s1, 20
	s_cbranch_scc1 .LBB0_386
	s_add_u32 s2, s14, 0xd178400
	s_addc_u32 s3, s15, 0
	v_mbcnt_hi_u32_b32 v3, -1, v152
	s_add_u32 s9, s74, 0x4410000
	v_and_b32_e32 v0, 64, v3
	s_mov_b64 s[0:1], 0xd178400
	s_addc_u32 s34, s75, 0
	s_movk_i32 s35, 0x1ff
	s_mov_b32 s5, 0
	v_mov_b32_e32 v1, 0
	s_mov_b32 s72, 0x88888889
	s_movk_i32 s73, 0x1000
	s_movk_i32 s76, 0x4000
	s_movk_i32 s77, 0x1d00
	s_mov_b64 s[6:7], 0x1100
	v_xor_b32_e32 v88, 16, v3
	v_add_u32_e32 v89, 64, v0
	v_xor_b32_e32 v90, 32, v3
	s_mov_b32 s8, 0x3c800000
	s_mov_b32 s78, 0x800000
	s_add_i32 s79, 0, 0x11e00
	s_mov_b32 s80, 0x10000
	v_mov_b32_e32 v91, 0x4000
	v_mov_b32_e32 v2, 0x3727c5ac
	s_mov_b32 s81, s91
	s_branch .LBB0_326

.LBB0_920:
	s_or_b64 exec, exec, s[0:1]
	s_waitcnt lgkmcnt(0)
	v_mov_b32_e32 v0, v154
	s_barrier
	s_nop 0
	v_readfirstlane_b32 s0, v154
	v_and_b32_e32 v1, 63, v154
	v_lshlrev_b32_e32 v1, 4, v1
	s_nop 3
	s_lshl_b32 s1, s0, 4
	v_add_u32_e32 v1, s1, v1
	s_add_u32 s2, s14, 0x1310000
	s_addc_u32 s3, s15, 0
	s_mov_b32 m0, s1
	s_nop 0
	global_load_lds_dwordx4 v1, s[2:3]
	s_add_u32 s2, s2, 0x2000
	s_addc_u32 s3, s3, 0
	s_add_u32 s1, s1, 0x2000
	s_mov_b32 m0, s1
	s_nop 0
	global_load_lds_dwordx4 v1, s[2:3]
	s_add_u32 s2, s2, 0x2000
	s_addc_u32 s3, s3, 0
	s_add_u32 s1, s1, 0x2000
	s_mov_b32 m0, s1
	s_nop 0
	global_load_lds_dwordx4 v1, s[2:3]
	s_add_u32 s2, s2, 0x2000
	s_addc_u32 s3, s3, 0
	s_add_u32 s1, s1, 0x2000
	s_mov_b32 m0, s1
	s_nop 0
	global_load_lds_dwordx4 v1, s[2:3]
	s_add_u32 s2, s2, 0x2000
	s_addc_u32 s3, s3, 0
	s_add_u32 s1, s1, 0x2000
	s_mov_b32 m0, s1
	s_nop 0
	global_load_lds_dwordx4 v1, s[2:3]
	s_add_u32 s2, s2, 0x2000
	s_addc_u32 s3, s3, 0
	s_add_u32 s1, s1, 0x2000
	s_mov_b32 m0, s1
	s_nop 0
	global_load_lds_dwordx4 v1, s[2:3]
	s_add_u32 s2, s2, 0x2000
	s_addc_u32 s3, s3, 0
	s_add_u32 s1, s1, 0x2000
	s_mov_b32 m0, s1
	s_nop 0
	global_load_lds_dwordx4 v1, s[2:3]
	s_add_u32 s2, s2, 0x2000
	s_addc_u32 s3, s3, 0
	s_add_u32 s1, s1, 0x2000
	s_mov_b32 m0, s1
	s_nop 0
	global_load_lds_dwordx4 v1, s[2:3]
	s_add_u32 s2, s2, 0x12000
	s_addc_u32 s3, s3, 0
	s_add_u32 s1, s1, 0x2000
	s_mov_b32 m0, s1
	s_nop 0
	global_load_lds_dwordx4 v1, s[2:3]
	s_add_u32 s2, s2, 0x2000
	s_addc_u32 s3, s3, 0
	s_add_u32 s1, s1, 0x2000
	s_mov_b32 m0, s1
	s_nop 0
	global_load_lds_dwordx4 v1, s[2:3]
	s_add_u32 s2, s2, 0x2000
	s_addc_u32 s3, s3, 0
	s_add_u32 s1, s1, 0x2000
	s_mov_b32 m0, s1
	s_nop 0
	global_load_lds_dwordx4 v1, s[2:3]
	s_add_u32 s2, s2, 0x2000
	s_addc_u32 s3, s3, 0
	s_add_u32 s1, s1, 0x2000
	s_mov_b32 m0, s1
	s_nop 0
	global_load_lds_dwordx4 v1, s[2:3]
	s_add_u32 s2, s2, 0x2000
	s_addc_u32 s3, s3, 0
	s_add_u32 s1, s1, 0x2000
	s_mov_b32 m0, s1
	s_nop 0
	global_load_lds_dwordx4 v1, s[2:3]
	s_add_u32 s2, s2, 0x2000
	s_addc_u32 s3, s3, 0
	s_add_u32 s1, s1, 0x2000
	s_mov_b32 m0, s1
	s_nop 0
	global_load_lds_dwordx4 v1, s[2:3]
	s_add_u32 s2, s2, 0x2000
	s_addc_u32 s3, s3, 0
	s_add_u32 s1, s1, 0x2000
	s_mov_b32 m0, s1
	s_nop 0
	global_load_lds_dwordx4 v1, s[2:3]
	s_add_u32 s2, s2, 0x2000
	s_addc_u32 s3, s3, 0
	s_add_u32 s1, s1, 0x2000
	s_mov_b32 m0, s1
	s_nop 0
	global_load_lds_dwordx4 v1, s[2:3]
	v_lshlrev_b32_e32 v2, 2, v154
	global_load_dword v3, v2, s[46:47] offset:2048
	global_load_dword v4, v2, s[50:51] offset:2048
	global_load_dword v5, v2, s[54:55] offset:2048
	v_add_u32_e32 v8, 0x2a00, v2
	global_load_dword v6, v8, s[44:45]
	global_load_dword v7, v2, s[56:57] offset:2048
	v_add_u32_e32 v2, 0x21000, v2
	s_waitcnt vmcnt(0)
	ds_write_b32 v2, v3
	ds_write_b32 v2, v4 offset:2048
	ds_write_b32 v2, v5 offset:4096
	ds_write_b32 v2, v6 offset:6144
	ds_write_b32 v2, v7 offset:8192
	s_waitcnt lgkmcnt(0)
	s_barrier
	v_ashrrev_i32_e32 v0, 6, v0
	v_cmp_lt_i32_e32 vcc, 3, v0
	s_and_saveexec_b64 s[0:1], vcc
	s_xor_b64 s[2:3], exec, s[0:1]
	s_cbranch_execz .LBB0_929
	v_cmp_eq_u32_e32 vcc, -1, v0
	s_and_saveexec_b64 s[4:5], vcc
	s_cbranch_execz .LBB0_928
	s_lshl_b32 s0, s13, 2
	s_ashr_i32 s1, s91, 3
	s_add_i32 s0, s0, s1
	s_cmpk_gt_i32 s0, 0x41f
	s_cbranch_scc1 .LBB0_928
	v_mov_b32_e32 v38, v154
	s_nop 0
	v_and_b32_e32 v55, 15, v38
	v_lshl_or_b32 v34, s0, 4, v55
	s_movk_i32 s0, 0x3fff
	v_cmp_lt_i32_e32 vcc, s0, v34
	v_add_u32_e32 v1, -1, v34
	s_and_saveexec_b64 s[0:1], vcc
	s_xor_b64 s[0:1], exec, s[0:1]
	v_add_u32_e32 v2, 0xffffc000, v34
	v_and_b32_e32 v0, 3, v38
	v_lshrrev_b32_e32 v2, 2, v2
	v_add_u32_e32 v2, 0x4200, v2
	v_cmp_eq_u32_e32 vcc, 0, v0
	s_nop 1
	v_cndmask_b32_e32 v0, v1, v2, vcc
	s_andn2_saveexec_b64 s[0:1], s[0:1]
	v_and_b32_e32 v0, 0x7ff, v34
	v_cmp_ne_u32_e32 vcc, 0, v0
	s_nop 1
	v_cndmask_b32_e32 v0, -1, v1, vcc
	s_or_b64 exec, exec, s[0:1]
	v_cmp_lt_i32_e32 vcc, -1, v0
	s_movk_i32 s6, 0x1d00
	v_mov_b64_e32 v[2:3], s[22:23]
	v_cndmask_b32_e32 v0, 0, v0, vcc
	v_mad_i64_i32 v[36:37], s[0:1], v34, s6, v[2:3]
	v_mad_u64_u32 v[28:29], s[0:1], v0, s6, v[2:3]
	v_bfe_u32 v39, v38, 4, 2
	s_mov_b64 s[0:1], 0x1000
	s_mov_b64 s[6:7], 0x1080
	v_lshl_add_u64 v[8:9], v[36:37], 0, s[0:1]
	v_lshl_add_u64 v[10:11], v[36:37], 0, s[6:7]
	v_lshl_add_u64 v[12:13], v[28:29], 0, s[0:1]
	v_lshlrev_b32_e32 v52, 4, v39
	v_mov_b32_e32 v53, 0
	s_add_u32 s8, s44, 0x2200
	v_lshl_add_u64 v[14:15], v[28:29], 0, s[6:7]
	v_lshl_add_u64 v[0:1], v[8:9], 0, v[52:53]
	v_lshl_add_u64 v[2:3], v[10:11], 0, v[52:53]
	v_lshl_add_u64 v[16:17], v[12:13], 0, v[52:53]
	s_addc_u32 s9, s45, 0
	v_lshl_add_u64 v[18:19], v[14:15], 0, v[52:53]
	global_load_dwordx4 v[4:7], v[2:3], off
	s_nop 0
	global_load_dwordx4 v[0:3], v[0:1], off
	s_nop 0
	global_load_dwordx4 v[20:23], v[18:19], off
	global_load_dwordx4 v[24:27], v[16:17], off
	v_lshlrev_b32_e32 v16, 5, v39
	v_mov_b32_e32 v17, v53
	v_lshl_add_u64 v[16:17], s[8:9], 0, v[16:17]
	s_movk_i32 s10, 0x2000
	v_cndmask_b32_e64 v54, 0, 1.0, vcc
	v_add_co_u32_e32 v18, vcc, s10, v16
	s_mov_b64 s[6:7], 0x2000
	s_nop 0
	v_addc_co_u32_e32 v19, vcc, 0, v17, vcc
	global_load_dwordx4 v[40:43], v[18:19], off
	global_load_dwordx4 v[44:47], v[18:19], off offset:256
	v_lshl_add_u64 v[18:19], v[16:17], 0, s[6:7]
	global_load_dwordx4 v[48:51], v[18:19], off offset:16
	s_mov_b64 s[0:1], 0x2100
	v_lshl_add_u64 v[16:17], v[16:17], 0, s[0:1]
	global_load_dwordx4 v[56:59], v[16:17], off offset:16
	v_lshl_or_b32 v30, v39, 3, 32
	v_mov_b32_e32 v19, v53
	v_mov_b32_e32 v31, v53
	v_lshlrev_b32_e32 v18, 1, v30
	v_lshlrev_b32_e32 v30, 2, v30
	v_lshl_add_u64 v[8:9], v[8:9], 0, v[18:19]
	v_lshl_add_u64 v[10:11], v[10:11], 0, v[18:19]
	v_lshl_add_u64 v[64:65], s[8:9], 0, v[30:31]
	v_lshl_add_u64 v[30:31], v[12:13], 0, v[18:19]
	v_lshl_add_u64 v[16:17], v[14:15], 0, v[18:19]
	global_load_dwordx4 v[12:15], v[10:11], off
	s_nop 0
	global_load_dwordx4 v[8:11], v[8:9], off
	v_add_co_u32_e32 v66, vcc, s10, v64
	s_mov_b64 s[8:9], 0x1330000
	s_nop 0
	v_addc_co_u32_e32 v67, vcc, 0, v65, vcc
	global_load_dwordx4 v[16:19], v[16:17], off
	s_nop 0
	global_load_dwordx4 v[30:33], v[30:31], off
	s_nop 0
	global_load_dwordx4 v[60:63], v[66:67], off
	v_lshlrev_b32_e32 v84, 2, v39
	v_ashrrev_i32_e32 v35, 31, v34
	s_waitcnt vmcnt(12)
	v_cvt_f32_f16_e32 v68, v4
	v_cvt_f32_f16_sdwa v69, v4 dst_sel:DWORD dst_unused:UNUSED_PAD src0_sel:WORD_1
	s_waitcnt vmcnt(10)
	v_cvt_f32_f16_e32 v70, v20
	s_waitcnt vmcnt(9)
	v_fma_mix_f32 v4, v54, v24, -v0 op_sel_hi:[0,1,1]
	v_fma_mix_f32 v24, v54, v24, -v0 op_sel:[0,1,1] op_sel_hi:[0,1,1]
	v_cvt_f32_f16_sdwa v71, v20 dst_sel:DWORD dst_unused:UNUSED_PAD src0_sel:WORD_1
	v_fma_mix_f32 v20, v54, v25, -v1 op_sel_hi:[0,1,1]
	v_fma_mix_f32 v25, v54, v25, -v1 op_sel:[0,1,1] op_sel_hi:[0,1,1]
	s_waitcnt vmcnt(8)
	v_fma_mix_f32 v4, v40, v4, v0 op_sel_hi:[0,0,1]
	v_fma_mix_f32 v0, v24, v41, v0 op_sel:[0,0,1] op_sel_hi:[0,0,1]
	v_add_f32_e32 v4, v4, v4
	v_add_f32_e32 v0, v0, v0
	v_mul_f32_e32 v4, 0x3fb8aa3b, v4
	v_mul_f32_e32 v0, 0x3fb8aa3b, v0
	v_exp_f32_e32 v4, v4
	v_exp_f32_e32 v0, v0
	v_fma_mix_f32 v20, v20, v42, v1 op_sel_hi:[0,0,1]
	v_fma_mix_f32 v1, v25, v43, v1 op_sel:[0,0,1] op_sel_hi:[0,0,1]
	v_add_f32_e32 v1, v1, v1
	v_add_f32_e32 v20, v20, v20
	v_mul_f32_e32 v24, 0x3fb8aa3b, v1
	v_add_f32_e32 v1, 1.0, v4
	v_add_f32_e32 v4, 1.0, v0
	v_mul_f32_e32 v20, 0x3fb8aa3b, v20
	v_rcp_f32_e32 v0, v1
	v_rcp_f32_e32 v1, v4
	v_exp_f32_e32 v20, v20
	v_exp_f32_e32 v4, v24
	v_pk_fma_f32 v[40:41], v[54:55], v[70:71], v[68:69] op_sel_hi:[0,1,1] neg_lo:[0,0,1] neg_hi:[0,0,1]
	v_pk_fma_f32 v[0:1], v[0:1], 2.0, 1.0 op_sel_hi:[1,0,0] neg_lo:[1,0,0] neg_hi:[1,0,0]
	v_add_f32_e32 v20, 1.0, v20
	v_cvt_pk_f16_f32 v0, v0, v1
	v_add_f32_e32 v1, 1.0, v4
	v_rcp_f32_e32 v24, v20
	v_rcp_f32_e32 v25, v1
	v_cvt_f32_f16_e32 v20, v21
	v_cvt_f32_f16_sdwa v21, v21 dst_sel:DWORD dst_unused:UNUSED_PAD src0_sel:WORD_1
	s_waitcnt vmcnt(7)
	v_pk_fma_f32 v[40:41], v[44:45], v[40:41], v[68:69]
	v_pk_fma_f32 v[24:25], v[24:25], 2.0, 1.0 op_sel_hi:[1,0,0] neg_lo:[1,0,0] neg_hi:[1,0,0]
	v_cvt_pk_f16_f32 v4, v40, v41
	v_cvt_pk_f16_f32 v1, v24, v25
	v_cvt_f32_f16_e32 v24, v5
	v_cvt_f32_f16_sdwa v25, v5 dst_sel:DWORD dst_unused:UNUSED_PAD src0_sel:WORD_1
	v_fma_mix_f32 v5, v54, v26, -v2 op_sel_hi:[0,1,1]
	v_fma_mix_f32 v26, v54, v26, -v2 op_sel:[0,1,1] op_sel_hi:[0,1,1]
	s_waitcnt vmcnt(6)
	v_fma_mix_f32 v5, v5, v48, v2 op_sel_hi:[0,0,1]
	v_fma_mix_f32 v2, v26, v49, v2 op_sel:[0,0,1] op_sel_hi:[0,0,1]
	v_add_f32_e32 v5, v5, v5
	v_add_f32_e32 v2, v2, v2
	v_mul_f32_e32 v5, 0x3fb8aa3b, v5
	v_mul_f32_e32 v2, 0x3fb8aa3b, v2
	v_exp_f32_e32 v5, v5
	v_exp_f32_e32 v2, v2
	v_pk_fma_f32 v[20:21], v[54:55], v[20:21], v[24:25] op_sel_hi:[0,1,1] neg_lo:[0,0,1] neg_hi:[0,0,1]
	v_pk_fma_f32 v[20:21], v[20:21], v[46:47], v[24:25]
	v_add_f32_e32 v5, 1.0, v5
	v_add_f32_e32 v2, 1.0, v2
	v_rcp_f32_e32 v40, v5
	v_rcp_f32_e32 v41, v2
	v_cvt_pk_f16_f32 v5, v20, v21
	v_fma_mix_f32 v25, v54, v27, -v3 op_sel:[0,1,1] op_sel_hi:[0,1,1]
	v_cvt_f32_f16_e32 v24, v22
	v_pk_fma_f32 v[20:21], v[40:41], 2.0, 1.0 op_sel_hi:[1,0,0] neg_lo:[1,0,0] neg_hi:[1,0,0]
	global_load_dwordx4 v[40:43], v[66:67], off offset:256
	v_cvt_pk_f16_f32 v2, v20, v21
	v_cvt_f32_f16_e32 v20, v6
	v_cvt_f32_f16_sdwa v21, v6 dst_sel:DWORD dst_unused:UNUSED_PAD src0_sel:WORD_1
	v_fma_mix_f32 v6, v54, v27, -v3 op_sel_hi:[0,1,1]
	v_fma_mix_f32 v6, v6, v50, v3 op_sel_hi:[0,0,1]
	v_fma_mix_f32 v3, v25, v51, v3 op_sel:[0,0,1] op_sel_hi:[0,0,1]
	v_cvt_f32_f16_sdwa v25, v22 dst_sel:DWORD dst_unused:UNUSED_PAD src0_sel:WORD_1
	v_add_f32_e32 v6, v6, v6
	v_add_f32_e32 v3, v3, v3
	v_mul_f32_e32 v6, 0x3fb8aa3b, v6
	v_pk_fma_f32 v[24:25], v[54:55], v[24:25], v[20:21] op_sel_hi:[0,1,1] neg_lo:[0,0,1] neg_hi:[0,0,1]
	s_waitcnt vmcnt(6)
	v_pk_fma_f32 v[20:21], v[24:25], v[56:57], v[20:21]
	v_lshl_add_u64 v[24:25], v[64:65], 0, s[6:7]
	global_load_dwordx4 v[44:47], v[24:25], off offset:16
	v_mul_f32_e32 v3, 0x3fb8aa3b, v3
	v_exp_f32_e32 v6, v6
	v_exp_f32_e32 v3, v3
	s_waitcnt vmcnt(3)
	v_fma_mix_f32 v24, v54, v30, -v8 op_sel:[0,1,1] op_sel_hi:[0,1,1]
	v_cvt_f32_f16_e32 v22, v23
	v_add_f32_e32 v6, 1.0, v6
	v_add_f32_e32 v3, 1.0, v3
	v_rcp_f32_e32 v26, v6
	v_rcp_f32_e32 v27, v3
	v_cvt_pk_f16_f32 v6, v20, v21
	v_cvt_f32_f16_sdwa v23, v23 dst_sel:DWORD dst_unused:UNUSED_PAD src0_sel:WORD_1
	v_pk_fma_f32 v[20:21], v[26:27], 2.0, 1.0 op_sel_hi:[1,0,0] neg_lo:[1,0,0] neg_hi:[1,0,0]
	s_nop 0
	v_cvt_pk_f16_f32 v3, v20, v21
	v_cvt_f32_f16_e32 v20, v7
	v_cvt_f32_f16_sdwa v21, v7 dst_sel:DWORD dst_unused:UNUSED_PAD src0_sel:WORD_1
	v_fma_mix_f32 v7, v54, v30, -v8 op_sel_hi:[0,1,1]
	s_waitcnt vmcnt(2)
	v_fma_mix_f32 v7, v60, v7, v8 op_sel_hi:[0,0,1]
	v_add_f32_e32 v7, v7, v7
	v_fma_mix_f32 v8, v24, v61, v8 op_sel:[0,0,1] op_sel_hi:[0,0,1]
	v_mul_f32_e32 v7, 0x3fb8aa3b, v7
	v_add_f32_e32 v8, v8, v8
	v_exp_f32_e32 v7, v7
	v_mul_f32_e32 v8, 0x3fb8aa3b, v8
	v_exp_f32_e32 v8, v8
	v_pk_fma_f32 v[22:23], v[54:55], v[22:23], v[20:21] op_sel_hi:[0,1,1] neg_lo:[0,0,1] neg_hi:[0,0,1]
	v_add_f32_e32 v7, 1.0, v7
	v_rcp_f32_e32 v24, v7
	v_add_f32_e32 v7, 1.0, v8
	v_rcp_f32_e32 v25, v7
	v_pk_fma_f32 v[20:21], v[22:23], v[58:59], v[20:21]
	v_pk_fma_f32 v[22:23], v[24:25], 2.0, 1.0 op_sel_hi:[1,0,0] neg_lo:[1,0,0] neg_hi:[1,0,0]
	v_cvt_pk_f16_f32 v7, v20, v21
	v_lshl_add_u64 v[20:21], v[64:65], 0, s[0:1]
	v_cvt_pk_f16_f32 v8, v22, v23
	v_cvt_f32_f16_e32 v22, v12
	v_cvt_f32_f16_sdwa v23, v12 dst_sel:DWORD dst_unused:UNUSED_PAD src0_sel:WORD_1
	v_cvt_f32_f16_e32 v24, v16
	v_cvt_f32_f16_sdwa v25, v16 dst_sel:DWORD dst_unused:UNUSED_PAD src0_sel:WORD_1
	global_load_dwordx4 v[48:51], v[20:21], off offset:16
	v_fma_mix_f32 v12, v54, v31, -v9 op_sel_hi:[0,1,1]
	v_fma_mix_f32 v16, v54, v31, -v9 op_sel:[0,1,1] op_sel_hi:[0,1,1]
	v_lshl_add_u64 v[20:21], s[14:15], 0, v[52:53]
	s_mov_b64 s[0:1], 0x1310000
	v_fma_mix_f32 v12, v12, v62, v9 op_sel_hi:[0,0,1]
	v_fma_mix_f32 v9, v16, v63, v9 op_sel:[0,0,1] op_sel_hi:[0,0,1]
	v_lshl_add_u64 v[62:63], v[20:21], 0, s[0:1]
	s_add_u32 s0, s44, 0x2a00
	s_addc_u32 s1, s45, 0
	s_lshl_b32 s6, s91, 6
	s_and_b32 s7, s6, 0x1c0
	v_or_b32_e32 v16, s7, v55
	v_lshlrev_b32_e32 v52, 7, v16
	v_lshl_add_u64 v[26:27], v[62:63], 0, v[52:53]
	global_load_dwordx4 v[56:59], v[26:27], off
	global_load_dwordx4 v[78:81], v[26:27], off offset:64
	v_lshl_add_u64 v[64:65], v[20:21], 0, s[8:9]
	v_lshl_add_u64 v[20:21], v[64:65], 0, v[52:53]
	global_load_dwordx4 v[74:77], v[20:21], off
	global_load_dwordx4 v[86:89], v[20:21], off offset:64
	v_add_f32_e32 v12, v12, v12
	v_add_f32_e32 v9, v9, v9
	v_mul_f32_e32 v12, 0x3fb8aa3b, v12
	v_mul_f32_e32 v9, 0x3fb8aa3b, v9
	v_exp_f32_e32 v12, v12
	v_exp_f32_e32 v9, v9
	v_cvt_f32_f16_e32 v20, v13
	v_cvt_f32_f16_sdwa v21, v13 dst_sel:DWORD dst_unused:UNUSED_PAD src0_sel:WORD_1
	v_or_b32_e32 v13, s7, v84
	v_lshlrev_b32_e32 v52, 1, v13
	v_lshl_add_u64 v[70:71], v[36:37], 0, v[52:53]
	v_add_f32_e32 v12, 1.0, v12
	v_add_f32_e32 v9, 1.0, v9
	global_load_dwordx2 v[66:67], v[70:71], off offset:1024
	v_rcp_f32_e32 v30, v12
	v_rcp_f32_e32 v31, v9
	v_pk_fma_f32 v[24:25], v[54:55], v[24:25], v[22:23] op_sel_hi:[0,1,1] neg_lo:[0,0,1] neg_hi:[0,0,1]
	s_waitcnt vmcnt(7)
	v_pk_fma_f32 v[22:23], v[40:41], v[24:25], v[22:23]
	v_lshl_add_u64 v[72:73], v[28:29], 0, v[52:53]
	v_cvt_pk_f16_f32 v12, v22, v23
	v_pk_fma_f32 v[22:23], v[30:31], 2.0, 1.0 op_sel_hi:[1,0,0] neg_lo:[1,0,0] neg_hi:[1,0,0]
	v_lshlrev_b32_e32 v83, 2, v13
	v_cvt_pk_f16_f32 v9, v22, v23
	v_fma_mix_f32 v22, v54, v32, -v10 op_sel_hi:[0,1,1]
	s_waitcnt vmcnt(6)
	v_fma_mix_f32 v22, v22, v44, v10 op_sel_hi:[0,0,1]
	v_add_f32_e32 v22, v22, v22
	global_load_dwordx2 v[68:69], v[72:73], off offset:1024
	global_load_dwordx4 v[24:27], v83, s[50:51] offset:2048
	v_cvt_f32_f16_e32 v16, v17
	v_cvt_f32_f16_sdwa v17, v17 dst_sel:DWORD dst_unused:UNUSED_PAD src0_sel:WORD_1
	v_mul_f32_e32 v22, 0x3fb8aa3b, v22
	v_exp_f32_e32 v22, v22
	global_load_dwordx4 v[28:31], v83, s[0:1]
	v_pk_fma_f32 v[16:17], v[54:55], v[16:17], v[20:21] op_sel_hi:[0,1,1] neg_lo:[0,0,1] neg_hi:[0,0,1]
	v_fma_mix_f32 v23, v54, v32, -v10 op_sel:[0,1,1] op_sel_hi:[0,1,1]
	v_pk_fma_f32 v[16:17], v[16:17], v[42:43], v[20:21]
	v_add_f32_e32 v20, 1.0, v22
	v_fma_mix_f32 v10, v23, v45, v10 op_sel:[0,0,1] op_sel_hi:[0,0,1]
	v_rcp_f32_e32 v36, v20
	global_load_dwordx4 v[20:23], v83, s[46:47] offset:2048
	v_add_f32_e32 v10, v10, v10
	v_mul_f32_e32 v10, 0x3fb8aa3b, v10
	v_cvt_f32_f16_e32 v40, v14
	v_cvt_f32_f16_sdwa v41, v14 dst_sel:DWORD dst_unused:UNUSED_PAD src0_sel:WORD_1
	v_cvt_f32_f16_e32 v42, v18
	v_cvt_f32_f16_sdwa v43, v18 dst_sel:DWORD dst_unused:UNUSED_PAD src0_sel:WORD_1
	v_fma_mix_f32 v14, v54, v33, -v11 op_sel_hi:[0,1,1]
	v_fma_mix_f32 v18, v54, v33, -v11 op_sel:[0,1,1] op_sel_hi:[0,1,1]
	v_exp_f32_e32 v10, v10
	v_fma_mix_f32 v14, v14, v46, v11 op_sel_hi:[0,0,1]
	v_fma_mix_f32 v11, v18, v47, v11 op_sel:[0,0,1] op_sel_hi:[0,0,1]
	v_add_f32_e32 v14, v14, v14
	v_add_f32_e32 v11, v11, v11
	v_mul_f32_e32 v14, 0x3fb8aa3b, v14
	v_mul_f32_e32 v11, 0x3fb8aa3b, v11
	v_exp_f32_e32 v14, v14
	v_exp_f32_e32 v11, v11
	v_add_f32_e32 v10, 1.0, v10
	v_rcp_f32_e32 v37, v10
	v_add_f32_e32 v14, 1.0, v14
	v_add_f32_e32 v11, 1.0, v11
	v_rcp_f32_e32 v32, v14
	v_rcp_f32_e32 v33, v11
	v_cvt_pk_f16_f32 v13, v16, v17
	v_pk_fma_f32 v[16:17], v[36:37], 2.0, 1.0 op_sel_hi:[1,0,0] neg_lo:[1,0,0] neg_hi:[1,0,0]
	v_cvt_f32_f16_e32 v36, v15
	v_cvt_f32_f16_sdwa v37, v15 dst_sel:DWORD dst_unused:UNUSED_PAD src0_sel:WORD_1
	v_cvt_f32_f16_e32 v18, v19
	v_cvt_f32_f16_sdwa v19, v19 dst_sel:DWORD dst_unused:UNUSED_PAD src0_sel:WORD_1
	v_cvt_pk_f16_f32 v10, v16, v17
	v_pk_fma_f32 v[16:17], v[54:55], v[42:43], v[40:41] op_sel_hi:[0,1,1] neg_lo:[0,0,1] neg_hi:[0,0,1]
	s_waitcnt vmcnt(9)
	v_pk_fma_f32 v[16:17], v[16:17], v[48:49], v[40:41]
	s_or_b32 s6, s7, 16
	v_cvt_pk_f16_f32 v14, v16, v17
	v_pk_fma_f32 v[16:17], v[32:33], 2.0, 1.0 op_sel_hi:[1,0,0] neg_lo:[1,0,0] neg_hi:[1,0,0]
	v_or_b32_e32 v44, s6, v55
	v_cvt_pk_f16_f32 v11, v16, v17
	v_pk_fma_f32 v[16:17], v[54:55], v[18:19], v[36:37] op_sel_hi:[0,1,1] neg_lo:[0,0,1] neg_hi:[0,0,1]
	v_pk_fma_f32 v[16:17], v[16:17], v[50:51], v[36:37]
	v_readlane_b32 s8, v250, 21
	v_cvt_pk_f16_f32 v15, v16, v17
	v_and_b32_e32 v16, 16, v38
	s_waitcnt vmcnt(8)
	v_mfma_f32_16x16x32_f16 v[36:39], v[56:59], v[0:3], 0
	v_add_u32_e32 v17, 12, v84
	v_cmp_eq_u32_e32 vcc, 0, v16
	v_lshlrev_b32_e32 v52, 7, v44
	v_readlane_b32 s9, v250, 22
	v_cndmask_b32_e32 v82, v17, v84, vcc
	v_lshlrev_b64 v[16:17], 11, v[34:35]
	s_waitcnt vmcnt(7)
	v_mfma_f32_16x16x32_f16 v[36:39], v[78:81], v[8:11], v[36:39]
	v_lshl_add_u64 v[80:81], v[62:63], 0, v[52:53]
	v_lshl_add_u64 v[60:61], s[8:9], 0, v[16:17]
	v_lshl_add_u64 v[56:57], s[30:31], 0, v[16:17]
	s_waitcnt vmcnt(6)
	v_mfma_f32_16x16x32_f16 v[40:43], v[74:77], v[4:7], 0
	v_lshl_add_u64 v[58:59], s[14:15], 0, v[16:17]
	global_load_dwordx4 v[16:19], v83, s[54:55] offset:2048
	global_load_dwordx4 v[32:35], v83, s[56:57] offset:2048
	global_load_dwordx4 v[44:47], v[80:81], off
	v_lshl_add_u64 v[78:79], v[64:65], 0, v[52:53]
	s_waitcnt vmcnt(8)
	v_mfma_f32_16x16x32_f16 v[48:51], v[86:89], v[12:15], v[40:43]
	s_nop 2
	global_load_dwordx4 v[40:43], v[78:79], off
	global_load_dwordx2 v[74:75], v[70:71], off offset:1056
	global_load_dwordx2 v[76:77], v[70:71], off offset:1088
	s_nop 0
	global_load_dwordx2 v[70:71], v[70:71], off offset:1120
	s_waitcnt vmcnt(11)
	v_cvt_f32_f16_e32 v90, v66
	global_load_dwordx4 v[86:89], v[80:81], off offset:64
	v_cvt_f32_f16_sdwa v91, v66 dst_sel:DWORD dst_unused:UNUSED_PAD src0_sel:WORD_1
	v_cvt_f32_f16_e32 v92, v67
	v_cvt_f32_f16_sdwa v93, v67 dst_sel:DWORD dst_unused:UNUSED_PAD src0_sel:WORD_1
	global_load_dwordx2 v[102:103], v[72:73], off offset:1056
	global_load_dwordx2 v[114:115], v[72:73], off offset:1088
	global_load_dwordx2 v[66:67], v[72:73], off offset:1120
	s_waitcnt vmcnt(14)
	v_cvt_f32_f16_e32 v94, v69
	global_load_dwordx4 v[78:81], v[78:79], off offset:64
	v_cvt_f32_f16_sdwa v95, v69 dst_sel:DWORD dst_unused:UNUSED_PAD src0_sel:WORD_1
	s_waitcnt vmcnt(14)
	v_pk_add_f32 v[26:27], v[50:51], v[26:27]
	v_pk_add_f32 v[24:25], v[48:49], v[24:25]
	global_load_dwordx4 v[48:51], v83, s[46:47] offset:2112
	v_cvt_f32_f16_e32 v72, v68
	v_cvt_f32_f16_sdwa v73, v68 dst_sel:DWORD dst_unused:UNUSED_PAD src0_sel:WORD_1
	v_xor_b32_e32 v68, 0x80000000, v92
	v_xor_b32_e32 v69, 0x80000000, v93
	v_pk_fma_f32 v[68:69], v[54:55], v[94:95], v[68:69] op_sel_hi:[0,1,1]
	s_waitcnt vmcnt(14)
	v_pk_fma_f32 v[68:69], v[30:31], v[68:69], v[92:93]
	v_or_b32_e32 v30, s6, v84
	v_lshlrev_b32_e32 v30, 2, v30
	s_waitcnt vmcnt(13)
	v_pk_add_f32 v[20:21], v[36:37], v[20:21]
	v_pk_add_f32 v[22:23], v[38:39], v[22:23]
	global_load_dwordx4 v[36:39], v30, s[0:1]
	v_xor_b32_e32 v94, 0x80000000, v90
	v_xor_b32_e32 v95, 0x80000000, v91
	v_pk_fma_f32 v[72:73], v[54:55], v[72:73], v[94:95] op_sel_hi:[0,1,1]
	v_pk_fma_f32 v[28:29], v[28:29], v[72:73], v[90:91]
	global_load_dwordx4 v[90:93], v83, s[50:51] offset:2112
	v_mul_f32_e32 v24, 0xbfb8aa3b, v24
	v_mul_f32_e32 v25, 0xbfb8aa3b, v25
	v_mul_f32_e32 v20, 0xbfb8aa3b, v20
	v_mul_f32_e32 v21, 0xbfb8aa3b, v21
	v_exp_f32_e32 v24, v24
	v_exp_f32_e32 v25, v25
	v_mul_f32_e32 v26, 0xbfb8aa3b, v26
	v_mul_f32_e32 v27, 0xbfb8aa3b, v27
	v_exp_f32_e32 v20, v20
	v_exp_f32_e32 v21, v21
	v_mul_f32_e32 v22, 0xbfb8aa3b, v22
	v_mul_f32_e32 v23, 0xbfb8aa3b, v23
	v_exp_f32_e32 v26, v26
	v_exp_f32_e32 v27, v27
	v_exp_f32_e32 v22, v22
	v_exp_f32_e32 v23, v23
	v_add_f32_e32 v24, 1.0, v24
	v_add_f32_e32 v25, 1.0, v25
	v_add_f32_e32 v20, 1.0, v20
	v_add_f32_e32 v21, 1.0, v21
	v_rcp_f32_e32 v24, v24
	v_rcp_f32_e32 v25, v25
	v_add_f32_e32 v26, 1.0, v26
	v_add_f32_e32 v27, 1.0, v27
	v_rcp_f32_e32 v20, v20
	v_rcp_f32_e32 v21, v21
	v_add_f32_e32 v22, 1.0, v22
	v_add_f32_e32 v23, 1.0, v23
	v_rcp_f32_e32 v26, v26
	v_rcp_f32_e32 v27, v27
	v_rcp_f32_e32 v22, v22
	v_rcp_f32_e32 v23, v23
	s_mov_b32 s6, 0x3f1b4598
	v_pk_add_f32 v[30:31], v[24:25], -1.0 op_sel_hi:[1,0]
	v_pk_mul_f32 v[72:73], v[20:21], s[6:7] op_sel_hi:[1,0]
	v_pk_add_f32 v[20:21], v[26:27], -1.0 op_sel_hi:[1,0]
	v_pk_mul_f32 v[22:23], v[22:23], s[6:7] op_sel_hi:[1,0]
	s_or_b32 s8, s7, 32
	s_waitcnt vmcnt(11)
	v_mfma_f32_16x16x32_f16 v[98:101], v[40:43], v[4:7], 0
	v_fma_f32 v30, v32, v30, 1.0
	v_fma_f32 v31, v33, v31, 1.0
	v_pk_fma_f32 v[20:21], v[34:35], v[20:21], 1.0 op_sel_hi:[1,1,0]
	v_pk_mul_f32 v[34:35], v[30:31], v[28:29]
	v_pk_mul_f32 v[30:31], v[16:17], v[28:29]
	v_pk_mul_f32 v[28:29], v[18:19], v[68:69]
	v_pk_mul_f32 v[32:33], v[20:21], v[68:69]
	v_cvt_pk_f16_f32 v21, v22, v23
	v_pk_mul_f32 v[18:19], v[28:29], v[28:29]
	v_pk_mul_f32 v[22:23], v[30:31], v[30:31]
	v_cvt_pk_f16_f32 v17, v32, v33
	v_pk_mov_b32 v[68:69], v[22:23], v[18:19] op_sel:[1,0]
	v_mov_b32_e32 v23, v19
	v_cvt_pk_f16_f32 v16, v34, v35
	v_mfma_f32_16x16x32_f16 v[32:35], v[44:47], v[0:3], 0
	v_add_f32_e64 v18, v68, v22
	v_add_f32_e64 v19, v69, v23
	global_load_dwordx4 v[44:47], v83, s[54:55] offset:2112
	global_load_dwordx4 v[94:97], v83, s[56:57] offset:2112
	v_pk_add_f32 v[40:41], v[18:19], v[18:19] op_sel:[0,1] op_sel_hi:[1,0]
	v_or_b32_e32 v18, s8, v55
	v_lshlrev_b32_e32 v52, 7, v18
	v_lshl_add_u64 v[18:19], v[62:63], 0, v[52:53]
	s_waitcnt vmcnt(9)
	v_mfma_f32_16x16x32_f16 v[32:35], v[86:89], v[8:11], v[32:35]
	global_load_dwordx4 v[86:89], v[18:19], off
	v_lshl_add_u64 v[42:43], v[64:65], 0, v[52:53]
	v_cvt_pk_f16_f32 v20, v72, v73
	s_waitcnt vmcnt(6)
	v_mfma_f32_16x16x32_f16 v[78:81], v[78:81], v[12:15], v[98:101]
	v_cvt_f32_f16_e32 v22, v74
	v_cvt_f32_f16_sdwa v23, v74 dst_sel:DWORD dst_unused:UNUSED_PAD src0_sel:WORD_1
	v_cvt_f32_f16_e32 v68, v75
	global_load_dwordx4 v[98:101], v[42:43], off
	v_cvt_f32_f16_sdwa v69, v75 dst_sel:DWORD dst_unused:UNUSED_PAD src0_sel:WORD_1
	global_load_dwordx4 v[72:75], v[18:19], off offset:64
	v_cvt_f32_f16_e32 v106, v102
	v_cvt_f32_f16_sdwa v107, v102 dst_sel:DWORD dst_unused:UNUSED_PAD src0_sel:WORD_1
	v_cvt_f32_f16_e32 v18, v103
	v_cvt_f32_f16_sdwa v19, v103 dst_sel:DWORD dst_unused:UNUSED_PAD src0_sel:WORD_1
	global_load_dwordx4 v[102:105], v[42:43], off offset:64
	s_waitcnt vmcnt(8)
	v_pk_add_f32 v[32:33], v[32:33], v[48:49]
	v_xor_b32_e32 v42, 0x80000000, v68
	v_mul_f32_e32 v32, 0xbfb8aa3b, v32
	v_exp_f32_e32 v32, v32
	v_xor_b32_e32 v43, 0x80000000, v69
	v_pk_fma_f32 v[18:19], v[54:55], v[18:19], v[42:43] op_sel_hi:[0,1,1]
	v_xor_b32_e32 v42, 0x80000000, v22
	v_xor_b32_e32 v43, 0x80000000, v23
	v_pk_fma_f32 v[42:43], v[54:55], v[106:107], v[42:43] op_sel_hi:[0,1,1]
	v_pk_add_f32 v[34:35], v[34:35], v[50:51]
	v_add_f32_e32 v32, 1.0, v32
	s_waitcnt vmcnt(7)
	v_pk_fma_f32 v[22:23], v[36:37], v[42:43], v[22:23]
	v_rcp_f32_e32 v42, v32
	v_mul_f32_e32 v32, 0xbfb8aa3b, v33
	v_mul_f32_e32 v33, 0xbfb8aa3b, v34
	v_or_b32_e32 v34, s8, v84
	v_lshlrev_b32_e32 v34, 2, v34
	global_load_dwordx4 v[48:51], v34, s[0:1]
	v_pk_fma_f32 v[18:19], v[38:39], v[18:19], v[68:69]
	s_waitcnt vmcnt(7)
	v_pk_add_f32 v[36:37], v[80:81], v[92:93]
	v_pk_add_f32 v[38:39], v[78:79], v[90:91]
	global_load_dwordx4 v[78:81], v83, s[46:47] offset:2176
	global_load_dwordx4 v[90:93], v83, s[50:51] offset:2176
	v_exp_f32_e32 v32, v32
	v_exp_f32_e32 v33, v33
	v_mul_f32_e32 v34, 0xbfb8aa3b, v38
	v_exp_f32_e32 v34, v34
	v_add_f32_e32 v32, 1.0, v32
	v_rcp_f32_e32 v43, v32
	v_add_f32_e32 v32, 1.0, v33
	v_mul_f32_e32 v33, 0xbfb8aa3b, v35
	v_exp_f32_e32 v33, v33
	v_rcp_f32_e32 v68, v32
	v_mul_f32_e32 v35, 0xbfb8aa3b, v37
	v_exp_f32_e32 v35, v35
	v_add_f32_e32 v32, 1.0, v33
	v_rcp_f32_e32 v69, v32
	v_add_f32_e32 v32, 1.0, v34
	v_mul_f32_e32 v34, 0xbfb8aa3b, v36
	v_mul_f32_e32 v33, 0xbfb8aa3b, v39
	v_exp_f32_e32 v34, v34
	v_exp_f32_e32 v33, v33
	v_add_f32_e32 v35, 1.0, v35
	v_rcp_f32_e32 v35, v35
	v_add_f32_e32 v34, 1.0, v34
	v_add_f32_e32 v33, 1.0, v33
	v_rcp_f32_e32 v34, v34
	v_rcp_f32_e32 v32, v32
	v_rcp_f32_e32 v33, v33
	s_or_b32 s8, s7, 48
	v_pk_add_f32 v[36:37], v[34:35], -1.0 op_sel_hi:[1,0]
	v_pk_mul_f32 v[68:69], v[68:69], s[6:7] op_sel_hi:[1,0]
	v_pk_add_f32 v[38:39], v[32:33], -1.0 op_sel_hi:[1,0]
	v_pk_mul_f32 v[42:43], v[42:43], s[6:7] op_sel_hi:[1,0]
	v_or_b32_e32 v41, s8, v84
	v_lshlrev_b32_e32 v41, 2, v41
	s_waitcnt vmcnt(7)
	v_pk_fma_f32 v[36:37], v[96:97], v[36:37], 1.0 op_sel_hi:[1,1,0]
	v_pk_fma_f32 v[38:39], v[94:95], v[38:39], 1.0 op_sel_hi:[1,1,0]
	v_pk_mul_f32 v[94:95], v[36:37], v[18:19]
	v_pk_mul_f32 v[36:37], v[46:47], v[18:19]
	v_or_b32_e32 v18, s8, v55
	v_lshlrev_b32_e32 v52, 7, v18
	v_pk_mul_f32 v[116:117], v[38:39], v[22:23]
	v_pk_mul_f32 v[38:39], v[44:45], v[22:23]
	v_cvt_pk_f16_f32 v23, v68, v69
	v_lshl_add_u64 v[68:69], v[64:65], 0, v[52:53]
	v_cvt_pk_f16_f32 v22, v42, v43
	v_cvt_pk_f16_f32 v19, v94, v95
	global_load_dwordx4 v[94:97], v83, s[54:55] offset:2176
	global_load_dwordx4 v[106:109], v83, s[56:57] offset:2176
	v_lshl_add_u64 v[46:47], v[62:63], 0, v[52:53]
	s_waitcnt vmcnt(8)
	v_mfma_f32_16x16x32_f16 v[42:45], v[86:89], v[0:3], 0
	global_load_dwordx4 v[62:65], v[68:69], off
	v_cvt_pk_f16_f32 v18, v116, v117
	v_pk_mul_f32 v[116:117], v[36:37], v[36:37]
	v_pk_mul_f32 v[118:119], v[38:39], v[38:39]
	s_waitcnt vmcnt(8)
	v_mfma_f32_16x16x32_f16 v[86:89], v[98:101], v[4:7], 0
	global_load_dwordx4 v[110:113], v[46:47], off
	global_load_dwordx4 v[98:101], v[46:47], off offset:64
	v_pk_mov_b32 v[46:47], v[118:119], v[116:117] op_sel:[1,0]
	v_mov_b32_e32 v119, v117
	s_waitcnt vmcnt(9)
	v_mfma_f32_16x16x32_f16 v[42:45], v[72:75], v[8:11], v[42:45]
	global_load_dwordx4 v[72:75], v[68:69], off offset:64
	v_pk_add_f32 v[46:47], v[46:47], v[118:119]
	v_cvt_f32_f16_e32 v116, v114
	v_pk_add_f32 v[68:69], v[46:47], v[46:47] op_sel:[0,1] op_sel_hi:[1,0]
	v_cvt_f32_f16_e32 v46, v76
	v_cvt_f32_f16_sdwa v47, v76 dst_sel:DWORD dst_unused:UNUSED_PAD src0_sel:WORD_1
	v_cvt_f32_f16_e32 v76, v77
	v_cvt_f32_f16_sdwa v77, v77 dst_sel:DWORD dst_unused:UNUSED_PAD src0_sel:WORD_1
	s_waitcnt vmcnt(9)
	v_mfma_f32_16x16x32_f16 v[86:89], v[102:105], v[12:15], v[86:89]
	v_cvt_f32_f16_e32 v102, v115
	v_cvt_f32_f16_sdwa v103, v115 dst_sel:DWORD dst_unused:UNUSED_PAD src0_sel:WORD_1
	v_cvt_f32_f16_sdwa v117, v114 dst_sel:DWORD dst_unused:UNUSED_PAD src0_sel:WORD_1
	v_xor_b32_e32 v104, 0x80000000, v76
	v_xor_b32_e32 v105, 0x80000000, v77
	v_xor_b32_e32 v114, 0x80000000, v46
	v_xor_b32_e32 v115, 0x80000000, v47
	v_pk_fma_f32 v[118:119], v[54:55], v[102:103], v[104:105] op_sel_hi:[0,1,1]
	v_pk_fma_f32 v[84:85], v[54:55], v[116:117], v[114:115] op_sel_hi:[0,1,1]
	global_load_dwordx4 v[114:117], v83, s[46:47] offset:2240
	s_waitcnt vmcnt(9)
	v_pk_fma_f32 v[46:47], v[48:49], v[84:85], v[46:47]
	v_pk_fma_f32 v[118:119], v[50:51], v[118:119], v[76:77]
	global_load_dwordx4 v[48:51], v83, s[50:51] offset:2240
	s_waitcnt vmcnt(9)
	v_pk_add_f32 v[42:43], v[42:43], v[78:79]
	global_load_dwordx4 v[102:105], v41, s[0:1]
	v_mul_f32_e32 v41, 0xbfb8aa3b, v42
	v_exp_f32_e32 v41, v41
	v_pk_add_f32 v[44:45], v[44:45], v[80:81]
	v_mul_f32_e32 v42, 0xbfb8aa3b, v43
	v_exp_f32_e32 v42, v42
	v_mul_f32_e32 v43, 0xbfb8aa3b, v44
	v_exp_f32_e32 v43, v43
	v_add_f32_e32 v41, 1.0, v41
	s_waitcnt vmcnt(9)
	v_pk_add_f32 v[78:79], v[86:87], v[90:91]
	v_rcp_f32_e32 v80, v41
	v_add_f32_e32 v41, 1.0, v42
	v_mul_f32_e32 v42, 0xbfb8aa3b, v45
	v_rcp_f32_e32 v81, v41
	v_add_f32_e32 v41, 1.0, v43
	v_exp_f32_e32 v42, v42
	v_mul_f32_e32 v43, 0xbfb8aa3b, v78
	v_exp_f32_e32 v43, v43
	v_pk_add_f32 v[76:77], v[88:89], v[92:93]
	v_rcp_f32_e32 v88, v41
	v_add_f32_e32 v41, 1.0, v42
	v_rcp_f32_e32 v89, v41
	v_add_f32_e32 v41, 1.0, v43
	v_rcp_f32_e32 v42, v41
	v_mul_f32_e32 v41, 0xbfb8aa3b, v79
	v_mul_f32_e32 v43, 0xbfb8aa3b, v76
	v_mul_f32_e32 v44, 0xbfb8aa3b, v77
	global_load_dwordx4 v[76:79], v83, s[54:55] offset:2240
	global_load_dwordx4 v[84:87], v83, s[56:57] offset:2240
	v_exp_f32_e32 v43, v43
	v_exp_f32_e32 v41, v41
	v_exp_f32_e32 v45, v44
	s_waitcnt vmcnt(8)
	v_mfma_f32_16x16x32_f16 v[4:7], v[62:65], v[4:7], 0
	v_add_f32_e32 v43, 1.0, v43
	v_add_f32_e32 v41, 1.0, v41
	v_rcp_f32_e32 v44, v43
	v_add_f32_e32 v43, 1.0, v45
	v_rcp_f32_e32 v45, v43
	v_rcp_f32_e32 v43, v41
	s_waitcnt vmcnt(5)
	v_mfma_f32_16x16x32_f16 v[4:7], v[72:75], v[12:15], v[4:7]
	v_mul_f32_e64 v92, v88, s6
	v_mul_f32_e64 v93, v89, s6
	v_pk_add_f32 v[88:89], v[44:45], -1.0 op_sel_hi:[1,0]
	v_pk_add_f32 v[90:91], v[42:43], -1.0 op_sel_hi:[1,0]
	v_pk_fma_f32 v[88:89], v[108:109], v[88:89], 1.0 op_sel_hi:[1,1,0]
	v_pk_fma_f32 v[90:91], v[106:107], v[90:91], 1.0 op_sel_hi:[1,1,0]
	v_pk_mul_f32 v[106:107], v[88:89], v[118:119]
	v_pk_mul_f32 v[108:109], v[90:91], v[46:47]
	v_mfma_f32_16x16x32_f16 v[88:91], v[110:113], v[0:3], 0
	v_mul_f32_e64 v0, v96, v118
	v_mul_f32_e64 v1, v97, v119
	v_cvt_f32_f16_e32 v14, v71
	v_cvt_f32_f16_sdwa v15, v71 dst_sel:DWORD dst_unused:UNUSED_PAD src0_sel:WORD_1
	v_mfma_f32_16x16x32_f16 v[8:11], v[98:101], v[8:11], v[88:91]
	v_mul_f32_e64 v64, v0, v0
	v_mul_f32_e64 v65, v1, v1
	v_cvt_f32_f16_e32 v12, v70
	v_cvt_f32_f16_sdwa v13, v70 dst_sel:DWORD dst_unused:UNUSED_PAD src0_sel:WORD_1
	v_cvt_f32_f16_e32 v70, v67
	s_waitcnt vmcnt(3)
	v_pk_add_f32 v[4:5], v[4:5], v[48:49]
	v_pk_add_f32 v[6:7], v[6:7], v[50:51]
	v_mul_f32_e32 v4, 0xbfb8aa3b, v4
	v_exp_f32_e32 v4, v4
	v_pk_add_f32 v[8:9], v[8:9], v[114:115]
	v_pk_add_f32 v[10:11], v[10:11], v[116:117]
	v_mul_f32_e32 v8, 0xbfb8aa3b, v8
	v_add_f32_e32 v4, 1.0, v4
	v_rcp_f32_e32 v48, v4
	v_mul_f32_e32 v4, 0xbfb8aa3b, v5
	v_mul_f32_e32 v5, 0xbfb8aa3b, v6
	v_mul_f32_e32 v9, 0xbfb8aa3b, v9
	v_mul_f32_e32 v10, 0xbfb8aa3b, v10
	v_mul_f32_e32 v11, 0xbfb8aa3b, v11
	v_exp_f32_e32 v5, v5
	v_mul_f32_e32 v6, 0xbfb8aa3b, v7
	v_exp_f32_e32 v8, v8
	v_exp_f32_e32 v9, v9
	v_exp_f32_e32 v10, v10
	v_exp_f32_e32 v11, v11
	v_exp_f32_e32 v4, v4
	v_exp_f32_e32 v6, v6
	v_add_f32_e32 v5, 1.0, v5
	v_cvt_f32_f16_sdwa v71, v67 dst_sel:DWORD dst_unused:UNUSED_PAD src0_sel:WORD_1
	v_add_f32_e32 v8, 1.0, v8
	v_add_f32_e32 v9, 1.0, v9
	v_add_f32_e32 v10, 1.0, v10
	v_add_f32_e32 v11, 1.0, v11
	v_add_f32_e32 v4, 1.0, v4
	v_rcp_f32_e32 v50, v5
	v_add_f32_e32 v5, 1.0, v6
	v_add_f32_e32 v88, v64, v65
	v_cvt_f32_f16_e32 v64, v66
	v_cvt_f32_f16_sdwa v65, v66 dst_sel:DWORD dst_unused:UNUSED_PAD src0_sel:WORD_1
	v_rcp_f32_e32 v8, v8
	v_rcp_f32_e32 v9, v9
	v_rcp_f32_e32 v10, v10
	v_rcp_f32_e32 v11, v11
	v_rcp_f32_e32 v51, v5
	v_rcp_f32_e32 v49, v4
	v_xor_b32_e32 v66, 0x80000000, v14
	v_xor_b32_e32 v67, 0x80000000, v15
	v_pk_fma_f32 v[66:67], v[54:55], v[70:71], v[66:67] op_sel_hi:[0,1,1]
	v_xor_b32_e32 v70, 0x80000000, v12
	v_xor_b32_e32 v71, 0x80000000, v13
	v_pk_fma_f32 v[54:55], v[54:55], v[64:65], v[70:71] op_sel_hi:[0,1,1]
	v_pk_mul_f32 v[4:5], v[10:11], s[6:7] op_sel_hi:[1,0]
	v_pk_mul_f32 v[6:7], v[8:9], s[6:7] op_sel_hi:[1,0]
	v_pk_add_f32 v[8:9], v[50:51], -1.0 op_sel_hi:[1,0]
	v_pk_add_f32 v[10:11], v[48:49], -1.0 op_sel_hi:[1,0]
	s_waitcnt vmcnt(2)
	v_pk_fma_f32 v[12:13], v[102:103], v[54:55], v[12:13]
	v_pk_fma_f32 v[14:15], v[104:105], v[66:67], v[14:15]
	s_waitcnt vmcnt(0)
	v_pk_fma_f32 v[8:9], v[86:87], v[8:9], 1.0 op_sel_hi:[1,1,0]
	v_pk_fma_f32 v[10:11], v[84:85], v[10:11], 1.0 op_sel_hi:[1,1,0]
	v_pk_mul_f32 v[80:81], v[80:81], s[6:7] op_sel_hi:[1,0]
	v_pk_mul_f32 v[46:47], v[94:95], v[46:47]
	v_pk_mul_f32 v[8:9], v[8:9], v[14:15]
	v_pk_mul_f32 v[10:11], v[10:11], v[12:13]
	v_pk_mul_f32 v[12:13], v[76:77], v[12:13]
	v_pk_mul_f32 v[54:55], v[78:79], v[14:15]
	v_cvt_pk_f16_f32 v2, v80, v81
	v_pk_mul_f32 v[80:81], v[46:47], v[46:47]
	v_cvt_pk_f16_f32 v5, v4, v5
	v_cvt_pk_f16_f32 v4, v6, v7
	v_cvt_pk_f16_f32 v65, v8, v9
	v_pk_mul_f32 v[6:7], v[54:55], v[54:55]
	v_pk_mul_f32 v[8:9], v[12:13], v[12:13]
	v_add_f32_e32 v80, v80, v81
	v_mov_b32_e32 v41, v8
	v_mov_b32_e32 v69, v9
	v_mov_b32_e32 v81, v6
	v_mov_b32_e32 v89, v7
	v_pk_add_f32 v[8:9], v[40:41], v[68:69]
	v_pk_add_f32 v[6:7], v[80:81], v[88:89]
	v_cvt_pk_f16_f32 v3, v92, v93
	v_pk_add_f32 v[6:7], v[8:9], v[6:7]
	v_permlane16_swap_b32_e32 v20, v22
	v_add_f32_e32 v8, v6, v7
	v_or_b32_e32 v6, s7, v82
	v_lshlrev_b32_e32 v52, 1, v6
	v_permlane16_swap_b32_e32 v21, v23
	v_lshl_add_u64 v[6:7], v[60:61], 0, v[52:53]
	global_store_dwordx4 v[6:7], v[20:23], off sc1
	s_nop 1
	v_permlane16_swap_b32_e32 v2, v4
	v_permlane16_swap_b32_e32 v3, v5
	v_lshl_add_u64 v[6:7], v[6:7], 0, 64
	global_store_dwordx4 v[6:7], v[2:5], off sc1
	s_nop 1
	v_mbcnt_hi_u32_b32 v2, -1, v152
	v_and_b32_e32 v4, 64, v2
	v_xor_b32_e32 v3, 16, v2
	v_add_u32_e32 v4, 64, v4
	v_cmp_lt_i32_e32 vcc, v3, v4
	v_lshl_add_u64 v[20:21], v[58:59], 0, v[52:53]
	s_mov_b64 s[0:1], 0xb078400
	v_cndmask_b32_e32 v3, v2, v3, vcc
	v_lshlrev_b32_e32 v3, 2, v3
	ds_bpermute_b32 v3, v3, v8
	v_permlane16_swap_b32_e32 v16, v18
	v_permlane16_swap_b32_e32 v17, v19
	s_waitcnt lgkmcnt(0)
	v_add_f32_e32 v5, v8, v3
	v_xor_b32_e32 v3, 32, v2
	v_cmp_lt_i32_e32 vcc, v3, v4
	v_cvt_pk_f16_f32 v63, v106, v107
	v_cvt_pk_f16_f32 v62, v108, v109
	v_cndmask_b32_e32 v2, v2, v3, vcc
	v_lshlrev_b32_e32 v2, 2, v2
	ds_bpermute_b32 v4, v2, v5
	v_lshl_add_u64 v[2:3], v[20:21], 0, s[0:1]
	global_store_dwordx4 v[2:3], v[16:19], off sc1
	s_nop 1
	s_mov_b32 s0, 0xf800000
	v_cvt_pk_f16_f32 v64, v10, v11
	s_waitcnt lgkmcnt(0)
	v_add_f32_e32 v2, v5, v4
	v_mul_f32_e32 v3, 0x4f800000, v2
	v_cmp_gt_f32_e32 vcc, s0, v2
	v_permlane16_swap_b32_e32 v62, v64
	s_nop 0
	v_cndmask_b32_e32 v2, v2, v3, vcc
	v_sqrt_f32_e32 v3, v2
	v_permlane16_swap_b32_e32 v63, v65
	v_add_u32_e32 v4, -1, v3
	v_fma_f32 v5, -v4, v3, v2
	v_cmp_ge_f32_e64 s[0:1], 0, v5
	v_add_u32_e32 v5, 1, v3
	s_nop 0
	v_cndmask_b32_e64 v4, v3, v4, s[0:1]
	v_fma_f32 v3, -v5, v3, v2
	v_cmp_lt_f32_e64 s[0:1], 0, v3
	s_nop 1
	v_cndmask_b32_e64 v3, v4, v5, s[0:1]
	v_mul_f32_e32 v4, 0x37800000, v3
	v_cndmask_b32_e32 v3, v3, v4, vcc
	v_mov_b32_e32 v4, 0x260
	v_cmp_class_f32_e32 vcc, v2, v4
	s_nop 1
	v_cndmask_b32_e32 v2, v3, v2, vcc
	v_max_f32_e32 v4, 0x2b8cbccc, v2
	v_div_scale_f32 v5, s[0:1], v4, v4, 1.0
	v_rcp_f32_e32 v6, v5
	s_mov_b64 s[0:1], 0xb078440
	v_lshl_add_u64 v[2:3], v[20:21], 0, s[0:1]
	global_store_dwordx4 v[2:3], v[62:65], off sc1
	s_nop 1
	v_fma_f32 v2, -v5, v6, 1.0
	v_fmac_f32_e32 v6, v2, v6
	v_div_scale_f32 v2, vcc, 1.0, v4, 1.0
	v_mul_f32_e32 v3, v2, v6
	v_fma_f32 v7, -v5, v3, v2
	v_fmac_f32_e32 v3, v7, v6
	v_fma_f32 v2, -v5, v3, v2
	v_div_fmas_f32 v2, v2, v6, v3
	v_div_fixup_f32 v16, v2, v4, 1.0
	v_pk_mul_f32 v[4:5], v[30:31], v[16:17] op_sel_hi:[1,0]
	v_pk_mul_f32 v[6:7], v[28:29], v[16:17] op_sel_hi:[1,0]
	v_pk_mul_f32 v[2:3], v[24:25], v[4:5]
	v_pk_mul_f32 v[8:9], v[26:27], v[6:7]
	v_cvt_pk_f16_f32 v2, v2, v3
	v_cvt_pk_f16_f32 v3, v8, v9
	v_pk_mul_f32 v[10:11], v[38:39], v[16:17] op_sel_hi:[1,0]
	v_pk_mul_f32 v[8:9], v[36:37], v[16:17] op_sel_hi:[1,0]
	v_cvt_pk_f16_f32 v7, v6, v7
	v_cvt_pk_f16_f32 v6, v4, v5
	v_pk_mul_f32 v[4:5], v[32:33], v[10:11]
	v_pk_mul_f32 v[14:15], v[34:35], v[8:9]
	v_pk_mul_f32 v[18:19], v[46:47], v[16:17] op_sel_hi:[1,0]
	v_pk_mul_f32 v[0:1], v[0:1], v[16:17] op_sel_hi:[1,0]
	v_cvt_pk_f16_f32 v4, v4, v5
	v_cvt_pk_f16_f32 v5, v14, v15
	v_cvt_pk_f16_f32 v9, v8, v9
	v_cvt_pk_f16_f32 v8, v10, v11
	v_pk_mul_f32 v[10:11], v[42:43], v[18:19]
	v_pk_mul_f32 v[14:15], v[44:45], v[0:1]
	v_cvt_pk_f16_f32 v10, v10, v11
	v_cvt_pk_f16_f32 v11, v14, v15
	v_cvt_pk_f16_f32 v15, v0, v1
	v_pk_mul_f32 v[0:1], v[12:13], v[16:17] op_sel_hi:[1,0]
	v_pk_mul_f32 v[16:17], v[54:55], v[16:17] op_sel_hi:[1,0]
	v_cvt_pk_f16_f32 v14, v18, v19
	v_pk_mul_f32 v[12:13], v[48:49], v[0:1]
	v_pk_mul_f32 v[18:19], v[50:51], v[16:17]
	v_cvt_pk_f16_f32 v17, v16, v17
	v_cvt_pk_f16_f32 v16, v0, v1
	v_permlane16_swap_b32_e32 v6, v8
	v_permlane16_swap_b32_e32 v7, v9
	v_lshl_add_u64 v[0:1], v[56:57], 0, v[52:53]
	global_store_dwordx4 v[0:1], v[6:9], off sc1
	s_nop 1
	v_permlane16_swap_b32_e32 v14, v16
	v_permlane16_swap_b32_e32 v15, v17
	v_lshl_add_u64 v[0:1], v[0:1], 0, 64
	global_store_dwordx4 v[0:1], v[14:17], off sc1
	s_nop 1
	s_mov_b64 s[0:1], 0x1670400
	v_cvt_pk_f16_f32 v12, v12, v13
	v_cvt_pk_f16_f32 v13, v18, v19
	v_permlane16_swap_b32_e32 v2, v4
	v_permlane16_swap_b32_e32 v3, v5
	v_lshl_add_u64 v[0:1], v[20:21], 0, s[0:1]
	global_store_dwordx4 v[0:1], v[2:5], off sc1
	s_nop 1
	s_mov_b64 s[0:1], 0x1670440
	v_permlane16_swap_b32_e32 v10, v12
	v_permlane16_swap_b32_e32 v11, v13
	v_lshl_add_u64 v[0:1], v[20:21], 0, s[0:1]
	global_store_dwordx4 v[0:1], v[10:13], off sc1
	s_nop 1

.Llora_pass_1:
	s_movk_i32 s0, 0x420
	v_cmp_gt_i32_e32 vcc, s0, v0
	s_and_saveexec_b64 s[4:5], vcc
	s_cbranch_execz .LBB0_937
	v_mov_b32_e32 v30, v154
	v_lshlrev_b32_e32 v0, 4, v0
	s_movk_i32 s0, 0x3fff
	v_and_or_b32 v24, v30, 15, v0
	v_cmp_lt_i32_e32 vcc, s0, v24
	v_add_u32_e32 v1, -1, v24
	s_and_saveexec_b64 s[0:1], vcc
	s_xor_b64 s[0:1], exec, s[0:1]
	v_add_u32_e32 v2, 0xffffc000, v24
	v_and_b32_e32 v0, 3, v30
	v_lshrrev_b32_e32 v2, 2, v2
	v_add_u32_e32 v2, 0x4200, v2
	v_cmp_eq_u32_e32 vcc, 0, v0
	s_nop 1
	v_cndmask_b32_e32 v0, v1, v2, vcc
	s_andn2_saveexec_b64 s[0:1], s[0:1]
	v_and_b32_e32 v0, 0x7ff, v24
	v_cmp_ne_u32_e32 vcc, 0, v0
	s_nop 1
	v_cndmask_b32_e32 v0, -1, v1, vcc
	s_or_b64 exec, exec, s[0:1]
	v_cmp_lt_i32_e32 vcc, -1, v0
	s_movk_i32 s11, 0x1d00
	v_mov_b64_e32 v[2:3], s[22:23]
	v_cndmask_b32_e32 v28, 0, v0, vcc
	v_mad_i64_i32 v[4:5], s[0:1], v24, s11, v[2:3]
	v_mad_u64_u32 v[0:1], s[0:1], v28, s11, v[2:3]
	v_bfe_u32 v31, v30, 4, 2
	s_add_u32 s8, s44, 0x2200
	s_mov_b64 s[0:1], 0x1000
	s_mov_b64 s[6:7], 0x1080
	v_mov_b32_e32 v35, 0
	s_addc_u32 s9, s45, 0
	v_lshl_add_u64 v[16:17], v[4:5], 0, s[0:1]
	v_lshl_add_u64 v[18:19], v[4:5], 0, s[6:7]
	v_lshl_add_u64 v[20:21], v[0:1], 0, s[0:1]
	v_lshl_add_u64 v[22:23], v[0:1], 0, s[6:7]
	v_lshlrev_b32_e32 v34, 4, v31
	v_lshlrev_b32_e32 v26, 5, v31
	v_mov_b32_e32 v27, v35
	v_lshl_add_u64 v[4:5], v[16:17], 0, v[34:35]
	v_lshl_add_u64 v[0:1], v[18:19], 0, v[34:35]
	v_lshl_add_u64 v[12:13], v[20:21], 0, v[34:35]
	v_lshl_add_u64 v[6:7], v[22:23], 0, v[34:35]
	v_lshl_add_u64 v[48:49], s[8:9], 0, v[26:27]
	s_movk_i32 s10, 0x2000
	v_cndmask_b32_e64 v32, 0, 1.0, vcc
	global_load_dwordx4 v[0:3], v[0:1], off
	s_nop 0
	global_load_dwordx4 v[8:11], v[4:5], off
	s_nop 0
	global_load_dwordx4 v[4:7], v[6:7], off
	s_nop 0
	global_load_dwordx4 v[12:15], v[12:13], off
	v_add_co_u32_e32 v26, vcc, s10, v48
	s_mov_b64 s[6:7], 0x2000
	s_nop 0
	v_addc_co_u32_e32 v27, vcc, 0, v49, vcc
	global_load_dwordx4 v[36:39], v[26:27], off
	global_load_dwordx4 v[40:43], v[26:27], off offset:256
	v_lshl_add_u64 v[26:27], v[48:49], 0, s[6:7]
	global_load_dwordx4 v[44:47], v[26:27], off offset:16
	s_mov_b64 s[0:1], 0x2100
	v_lshl_add_u64 v[48:49], v[48:49], 0, s[0:1]
	global_load_dwordx4 v[48:51], v[48:49], off offset:16
	v_lshlrev_b32_e32 v72, 3, v31
	v_or_b32_e32 v33, 32, v72
	v_mov_b32_e32 v55, v35
	v_lshlrev_b32_e32 v54, 2, v33
	v_mov_b32_e32 v53, v35
	v_lshlrev_b32_e32 v52, 1, v33
	v_lshl_add_u64 v[64:65], s[8:9], 0, v[54:55]
	v_lshl_add_u64 v[16:17], v[16:17], 0, v[52:53]
	v_lshl_add_u64 v[18:19], v[18:19], 0, v[52:53]
	v_lshl_add_u64 v[56:57], v[20:21], 0, v[52:53]
	v_lshl_add_u64 v[58:59], v[22:23], 0, v[52:53]
	v_add_co_u32_e32 v66, vcc, s10, v64
	global_load_dwordx4 v[20:23], v[18:19], off
	global_load_dwordx4 v[52:55], v[16:17], off
	s_nop 0
	global_load_dwordx4 v[16:19], v[58:59], off
	s_nop 0
	global_load_dwordx4 v[56:59], v[56:57], off
	v_addc_co_u32_e32 v67, vcc, 0, v65, vcc
	global_load_dwordx4 v[60:63], v[66:67], off
	v_ashrrev_i32_e32 v25, 31, v24
	v_mad_i64_i32 v[26:27], s[24:25], v24, s11, 0
	v_mad_u64_u32 v[28:29], s[24:25], v28, s11, 0
	v_or_b32_e32 v26, v26, v72
	v_or_b32_e32 v28, v28, v72
	s_mov_b64 s[8:9], 0
	s_mov_b32 s11, 0x37f0000
	s_mov_b32 s24, 0x3f1b4598
	s_mov_b32 s25, 0x1311000
	s_mov_b32 s34, 0x1331000
	s_mov_b32 s35, 0xf800000
	v_mov_b32_e32 v84, 0x260
	v_mbcnt_hi_u32_b32 v85, -1, v152
	s_mov_b64 s[38:39], s[44:45]
	s_waitcnt vmcnt(12)
	v_cvt_f32_f16_e32 v68, v0
	v_cvt_f32_f16_sdwa v69, v0 dst_sel:DWORD dst_unused:UNUSED_PAD src0_sel:WORD_1
	s_waitcnt vmcnt(10)
	v_cvt_f32_f16_e32 v70, v4
	s_waitcnt vmcnt(9)
	v_fma_mix_f32 v0, v32, v12, -v8 op_sel_hi:[0,1,1]
	v_fma_mix_f32 v12, v32, v12, -v8 op_sel:[0,1,1] op_sel_hi:[0,1,1]
	v_cvt_f32_f16_sdwa v71, v4 dst_sel:DWORD dst_unused:UNUSED_PAD src0_sel:WORD_1
	v_fma_mix_f32 v4, v32, v13, -v9 op_sel_hi:[0,1,1]
	v_fma_mix_f32 v33, v32, v13, -v9 op_sel:[0,1,1] op_sel_hi:[0,1,1]
	s_waitcnt vmcnt(8)
	v_fma_mix_f32 v0, v36, v0, v8 op_sel_hi:[0,0,1]
	v_fma_mix_f32 v8, v12, v37, v8 op_sel:[0,0,1] op_sel_hi:[0,0,1]
	v_add_f32_e32 v0, v0, v0
	v_add_f32_e32 v8, v8, v8
	v_mul_f32_e32 v0, 0x3fb8aa3b, v0
	v_mul_f32_e32 v8, 0x3fb8aa3b, v8
	v_exp_f32_e32 v0, v0
	v_exp_f32_e32 v8, v8
	v_fma_mix_f32 v4, v4, v38, v9 op_sel_hi:[0,0,1]
	v_add_f32_e32 v4, v4, v4
	v_add_f32_e32 v0, 1.0, v0
	v_add_f32_e32 v8, 1.0, v8
	v_rcp_f32_e32 v12, v0
	v_rcp_f32_e32 v13, v8
	v_fma_mix_f32 v8, v33, v39, v9 op_sel:[0,0,1] op_sel_hi:[0,0,1]
	v_mul_f32_e32 v0, 0x3fb8aa3b, v4
	v_add_f32_e32 v8, v8, v8
	v_exp_f32_e32 v4, v0
	v_pk_fma_f32 v[12:13], v[12:13], 2.0, 1.0 op_sel_hi:[1,0,0] neg_lo:[1,0,0] neg_hi:[1,0,0]
	v_mul_f32_e32 v8, 0x3fb8aa3b, v8
	v_cvt_pk_f16_f32 v0, v12, v13
	v_exp_f32_e32 v13, v8
	v_add_f32_e32 v4, 1.0, v4
	v_rcp_f32_e32 v12, v4
	v_pk_fma_f32 v[36:37], v[32:33], v[70:71], v[68:69] op_sel_hi:[0,1,1] neg_lo:[0,0,1] neg_hi:[0,0,1]
	v_add_f32_e32 v4, 1.0, v13
	v_rcp_f32_e32 v13, v4
	s_waitcnt vmcnt(7)
	v_pk_fma_f32 v[8:9], v[40:41], v[36:37], v[68:69]
	v_cvt_f32_f16_e32 v40, v1
	v_cvt_f32_f16_sdwa v41, v1 dst_sel:DWORD dst_unused:UNUSED_PAD src0_sel:WORD_1
	v_cvt_f32_f16_e32 v36, v5
	v_cvt_f32_f16_sdwa v37, v5 dst_sel:DWORD dst_unused:UNUSED_PAD src0_sel:WORD_1
	v_cvt_pk_f16_f32 v4, v8, v9
	v_pk_fma_f32 v[8:9], v[12:13], 2.0, 1.0 op_sel_hi:[1,0,0] neg_lo:[1,0,0] neg_hi:[1,0,0]
	v_fma_mix_f32 v5, v32, v14, -v10 op_sel_hi:[0,1,1]
	v_cvt_pk_f16_f32 v1, v8, v9
	v_pk_fma_f32 v[8:9], v[32:33], v[36:37], v[40:41] op_sel_hi:[0,1,1] neg_lo:[0,0,1] neg_hi:[0,0,1]
	global_load_dwordx4 v[36:39], v[66:67], off offset:256
	v_pk_fma_f32 v[8:9], v[8:9], v[42:43], v[40:41]
	v_lshl_add_u64 v[40:41], v[64:65], 0, s[6:7]
	global_load_dwordx4 v[40:43], v[40:41], off offset:16
	s_waitcnt vmcnt(8)
	v_fma_mix_f32 v5, v5, v44, v10 op_sel_hi:[0,0,1]
	v_fma_mix_f32 v12, v32, v14, -v10 op_sel:[0,1,1] op_sel_hi:[0,1,1]
	v_add_f32_e32 v5, v5, v5
	v_fma_mix_f32 v10, v12, v45, v10 op_sel:[0,0,1] op_sel_hi:[0,0,1]
	v_mul_f32_e32 v5, 0x3fb8aa3b, v5
	v_add_f32_e32 v10, v10, v10
	v_exp_f32_e32 v5, v5
	v_mul_f32_e32 v10, 0x3fb8aa3b, v10
	v_exp_f32_e32 v10, v10
	v_cvt_f32_f16_e32 v66, v6
	v_add_f32_e32 v5, 1.0, v5
	v_cvt_f32_f16_sdwa v67, v6 dst_sel:DWORD dst_unused:UNUSED_PAD src0_sel:WORD_1
	v_fma_mix_f32 v6, v32, v15, -v11 op_sel_hi:[0,1,1]
	v_rcp_f32_e32 v12, v5
	v_add_f32_e32 v5, 1.0, v10
	v_fma_mix_f32 v6, v6, v46, v11 op_sel_hi:[0,0,1]
	v_fma_mix_f32 v10, v32, v15, -v11 op_sel:[0,1,1] op_sel_hi:[0,1,1]
	v_add_f32_e32 v6, v6, v6
	v_fma_mix_f32 v10, v10, v47, v11 op_sel:[0,0,1] op_sel_hi:[0,0,1]
	v_mul_f32_e32 v6, 0x3fb8aa3b, v6
	v_add_f32_e32 v10, v10, v10
	v_exp_f32_e32 v6, v6
	v_mul_f32_e32 v10, 0x3fb8aa3b, v10
	v_exp_f32_e32 v11, v10
	v_rcp_f32_e32 v13, v5
	v_cvt_f32_f16_e32 v44, v2
	v_cvt_f32_f16_sdwa v45, v2 dst_sel:DWORD dst_unused:UNUSED_PAD src0_sel:WORD_1
	v_add_f32_e32 v6, 1.0, v6
	v_rcp_f32_e32 v10, v6
	v_add_f32_e32 v6, 1.0, v11
	v_rcp_f32_e32 v11, v6
	v_cvt_pk_f16_f32 v5, v8, v9
	v_pk_fma_f32 v[8:9], v[12:13], 2.0, 1.0 op_sel_hi:[1,0,0] neg_lo:[1,0,0] neg_hi:[1,0,0]
	v_cvt_f32_f16_e32 v14, v7
	v_cvt_pk_f16_f32 v2, v8, v9
	v_pk_fma_f32 v[8:9], v[32:33], v[66:67], v[44:45] op_sel_hi:[0,1,1] neg_lo:[0,0,1] neg_hi:[0,0,1]
	s_waitcnt vmcnt(7)
	v_pk_fma_f32 v[8:9], v[8:9], v[48:49], v[44:45]
	v_cvt_f32_f16_sdwa v15, v7 dst_sel:DWORD dst_unused:UNUSED_PAD src0_sel:WORD_1
	v_cvt_pk_f16_f32 v6, v8, v9
	v_pk_fma_f32 v[8:9], v[10:11], 2.0, 1.0 op_sel_hi:[1,0,0] neg_lo:[1,0,0] neg_hi:[1,0,0]
	v_lshl_add_u64 v[10:11], v[64:65], 0, s[0:1]
	global_load_dwordx4 v[44:47], v[10:11], off offset:16
	s_waitcnt vmcnt(4)
	v_fma_mix_f32 v7, v32, v56, -v52 op_sel_hi:[0,1,1]
	s_waitcnt vmcnt(3)
	v_fma_mix_f32 v7, v60, v7, v52 op_sel_hi:[0,0,1]
	v_fma_mix_f32 v10, v32, v56, -v52 op_sel:[0,1,1] op_sel_hi:[0,1,1]
	v_add_f32_e32 v7, v7, v7
	v_fma_mix_f32 v10, v10, v61, v52 op_sel:[0,0,1] op_sel_hi:[0,0,1]
	v_mul_f32_e32 v7, 0x3fb8aa3b, v7
	v_add_f32_e32 v10, v10, v10
	v_exp_f32_e32 v7, v7
	v_mul_f32_e32 v10, 0x3fb8aa3b, v10
	v_exp_f32_e32 v11, v10
	v_cvt_f32_f16_e32 v12, v3
	v_cvt_f32_f16_sdwa v13, v3 dst_sel:DWORD dst_unused:UNUSED_PAD src0_sel:WORD_1
	v_add_f32_e32 v7, 1.0, v7
	v_rcp_f32_e32 v10, v7
	v_add_f32_e32 v7, 1.0, v11
	v_rcp_f32_e32 v11, v7
	v_cvt_pk_f16_f32 v3, v8, v9
	v_pk_fma_f32 v[8:9], v[32:33], v[14:15], v[12:13] op_sel_hi:[0,1,1] neg_lo:[0,0,1] neg_hi:[0,0,1]
	v_pk_fma_f32 v[8:9], v[8:9], v[50:51], v[12:13]
	v_cvt_f32_f16_e32 v12, v20
	v_cvt_f32_f16_sdwa v13, v20 dst_sel:DWORD dst_unused:UNUSED_PAD src0_sel:WORD_1
	v_cvt_f32_f16_e32 v14, v16
	v_cvt_f32_f16_sdwa v15, v16 dst_sel:DWORD dst_unused:UNUSED_PAD src0_sel:WORD_1
	v_cvt_pk_f16_f32 v7, v8, v9
	v_pk_fma_f32 v[8:9], v[10:11], 2.0, 1.0 op_sel_hi:[1,0,0] neg_lo:[1,0,0] neg_hi:[1,0,0]
	v_cvt_f32_f16_e32 v20, v21
	v_cvt_pk_f16_f32 v8, v8, v9
	v_fma_mix_f32 v9, v32, v57, -v53 op_sel_hi:[0,1,1]
	v_pk_fma_f32 v[10:11], v[32:33], v[14:15], v[12:13] op_sel_hi:[0,1,1] neg_lo:[0,0,1] neg_hi:[0,0,1]
	v_fma_mix_f32 v9, v9, v62, v53 op_sel_hi:[0,0,1]
	v_fma_mix_f32 v14, v32, v57, -v53 op_sel:[0,1,1] op_sel_hi:[0,1,1]
	v_add_f32_e32 v9, v9, v9
	v_fma_mix_f32 v14, v14, v63, v53 op_sel:[0,0,1] op_sel_hi:[0,0,1]
	v_mul_f32_e32 v9, 0x3fb8aa3b, v9
	v_add_f32_e32 v14, v14, v14
	v_exp_f32_e32 v9, v9
	v_mul_f32_e32 v14, 0x3fb8aa3b, v14
	v_exp_f32_e32 v15, v14
	s_waitcnt vmcnt(2)
	v_pk_fma_f32 v[10:11], v[36:37], v[10:11], v[12:13]
	v_add_f32_e32 v9, 1.0, v9
	v_rcp_f32_e32 v14, v9
	v_add_f32_e32 v9, 1.0, v15
	v_rcp_f32_e32 v15, v9
	v_fma_mix_f32 v13, v32, v58, -v54 op_sel_hi:[0,1,1]
	v_cvt_pk_f16_f32 v12, v10, v11
	s_waitcnt vmcnt(1)
	v_fma_mix_f32 v13, v13, v40, v54 op_sel_hi:[0,0,1]
	v_pk_fma_f32 v[10:11], v[14:15], 2.0, 1.0 op_sel_hi:[1,0,0] neg_lo:[1,0,0] neg_hi:[1,0,0]
	v_fma_mix_f32 v14, v32, v58, -v54 op_sel:[0,1,1] op_sel_hi:[0,1,1]
	v_add_f32_e32 v13, v13, v13
	v_fma_mix_f32 v14, v14, v41, v54 op_sel:[0,0,1] op_sel_hi:[0,0,1]
	v_mul_f32_e32 v13, 0x3fb8aa3b, v13
	v_add_f32_e32 v14, v14, v14
	v_exp_f32_e32 v13, v13
	v_mul_f32_e32 v14, 0x3fb8aa3b, v14
	v_exp_f32_e32 v15, v14
	v_cvt_f32_f16_sdwa v21, v21 dst_sel:DWORD dst_unused:UNUSED_PAD src0_sel:WORD_1
	v_cvt_f32_f16_e32 v16, v17
	v_cvt_f32_f16_sdwa v17, v17 dst_sel:DWORD dst_unused:UNUSED_PAD src0_sel:WORD_1
	v_add_f32_e32 v13, 1.0, v13
	v_rcp_f32_e32 v14, v13
	v_add_f32_e32 v13, 1.0, v15
	v_rcp_f32_e32 v15, v13
	v_cvt_pk_f16_f32 v9, v10, v11
	v_pk_fma_f32 v[10:11], v[32:33], v[16:17], v[20:21] op_sel_hi:[0,1,1] neg_lo:[0,0,1] neg_hi:[0,0,1]
	v_pk_fma_f32 v[10:11], v[10:11], v[38:39], v[20:21]
	v_cvt_f32_f16_e32 v20, v18
	v_cvt_pk_f16_f32 v13, v10, v11
	v_pk_fma_f32 v[10:11], v[14:15], 2.0, 1.0 op_sel_hi:[1,0,0] neg_lo:[1,0,0] neg_hi:[1,0,0]
	v_cvt_f32_f16_sdwa v21, v18 dst_sel:DWORD dst_unused:UNUSED_PAD src0_sel:WORD_1
	v_cvt_pk_f16_f32 v10, v10, v11
	v_fma_mix_f32 v11, v32, v59, -v55 op_sel_hi:[0,1,1]
	v_fma_mix_f32 v11, v11, v42, v55 op_sel_hi:[0,0,1]
	v_fma_mix_f32 v18, v32, v59, -v55 op_sel:[0,1,1] op_sel_hi:[0,1,1]
	v_add_f32_e32 v11, v11, v11
	v_fma_mix_f32 v18, v18, v43, v55 op_sel:[0,0,1] op_sel_hi:[0,0,1]
	v_mul_f32_e32 v11, 0x3fb8aa3b, v11
	v_add_f32_e32 v18, v18, v18
	v_cvt_f32_f16_e32 v16, v22
	v_cvt_f32_f16_sdwa v17, v22 dst_sel:DWORD dst_unused:UNUSED_PAD src0_sel:WORD_1
	v_exp_f32_e32 v11, v11
	v_mul_f32_e32 v18, 0x3fb8aa3b, v18
	v_exp_f32_e32 v18, v18
	v_pk_fma_f32 v[14:15], v[32:33], v[20:21], v[16:17] op_sel_hi:[0,1,1] neg_lo:[0,0,1] neg_hi:[0,0,1]
	v_add_f32_e32 v11, 1.0, v11
	s_waitcnt vmcnt(0)
	v_pk_fma_f32 v[14:15], v[14:15], v[44:45], v[16:17]
	v_rcp_f32_e32 v16, v11
	v_add_f32_e32 v11, 1.0, v18
	v_rcp_f32_e32 v17, v11
	v_cvt_f32_f16_e32 v20, v23
	v_cvt_f32_f16_sdwa v21, v23 dst_sel:DWORD dst_unused:UNUSED_PAD src0_sel:WORD_1
	v_cvt_f32_f16_e32 v18, v19
	v_cvt_f32_f16_sdwa v19, v19 dst_sel:DWORD dst_unused:UNUSED_PAD src0_sel:WORD_1
	v_pk_fma_f32 v[16:17], v[16:17], 2.0, 1.0 op_sel_hi:[1,0,0] neg_lo:[1,0,0] neg_hi:[1,0,0]
	v_cvt_pk_f16_f32 v14, v14, v15
	v_cvt_pk_f16_f32 v11, v16, v17
	v_pk_fma_f32 v[16:17], v[32:33], v[18:19], v[20:21] op_sel_hi:[0,1,1] neg_lo:[0,0,1] neg_hi:[0,0,1]
	v_pk_fma_f32 v[16:17], v[16:17], v[46:47], v[20:21]
	v_readlane_b32 s0, v250, 21
	v_cvt_pk_f16_f32 v15, v16, v17
	v_lshlrev_b32_e32 v16, 2, v31
	v_and_b32_e32 v17, 16, v30
	v_add_u32_e32 v18, 12, v16
	v_cmp_eq_u32_e32 vcc, 0, v17
	v_readlane_b32 s1, v250, 22
	v_mov_b32_e32 v23, v35
	v_cndmask_b32_e32 v22, v18, v16, vcc
	v_lshlrev_b64 v[16:17], 11, v[24:25]
	v_lshl_add_u64 v[18:19], s[0:1], 0, v[16:17]
	v_lshl_add_u64 v[20:21], s[30:31], 0, v[16:17]
	v_lshl_add_u64 v[16:17], s[14:15], 0, v[16:17]
	v_lshlrev_b32_e32 v22, 1, v22
	v_lshl_add_u64 v[16:17], v[16:17], 0, v[22:23]
	s_mov_b64 s[0:1], 0x1670400
	v_lshl_add_u64 v[42:43], v[16:17], 0, s[0:1]
	s_mov_b64 s[0:1], 0xb078400
	v_lshl_add_u64 v[46:47], v[16:17], 0, s[0:1]
	v_and_b32_e32 v16, 15, v30
	v_lshlrev_b32_e32 v16, 7, v16
	v_mov_b32_e32 v17, v35
	v_mov_b32_e32 v33, v32
	v_mov_b32_e32 v36, v32
	v_mov_b32_e32 v37, v32
	v_lshl_add_u64 v[38:39], s[14:15], 0, v[26:27]
	v_lshl_add_u64 v[40:41], s[14:15], 0, v[28:29]
	v_lshl_add_u64 v[44:45], v[20:21], 0, v[22:23]
	v_lshl_add_u64 v[48:49], v[18:19], 0, v[22:23]
	v_lshl_add_u64 v[50:51], s[14:15], 0, v[16:17]
	v_readfirstlane_b32 s0, v154
	s_nop 3
	s_bfe_u32 s0, s0, 0x10008
	s_lshl_b32 s0, s0, 2
	s_mov_b32 s1, 4
	s_cmp_eq_u32 m0, 0
	s_cbranch_scc1 .Llora_set_1
	s_and_b32 s0, s91, 7
	s_mov_b32 s1, 1
.Llora_set_1:
	s_lshl_b32 s8, s0, 7
	s_add_u32 s1, s1, s0
	s_lshl_b32 s101, s1, 7
	s_lshl_b32 s1, s0, 8
	s_add_u32 s46, s46, s1
	s_addc_u32 s47, s47, 0
	s_add_u32 s50, s50, s1
	s_addc_u32 s51, s51, 0
	s_add_u32 s54, s54, s1
	s_addc_u32 s55, s55, 0
	s_add_u32 s56, s56, s1
	s_addc_u32 s57, s57, 0
	s_add_u32 s38, s38, s1
	s_addc_u32 s39, s39, 0
	s_lshl_b32 s0, s0, 13
	s_mov_b32 s1, 0
	v_lshl_add_u64 v[50:51], v[50:51], 0, s[0:1]
.LBB0_936:
	v_and_b32_e32 v246, 15, v85
	v_lshl_add_u32 v246, v246, 7, v34
	s_lshl_b32 s0, s8, 6
	v_add_u32_e32 v246, s0, v246
	v_add_u32_e32 v247, 0x10000, v246
	s_lshl_b32 s0, s8, 1
	s_add_u32 s0, s0, 0x21000
	v_add_u32_e32 v245, s0, v34
	v_lshl_add_u64 v[16:17], s[38:39], 0, v[34:35]
	v_add_co_u32_e64 v150, s[0:1], s10, v16
	v_lshl_add_u64 v[18:19], v[38:39], 0, s[8:9]
	s_nop 0
	v_addc_co_u32_e64 v151, s[0:1], 0, v17, s[0:1]
	v_add_co_u32_e64 v122, s[0:1], s11, v18
	v_lshl_add_u64 v[20:21], v[40:41], 0, s[8:9]
	s_nop 0
	v_addc_co_u32_e64 v123, s[0:1], 0, v19, s[0:1]
	v_add_co_u32_e64 v124, s[0:1], s11, v20
	v_lshl_add_u64 v[52:53], v[50:51], 0, v[34:35]
	s_nop 0
	v_addc_co_u32_e64 v125, s[0:1], 0, v21, s[0:1]
	v_add_co_u32_e64 v156, s[0:1], s25, v52
	v_and_b32_e32 v64, 64, v85
	s_nop 0
	v_addc_co_u32_e64 v157, s[0:1], 0, v53, s[0:1]
	v_add_co_u32_e64 v164, s[0:1], s34, v52
	v_xor_b32_e32 v153, 16, v85
	v_add_co_u32_e32 v82, vcc, 0x1310000, v52
	v_addc_co_u32_e64 v165, s[0:1], 0, v53, s[0:1]
	v_add_u32_e32 v176, 64, v64
	v_lshl_add_u64 v[24:25], s[46:47], 0, v[34:35]
	v_lshl_add_u64 v[26:27], s[50:51], 0, v[34:35]
	v_lshl_add_u64 v[28:29], s[54:55], 0, v[34:35]
	v_xor_b32_e32 v155, 32, v85
	v_addc_co_u32_e32 v83, vcc, 0, v53, vcc
	v_cmp_lt_i32_e64 s[0:1], v153, v176
	v_lshl_add_u64 v[54:55], s[56:57], 0, v[34:35]
	ds_read_b128 v[86:89], v245 offset:0
	ds_read_b128 v[90:93], v245 offset:64
	ds_read_b128 v[94:97], v245 offset:2048
	ds_read_b128 v[98:101], v245 offset:2112
	ds_read_b128 v[70:73], v245 offset:4096
	ds_read_b128 v[74:77], v245 offset:4160
	ds_read_b128 v[20:23], v245 offset:8192
	ds_read_b128 v[16:19], v245 offset:8256
	ds_read_b128 v[102:105], v245 offset:128
	ds_read_b128 v[106:109], v245 offset:192
	ds_read_b128 v[110:113], v245 offset:2176
	ds_read_b128 v[114:117], v245 offset:2240
	ds_read_b128 v[78:81], v245 offset:4224
	ds_read_b128 v[118:121], v245 offset:4288
	s_nop 0
	ds_read_b128 v[28:31], v245 offset:8320
	ds_read_b128 v[24:27], v245 offset:8384
	global_load_dwordx2 v[208:209], v[122:123], off offset:1024
	global_load_dwordx2 v[210:211], v[124:125], off offset:1024
	global_load_dwordx2 v[212:213], v[122:123], off offset:1056
	global_load_dwordx2 v[214:215], v[124:125], off offset:1056
	global_load_dwordx2 v[216:217], v[122:123], off offset:1088
	global_load_dwordx2 v[218:219], v[124:125], off offset:1088
	global_load_dwordx2 v[220:221], v[122:123], off offset:1120
	global_load_dwordx2 v[222:223], v[124:125], off offset:1120
	s_nop 0
	ds_read_b128 v[122:125], v246 offset:4096
	ds_read_b128 v[126:129], v245 offset:6144
	ds_read_b128 v[130:133], v245 offset:6208
	ds_read_b128 v[134:137], v246 offset:4160
	ds_read_b128 v[138:141], v247 offset:4096
	ds_read_b128 v[142:145], v247 offset:4160
	ds_read_b128 v[146:149], v246 offset:6144
	s_nop 0
	ds_read_b128 v[156:159], v246 offset:6208
	s_nop 0
	ds_read_b128 v[160:163], v247 offset:6144
	s_nop 0
	ds_read_b128 v[164:167], v247 offset:6208
	s_nop 0
	ds_read_b128 v[168:171], v245 offset:6272
	ds_read_b128 v[172:175], v245 offset:6336
	v_cndmask_b32_e64 v150, v85, v153, s[0:1]
	v_cmp_lt_i32_e64 s[0:1], v155, v176
	ds_read_b128 v[176:179], v246 offset:0
	v_add_co_u32_e32 v52, vcc, 0x1330000, v52
	ds_read_b128 v[180:183], v246 offset:2048
	ds_read_b128 v[184:187], v246 offset:64
	ds_read_b128 v[188:191], v246 offset:2112
	v_addc_co_u32_e32 v53, vcc, 0, v53, vcc
	ds_read_b128 v[192:195], v247 offset:0
	ds_read_b128 v[196:199], v247 offset:2048
	ds_read_b128 v[200:203], v247 offset:64
	ds_read_b128 v[204:207], v247 offset:2112
	v_cndmask_b32_e64 v151, v85, v155, s[0:1]
	v_lshlrev_b32_e32 v153, 2, v150
	v_lshlrev_b32_e32 v155, 2, v151
	v_lshl_add_u64 v[56:57], v[48:49], 0, s[8:9]
	v_lshl_add_u64 v[68:69], v[56:57], 0, 64
	v_lshl_add_u64 v[58:59], v[46:47], 0, s[8:9]
	v_lshl_add_u64 v[66:67], v[58:59], 0, 64
	v_lshl_add_u64 v[60:61], v[44:45], 0, s[8:9]
	v_lshl_add_u64 v[62:63], v[42:43], 0, s[8:9]
	s_add_u32 s8, s8, 0x80
	s_addc_u32 s9, s9, 0
	s_add_u32 s46, s46, 0x100
	s_addc_u32 s47, s47, 0
	s_add_u32 s50, s50, 0x100
	s_addc_u32 s51, s51, 0
	s_add_u32 s54, s54, 0x100
	s_addc_u32 s55, s55, 0
	v_lshl_add_u64 v[64:65], v[60:61], 0, 64
	s_add_u32 s56, s56, 0x100
	s_addc_u32 s57, s57, 0
	v_lshl_add_u64 v[54:55], v[62:63], 0, 64
	s_add_u32 s38, s38, 0x100
	s_addc_u32 s39, s39, 0
	s_cmp_eq_u32 s8, s101
	v_lshl_add_u64 v[50:51], v[50:51], 0, s[6:7]
	s_waitcnt vmcnt(0) lgkmcnt(0)
	v_mfma_f32_16x16x32_f16 v[122:125], v[122:125], v[0:3], 0
	v_cvt_f32_f16_e32 v52, v208
	v_cvt_f32_f16_sdwa v53, v208 dst_sel:DWORD dst_unused:UNUSED_PAD src0_sel:WORD_1
	v_cvt_f32_f16_e32 v82, v209
	v_cvt_f32_f16_sdwa v83, v209 dst_sel:DWORD dst_unused:UNUSED_PAD src0_sel:WORD_1
	v_cvt_f32_f16_e32 v150, v210
	v_cvt_f32_f16_sdwa v151, v210 dst_sel:DWORD dst_unused:UNUSED_PAD src0_sel:WORD_1
	v_cvt_f32_f16_e32 v208, v211
	v_cvt_f32_f16_sdwa v209, v211 dst_sel:DWORD dst_unused:UNUSED_PAD src0_sel:WORD_1
	v_cvt_f32_f16_e32 v210, v212
	v_cvt_f32_f16_sdwa v211, v212 dst_sel:DWORD dst_unused:UNUSED_PAD src0_sel:WORD_1
	v_cvt_f32_f16_e32 v212, v213
	v_cvt_f32_f16_sdwa v213, v213 dst_sel:DWORD dst_unused:UNUSED_PAD src0_sel:WORD_1
	v_cvt_f32_f16_e32 v224, v214
	v_cvt_f32_f16_sdwa v225, v214 dst_sel:DWORD dst_unused:UNUSED_PAD src0_sel:WORD_1
	v_cvt_f32_f16_e32 v214, v215
	v_cvt_f32_f16_sdwa v215, v215 dst_sel:DWORD dst_unused:UNUSED_PAD src0_sel:WORD_1
	v_cvt_f32_f16_e32 v226, v216
	v_cvt_f32_f16_sdwa v227, v216 dst_sel:DWORD dst_unused:UNUSED_PAD src0_sel:WORD_1
	v_cvt_f32_f16_e32 v216, v217
	v_cvt_f32_f16_sdwa v217, v217 dst_sel:DWORD dst_unused:UNUSED_PAD src0_sel:WORD_1
	v_cvt_f32_f16_e32 v230, v220
	v_cvt_f32_f16_sdwa v231, v220 dst_sel:DWORD dst_unused:UNUSED_PAD src0_sel:WORD_1
	v_cvt_f32_f16_e32 v220, v221
	v_cvt_f32_f16_sdwa v221, v221 dst_sel:DWORD dst_unused:UNUSED_PAD src0_sel:WORD_1
	v_cvt_f32_f16_e32 v228, v218
	v_cvt_f32_f16_sdwa v229, v218 dst_sel:DWORD dst_unused:UNUSED_PAD src0_sel:WORD_1
	v_cvt_f32_f16_e32 v218, v219
	v_cvt_f32_f16_sdwa v219, v219 dst_sel:DWORD dst_unused:UNUSED_PAD src0_sel:WORD_1
	v_cvt_f32_f16_e32 v232, v222
	v_cvt_f32_f16_sdwa v233, v222 dst_sel:DWORD dst_unused:UNUSED_PAD src0_sel:WORD_1
	v_cvt_f32_f16_e32 v222, v223
	v_cvt_f32_f16_sdwa v223, v223 dst_sel:DWORD dst_unused:UNUSED_PAD src0_sel:WORD_1
	v_xor_b32_e32 v234, 0x80000000, v82
	v_xor_b32_e32 v235, 0x80000000, v83
	v_xor_b32_e32 v236, 0x80000000, v52
	v_xor_b32_e32 v237, 0x80000000, v53
	v_xor_b32_e32 v238, 0x80000000, v212
	v_xor_b32_e32 v239, 0x80000000, v213
	s_waitcnt vmcnt(0)
	v_mfma_f32_16x16x32_f16 v[138:141], v[138:141], v[4:7], 0
	v_xor_b32_e32 v240, 0x80000000, v210
	v_xor_b32_e32 v241, 0x80000000, v211
	v_xor_b32_e32 v242, 0x80000000, v216
	s_waitcnt vmcnt(0)
	v_mfma_f32_16x16x32_f16 v[146:149], v[146:149], v[0:3], 0
	v_xor_b32_e32 v243, 0x80000000, v217
	v_xor_b32_e32 v244, 0x80000000, v226
	v_xor_b32_e32 v245, 0x80000000, v227
	s_waitcnt vmcnt(0)
	v_mfma_f32_16x16x32_f16 v[160:163], v[160:163], v[4:7], 0
	v_xor_b32_e32 v246, 0x80000000, v220
	v_xor_b32_e32 v247, 0x80000000, v221
	v_xor_b32_e32 v248, 0x80000000, v230
	s_waitcnt vmcnt(0)
	v_mfma_f32_16x16x32_f16 v[176:179], v[176:179], v[0:3], 0
	v_xor_b32_e32 v249, 0x80000000, v231
	v_pk_fma_f32 v[208:209], v[36:37], v[208:209], v[234:235]
	v_pk_fma_f32 v[150:151], v[32:33], v[150:151], v[236:237]
	s_waitcnt vmcnt(0)
	v_mfma_f32_16x16x32_f16 v[180:183], v[180:183], v[0:3], 0
	v_fma_f32 v214, v36, v214, v238
	v_fma_f32 v215, v37, v215, v239
	v_pk_fma_f32 v[224:225], v[32:33], v[224:225], v[240:241]
	v_pk_fma_f32 v[218:219], v[36:37], v[218:219], v[242:243]
	v_pk_fma_f32 v[228:229], v[32:33], v[228:229], v[244:245]
	v_pk_fma_f32 v[222:223], v[36:37], v[222:223], v[246:247]
	v_pk_fma_f32 v[232:233], v[32:33], v[232:233], v[248:249]
	v_pk_fma_f32 v[150:151], v[126:127], v[150:151], v[52:53]
	v_pk_fma_f32 v[208:209], v[128:129], v[208:209], v[82:83]
	s_waitcnt vmcnt(0)
	v_mfma_f32_16x16x32_f16 v[126:129], v[196:199], v[4:7], 0
	v_fma_f32 v196, v130, v224, v210
	v_fma_f32 v197, v131, v225, v211
	v_pk_fma_f32 v[198:199], v[132:133], v[214:215], v[212:213]
	v_pk_fma_f32 v[168:169], v[168:169], v[228:229], v[226:227]
	v_pk_fma_f32 v[170:171], v[170:171], v[218:219], v[216:217]
	v_pk_fma_f32 v[172:173], v[172:173], v[232:233], v[230:231]
	v_pk_fma_f32 v[174:175], v[174:175], v[222:223], v[220:221]
	v_pk_mul_f32 v[52:53], v[70:71], v[150:151]
	v_pk_mul_f32 v[70:71], v[72:73], v[208:209]
	v_pk_mul_f32 v[72:73], v[74:75], v[196:197]
	v_pk_mul_f32 v[74:75], v[76:77], v[198:199]
	v_mfma_f32_16x16x32_f16 v[192:195], v[192:195], v[4:7], 0
	v_mul_f32_e64 v76, v78, v168
	v_mul_f32_e64 v77, v79, v169
	v_pk_mul_f32 v[78:79], v[80:81], v[170:171]
	v_pk_mul_f32 v[80:81], v[118:119], v[172:173]
	v_mfma_f32_16x16x32_f16 v[122:125], v[134:137], v[8:11], v[122:125]
	v_mul_f32_e64 v82, v120, v174
	v_mul_f32_e64 v83, v121, v175
	v_mfma_f32_16x16x32_f16 v[130:133], v[142:145], v[12:15], v[138:141]
	v_mul_f32_e64 v142, v70, v70
	v_mul_f32_e64 v143, v71, v71
	s_nop 2
	v_pk_add_f32 v[102:103], v[122:123], v[102:103]
	v_pk_add_f32 v[104:105], v[124:125], v[104:105]
	v_mfma_f32_16x16x32_f16 v[118:121], v[156:159], v[8:11], v[146:149]
	v_mul_f32_e64 v156, v52, v52
	v_mul_f32_e64 v157, v53, v53
	v_pk_mul_f32 v[158:159], v[72:73], v[72:73]
	v_pk_add_f32 v[112:113], v[132:133], v[112:113]
	v_pk_mul_f32 v[146:147], v[74:75], v[74:75]
	v_mfma_f32_16x16x32_f16 v[134:137], v[164:167], v[12:15], v[160:163]
	v_pk_mov_b32 v[166:167], v[156:157], v[142:143] op_sel:[1,0]
	v_mov_b32_e32 v157, v143
	v_pk_add_f32 v[156:157], v[166:167], v[156:157]
	v_mfma_f32_16x16x32_f16 v[138:141], v[184:187], v[8:11], v[176:179]
	v_mul_f32_e64 v148, v78, v78
	v_mul_f32_e64 v149, v79, v79
	v_pk_mul_f32 v[160:161], v[76:77], v[76:77]
	v_pk_mul_f32 v[162:163], v[82:83], v[82:83]
	v_mfma_f32_16x16x32_f16 v[142:145], v[188:191], v[8:11], v[180:183]
	v_pk_mov_b32 v[176:177], v[158:159], v[146:147] op_sel:[1,0]
	v_mov_b32_e32 v159, v147
	v_pk_add_f32 v[158:159], v[176:177], v[158:159]
	s_waitcnt vmcnt(0)
	v_mfma_f32_16x16x32_f16 v[126:129], v[204:207], v[12:15], v[126:129]
	v_mul_f32_e64 v164, v80, v80
	v_mul_f32_e64 v165, v81, v81
	v_pk_add_f32 v[156:157], v[156:157], v[156:157] op_sel:[0,1] op_sel_hi:[1,0]
	v_pk_add_f32 v[158:159], v[158:159], v[158:159] op_sel:[0,1] op_sel_hi:[1,0]
	v_add_f32_e32 v160, v160, v161
	v_add_f32_e32 v178, v148, v149
	v_mfma_f32_16x16x32_f16 v[146:149], v[200:203], v[12:15], v[192:195]
	v_mov_b32_e32 v161, v162
	v_mov_b32_e32 v179, v163
	v_mov_b32_e32 v157, v164
	v_mov_b32_e32 v159, v165
	v_pk_add_f32 v[160:161], v[160:161], v[178:179]
	v_pk_add_f32 v[110:111], v[130:131], v[110:111]
	v_pk_add_f32 v[108:109], v[120:121], v[108:109]
	v_pk_add_f32 v[106:107], v[118:119], v[106:107]
	v_pk_add_f32 v[116:117], v[136:137], v[116:117]
	v_pk_add_f32 v[114:115], v[134:135], v[114:115]
	v_pk_add_f32 v[88:89], v[140:141], v[88:89]
	v_pk_add_f32 v[86:87], v[138:139], v[86:87]
	v_pk_add_f32 v[90:91], v[142:143], v[90:91]
	v_mul_f32_e32 v118, 0xbfb8aa3b, v102
	v_mul_f32_e32 v119, 0xbfb8aa3b, v103
	v_pk_add_f32 v[102:103], v[156:157], v[158:159]
	v_pk_add_f32 v[92:93], v[144:145], v[92:93]
	v_mul_f32_e32 v104, 0xbfb8aa3b, v104
	v_mul_f32_e32 v105, 0xbfb8aa3b, v105
	v_mul_f32_e32 v110, 0xbfb8aa3b, v110
	v_mul_f32_e32 v111, 0xbfb8aa3b, v111
	v_mul_f32_e32 v112, 0xbfb8aa3b, v112
	v_mul_f32_e32 v113, 0xbfb8aa3b, v113
	v_mul_f32_e32 v106, 0xbfb8aa3b, v106
	v_mul_f32_e32 v107, 0xbfb8aa3b, v107
	v_mul_f32_e32 v108, 0xbfb8aa3b, v108
	v_mul_f32_e32 v109, 0xbfb8aa3b, v109
	v_mul_f32_e32 v114, 0xbfb8aa3b, v114
	v_mul_f32_e32 v115, 0xbfb8aa3b, v115
	v_mul_f32_e32 v116, 0xbfb8aa3b, v116
	v_mul_f32_e32 v117, 0xbfb8aa3b, v117
	v_mul_f32_e32 v120, 0xbfb8aa3b, v86
	v_mul_f32_e32 v121, 0xbfb8aa3b, v87
	v_mul_f32_e32 v122, 0xbfb8aa3b, v88
	v_mul_f32_e32 v123, 0xbfb8aa3b, v89
	v_pk_add_f32 v[88:89], v[126:127], v[98:99]
	v_mul_f32_e32 v98, 0xbfb8aa3b, v90
	v_mul_f32_e32 v99, 0xbfb8aa3b, v91
	v_pk_add_f32 v[90:91], v[102:103], v[160:161]
	v_pk_add_f32 v[86:87], v[128:129], v[100:101]
	v_mul_f32_e32 v92, 0xbfb8aa3b, v92
	v_mul_f32_e32 v93, 0xbfb8aa3b, v93
	v_exp_f32_e32 v100, v118
	v_exp_f32_e32 v101, v119
	v_exp_f32_e32 v104, v104
	v_exp_f32_e32 v105, v105
	v_exp_f32_e32 v110, v110
	v_exp_f32_e32 v111, v111
	v_exp_f32_e32 v112, v112
	v_exp_f32_e32 v113, v113
	v_exp_f32_e32 v106, v106
	v_exp_f32_e32 v107, v107
	v_exp_f32_e32 v108, v108
	v_exp_f32_e32 v109, v109
	v_exp_f32_e32 v114, v114
	v_exp_f32_e32 v115, v115
	v_exp_f32_e32 v116, v116
	v_exp_f32_e32 v117, v117
	v_exp_f32_e32 v102, v120
	v_exp_f32_e32 v103, v121
	v_exp_f32_e32 v98, v98
	v_exp_f32_e32 v99, v99
	v_add_f32_e32 v120, v90, v91
	v_pk_add_f32 v[94:95], v[146:147], v[94:95]
	v_exp_f32_e32 v118, v122
	v_exp_f32_e32 v119, v123
	v_exp_f32_e32 v92, v92
	v_exp_f32_e32 v93, v93
	v_mul_f32_e32 v89, 0xbfb8aa3b, v89
	ds_bpermute_b32 v129, v153, v120
	v_pk_add_f32 v[96:97], v[148:149], v[96:97]
	v_mul_f32_e32 v94, 0xbfb8aa3b, v94
	v_mul_f32_e32 v86, 0xbfb8aa3b, v86
	v_exp_f32_e32 v126, v89
	v_mul_f32_e32 v95, 0xbfb8aa3b, v95
	v_mul_f32_e32 v96, 0xbfb8aa3b, v96
	v_mul_f32_e32 v97, 0xbfb8aa3b, v97
	v_mul_f32_e32 v88, 0xbfb8aa3b, v88
	v_mul_f32_e32 v87, 0xbfb8aa3b, v87
	v_exp_f32_e32 v121, v94
	v_exp_f32_e32 v127, v86
	v_exp_f32_e32 v122, v95
	v_exp_f32_e32 v123, v96
	v_exp_f32_e32 v124, v97
	v_exp_f32_e32 v125, v88
	v_exp_f32_e32 v128, v87
	v_add_f32_e32 v86, 1.0, v100
	v_add_f32_e32 v87, 1.0, v101
	v_add_f32_e32 v88, 1.0, v104
	v_add_f32_e32 v89, 1.0, v105
	v_add_f32_e32 v90, 1.0, v110
	v_add_f32_e32 v91, 1.0, v111
	v_add_f32_e32 v94, 1.0, v112
	v_add_f32_e32 v95, 1.0, v113
	v_add_f32_e32 v96, 1.0, v106
	v_add_f32_e32 v97, 1.0, v107
	v_add_f32_e32 v100, 1.0, v108
	v_add_f32_e32 v101, 1.0, v109
	v_add_f32_e32 v104, 1.0, v114
	v_add_f32_e32 v105, 1.0, v115
	v_add_f32_e32 v106, 1.0, v116
	v_add_f32_e32 v107, 1.0, v117
	v_add_f32_e32 v102, 1.0, v102
	v_add_f32_e32 v103, 1.0, v103
	v_add_f32_e32 v110, 1.0, v98
	v_add_f32_e32 v111, 1.0, v99
	v_add_f32_e32 v108, 1.0, v118
	v_add_f32_e32 v109, 1.0, v119
	v_add_f32_e32 v112, 1.0, v92
	v_add_f32_e32 v113, 1.0, v93
	v_rcp_f32_e32 v86, v86
	v_rcp_f32_e32 v87, v87
	v_rcp_f32_e32 v88, v88
	v_rcp_f32_e32 v89, v89
	v_rcp_f32_e32 v90, v90
	v_rcp_f32_e32 v91, v91
	v_rcp_f32_e32 v92, v94
	v_rcp_f32_e32 v93, v95
	v_rcp_f32_e32 v94, v96
	v_rcp_f32_e32 v95, v97
	v_rcp_f32_e32 v96, v100
	v_rcp_f32_e32 v97, v101
	v_rcp_f32_e32 v98, v104
	v_rcp_f32_e32 v99, v105
	v_rcp_f32_e32 v100, v106
	v_rcp_f32_e32 v101, v107
	v_rcp_f32_e32 v102, v102
	v_rcp_f32_e32 v103, v103
	v_rcp_f32_e32 v106, v110
	v_rcp_f32_e32 v107, v111
	v_rcp_f32_e32 v104, v108
	v_rcp_f32_e32 v105, v109
	v_rcp_f32_e32 v108, v112
	v_rcp_f32_e32 v109, v113
	v_add_f32_e32 v119, 1.0, v126
	s_waitcnt lgkmcnt(0)
	v_add_f32_e32 v126, v120, v129
	v_add_f32_e32 v114, 1.0, v121
	v_add_f32_e32 v121, 1.0, v127
	ds_bpermute_b32 v127, v155, v126
	v_add_f32_e32 v115, 1.0, v122
	v_add_f32_e32 v116, 1.0, v123
	v_add_f32_e32 v117, 1.0, v124
	v_add_f32_e32 v122, 1.0, v128
	v_add_f32_e32 v118, 1.0, v125
	v_rcp_f32_e32 v112, v116
	v_rcp_f32_e32 v113, v117
	v_rcp_f32_e32 v116, v121
	v_rcp_f32_e32 v117, v122
	v_pk_mul_f32 v[88:89], v[88:89], s[24:25] op_sel_hi:[1,0]
	v_pk_mul_f32 v[86:87], v[86:87], s[24:25] op_sel_hi:[1,0]
	v_pk_add_f32 v[120:121], v[90:91], -1.0 op_sel_hi:[1,0]
	v_pk_add_f32 v[122:123], v[100:101], -1.0 op_sel_hi:[1,0]
	v_pk_add_f32 v[124:125], v[98:99], -1.0 op_sel_hi:[1,0]
	v_pk_mul_f32 v[102:103], v[102:103], s[24:25] op_sel_hi:[1,0]
	v_pk_mul_f32 v[106:107], v[106:107], s[24:25] op_sel_hi:[1,0]
	v_rcp_f32_e32 v110, v114
	v_rcp_f32_e32 v111, v115
	v_rcp_f32_e32 v114, v118
	v_rcp_f32_e32 v115, v119
	v_pk_mul_f32 v[104:105], v[104:105], s[24:25] op_sel_hi:[1,0]
	v_pk_mul_f32 v[108:109], v[108:109], s[24:25] op_sel_hi:[1,0]
	v_pk_fma_f32 v[120:121], v[28:29], v[120:121], 1.0 op_sel_hi:[1,1,0]
	v_cvt_pk_f16_f32 v28, v86, v87
	v_cvt_pk_f16_f32 v29, v88, v89
	v_pk_fma_f32 v[86:87], v[26:27], v[122:123], 1.0 op_sel_hi:[1,1,0]
	v_pk_fma_f32 v[88:89], v[24:25], v[124:125], 1.0 op_sel_hi:[1,1,0]
	v_cvt_pk_f16_f32 v24, v102, v103
	v_cvt_pk_f16_f32 v26, v106, v107
	v_cvt_pk_f16_f32 v25, v104, v105
	v_cvt_pk_f16_f32 v27, v108, v109
	v_permlane16_swap_b32_e32 v24, v26
	s_nop 0
	v_permlane16_swap_b32_e32 v25, v27
	global_store_dwordx4 v[56:57], v[24:27], off sc1
	s_nop 1
	s_waitcnt lgkmcnt(0)
	v_add_f32_e32 v24, v126, v127
	v_pk_add_f32 v[118:119], v[92:93], -1.0 op_sel_hi:[1,0]
	v_pk_mul_f32 v[96:97], v[96:97], s[24:25] op_sel_hi:[1,0]
	v_pk_mul_f32 v[94:95], v[94:95], s[24:25] op_sel_hi:[1,0]
	v_mul_f32_e32 v25, 0x4f800000, v24
	v_cmp_gt_f32_e32 vcc, s35, v24
	v_pk_fma_f32 v[118:119], v[30:31], v[118:119], 1.0 op_sel_hi:[1,1,0]
	v_cvt_pk_f16_f32 v30, v94, v95
	v_cvt_pk_f16_f32 v31, v96, v97
	v_pk_add_f32 v[94:95], v[112:113], -1.0 op_sel_hi:[1,0]
	v_pk_add_f32 v[96:97], v[110:111], -1.0 op_sel_hi:[1,0]
	v_pk_add_f32 v[102:103], v[116:117], -1.0 op_sel_hi:[1,0]
	v_pk_add_f32 v[104:105], v[114:115], -1.0 op_sel_hi:[1,0]
	v_cndmask_b32_e32 v24, v24, v25, vcc
	v_pk_mul_f32 v[86:87], v[86:87], v[174:175]
	v_pk_mul_f32 v[88:89], v[88:89], v[172:173]
	v_pk_fma_f32 v[22:23], v[22:23], v[94:95], 1.0 op_sel_hi:[1,1,0]
	v_pk_fma_f32 v[20:21], v[20:21], v[96:97], 1.0 op_sel_hi:[1,1,0]
	v_pk_fma_f32 v[94:95], v[18:19], v[102:103], 1.0 op_sel_hi:[1,1,0]
	v_pk_fma_f32 v[96:97], v[16:17], v[104:105], 1.0 op_sel_hi:[1,1,0]
	v_sqrt_f32_e32 v25, v24
	v_pk_mul_f32 v[108:109], v[120:121], v[168:169]
	v_cvt_pk_f16_f32 v18, v88, v89
	v_cvt_pk_f16_f32 v19, v86, v87
	v_pk_mul_f32 v[22:23], v[22:23], v[208:209]
	v_pk_mul_f32 v[20:21], v[20:21], v[150:151]
	v_pk_mul_f32 v[86:87], v[94:95], v[198:199]
	v_pk_mul_f32 v[88:89], v[96:97], v[196:197]
	v_pk_mul_f32 v[106:107], v[118:119], v[170:171]
	v_permlane16_swap_b32_e32 v28, v30
	v_permlane16_swap_b32_e32 v29, v31
	v_cvt_pk_f16_f32 v16, v108, v109
	v_cvt_pk_f16_f32 v20, v20, v21
	v_cvt_pk_f16_f32 v21, v22, v23
	v_cvt_pk_f16_f32 v22, v88, v89
	v_cvt_pk_f16_f32 v23, v86, v87
	global_store_dwordx4 v[68:69], v[28:31], off sc1
	s_nop 1
	v_cvt_pk_f16_f32 v17, v106, v107
	v_permlane16_swap_b32_e32 v16, v18
	v_permlane16_swap_b32_e32 v20, v22
	v_permlane16_swap_b32_e32 v21, v23
	global_store_dwordx4 v[58:59], v[20:23], off sc1
	s_nop 1
	v_permlane16_swap_b32_e32 v17, v19
	global_store_dwordx4 v[66:67], v[16:19], off sc1
	s_nop 1
	v_add_u32_e32 v16, -1, v25
	v_add_u32_e32 v17, 1, v25
	v_fma_f32 v18, -v16, v25, v24
	v_fma_f32 v19, -v17, v25, v24
	v_cmp_ge_f32_e64 s[0:1], 0, v18
	s_nop 1
	v_cndmask_b32_e64 v16, v25, v16, s[0:1]
	v_cmp_lt_f32_e64 s[0:1], 0, v19
	s_nop 1
	v_cndmask_b32_e64 v16, v16, v17, s[0:1]
	v_mul_f32_e32 v17, 0x37800000, v16
	v_cndmask_b32_e32 v16, v16, v17, vcc
	v_cmp_class_f32_e32 vcc, v24, v84
	s_nop 1
	v_cndmask_b32_e32 v16, v16, v24, vcc
	v_max_f32_e32 v16, 0x2b8cbccc, v16
	v_div_scale_f32 v17, s[0:1], v16, v16, 1.0
	v_rcp_f32_e32 v19, v17
	v_div_scale_f32 v18, vcc, 1.0, v16, 1.0
	v_fma_f32 v20, -v17, v19, 1.0
	v_fmac_f32_e32 v19, v20, v19
	v_mul_f32_e32 v20, v18, v19
	v_fma_f32 v21, -v17, v20, v18
	v_fmac_f32_e32 v20, v21, v19
	v_fma_f32 v17, -v17, v20, v18
	v_div_fmas_f32 v17, v17, v19, v20
	v_div_fixup_f32 v16, v17, v16, 1.0
	v_pk_mul_f32 v[18:19], v[52:53], v[16:17] op_sel_hi:[1,0]
	v_pk_mul_f32 v[20:21], v[70:71], v[16:17] op_sel_hi:[1,0]
	v_pk_mul_f32 v[22:23], v[72:73], v[16:17] op_sel_hi:[1,0]
	v_pk_mul_f32 v[24:25], v[74:75], v[16:17] op_sel_hi:[1,0]
	v_pk_mul_f32 v[26:27], v[76:77], v[16:17] op_sel_hi:[1,0]
	v_pk_mul_f32 v[28:29], v[78:79], v[16:17] op_sel_hi:[1,0]
	v_pk_mul_f32 v[30:31], v[80:81], v[16:17] op_sel_hi:[1,0]
	v_pk_mul_f32 v[52:53], v[82:83], v[16:17] op_sel_hi:[1,0]
	v_pk_mul_f32 v[56:57], v[110:111], v[18:19]
	v_cvt_pk_f16_f32 v16, v18, v19
	v_cvt_pk_f16_f32 v17, v20, v21
	v_cvt_pk_f16_f32 v18, v22, v23
	v_cvt_pk_f16_f32 v19, v24, v25
	v_pk_mul_f32 v[58:59], v[112:113], v[20:21]
	v_pk_mul_f32 v[66:67], v[114:115], v[22:23]
	v_pk_mul_f32 v[68:69], v[116:117], v[24:25]
	v_cvt_pk_f16_f32 v20, v26, v27
	v_cvt_pk_f16_f32 v21, v28, v29
	v_cvt_pk_f16_f32 v22, v30, v31
	v_cvt_pk_f16_f32 v23, v52, v53
	v_permlane16_swap_b32_e32 v16, v18
	v_permlane16_swap_b32_e32 v17, v19
	global_store_dwordx4 v[60:61], v[16:19], off sc1
	s_nop 1
	v_pk_mul_f32 v[70:71], v[90:91], v[26:27]
	v_pk_mul_f32 v[72:73], v[92:93], v[28:29]
	v_pk_mul_f32 v[74:75], v[98:99], v[30:31]
	v_pk_mul_f32 v[76:77], v[100:101], v[52:53]
	v_cvt_pk_f16_f32 v24, v56, v57
	v_cvt_pk_f16_f32 v25, v58, v59
	v_cvt_pk_f16_f32 v26, v66, v67
	v_cvt_pk_f16_f32 v27, v68, v69
	v_permlane16_swap_b32_e32 v20, v22
	v_permlane16_swap_b32_e32 v21, v23
	global_store_dwordx4 v[64:65], v[20:23], off sc1
	s_nop 1
	v_cvt_pk_f16_f32 v28, v70, v71
	v_cvt_pk_f16_f32 v29, v72, v73
	v_cvt_pk_f16_f32 v30, v74, v75
	v_cvt_pk_f16_f32 v31, v76, v77
	v_permlane16_swap_b32_e32 v24, v26
	v_permlane16_swap_b32_e32 v25, v27
	global_store_dwordx4 v[62:63], v[24:27], off sc1
	s_nop 1
	v_permlane16_swap_b32_e32 v28, v30
	v_permlane16_swap_b32_e32 v29, v31
	global_store_dwordx4 v[54:55], v[28:31], off sc1
	s_nop 1
	s_cbranch_scc0 .LBB0_936

.Llora_done_1:
.LBB0_938:
	s_or_b64 exec, exec, s[2:3]
	s_barrier
	v_readlane_b32 s0, v250, 19
	v_readlane_b32 s1, v250, 20
	s_andn2_b64 vcc, exec, s[0:1]
	s_cbranch_vccnz .LBB0_1002
	s_add_u32 s2, s14, 0xd178400
	s_addc_u32 s3, s15, 0
	v_mbcnt_hi_u32_b32 v3, -1, v152
	s_add_u32 s9, s74, 0x4410000
	v_and_b32_e32 v0, 64, v3
	s_mov_b64 s[0:1], 0xd178400
	s_addc_u32 s34, s75, 0
	s_movk_i32 s35, 0x1ff
	s_mov_b32 s5, 0
	v_mov_b32_e32 v1, 0
	s_mov_b32 s48, 0x88888889
	s_movk_i32 s49, 0x1000
	s_movk_i32 s52, 0x1d00
	s_mov_b64 s[6:7], 0x1100
	s_mov_b32 s53, 0x10000
	v_xor_b32_e32 v67, 16, v3
	v_add_u32_e32 v80, 64, v0
	v_xor_b32_e32 v81, 32, v3
	s_mov_b32 s8, 0x3c800000
	s_mov_b32 s54, 0x800000
	s_add_i32 s55, 0, 0x11e00
	v_mov_b32_e32 v82, 0x4000
	v_mov_b32_e32 v2, 0x3727c5ac
	s_mov_b32 s56, s91
	s_branch .LBB0_942

	.amdhsa_kernel _Z8fwd_mega6Params
		.amdhsa_group_segment_fixed_size 10240
		.amdhsa_private_segment_fixed_size 0
		.amdhsa_kernarg_size 488
		.amdhsa_user_sgpr_count 2
		.amdhsa_user_sgpr_dispatch_ptr 0
		.amdhsa_user_sgpr_queue_ptr 0
		.amdhsa_user_sgpr_kernarg_segment_ptr 1
		.amdhsa_user_sgpr_dispatch_id 0
		.amdhsa_user_sgpr_kernarg_preload_length 0
		.amdhsa_user_sgpr_kernarg_preload_offset 0
		.amdhsa_user_sgpr_private_segment_size 0
		.amdhsa_uses_dynamic_stack 0
		.amdhsa_enable_private_segment 0
		.amdhsa_system_sgpr_workgroup_id_x 1
		.amdhsa_system_sgpr_workgroup_id_y 0
		.amdhsa_system_sgpr_workgroup_id_z 0
		.amdhsa_system_sgpr_workgroup_info 0
		.amdhsa_system_vgpr_workitem_id 2
		.amdhsa_next_free_vgpr 251
		.amdhsa_next_free_sgpr 102
		.amdhsa_accum_offset 252
		.amdhsa_reserve_vcc 1
		.amdhsa_float_round_mode_32 0
		.amdhsa_float_round_mode_16_64 0
		.amdhsa_float_denorm_mode_32 3
		.amdhsa_float_denorm_mode_16_64 3
		.amdhsa_dx10_clamp 1
		.amdhsa_ieee_mode 1
		.amdhsa_fp16_overflow 0
		.amdhsa_tg_split 0
		.amdhsa_exception_fp_ieee_invalid_op 0
		.amdhsa_exception_fp_denorm_src 0
		.amdhsa_exception_fp_ieee_div_zero 0
		.amdhsa_exception_fp_ieee_overflow 0
		.amdhsa_exception_fp_ieee_underflow 0
		.amdhsa_exception_fp_ieee_inexact 0
		.amdhsa_exception_int_div_zero 0
	.end_amdhsa_kernel

amdhsa.kernels:
  - .agpr_count:     0
    .args:
      - .offset:         0
        .size:           232
        .value_kind:     by_value
      - .offset:         232
        .size:           4
        .value_kind:     hidden_block_count_x
      - .offset:         236
        .size:           4
        .value_kind:     hidden_block_count_y
      - .offset:         240
        .size:           4
        .value_kind:     hidden_block_count_z
      - .offset:         244
        .size:           2
        .value_kind:     hidden_group_size_x
      - .offset:         246
        .size:           2
        .value_kind:     hidden_group_size_y
      - .offset:         248
        .size:           2
        .value_kind:     hidden_group_size_z
      - .offset:         250
        .size:           2
        .value_kind:     hidden_remainder_x
      - .offset:         252
        .size:           2
        .value_kind:     hidden_remainder_y
      - .offset:         254
        .size:           2
        .value_kind:     hidden_remainder_z
      - .offset:         272
        .size:           8
        .value_kind:     hidden_global_offset_x
      - .offset:         280
        .size:           8
        .value_kind:     hidden_global_offset_y
      - .offset:         288
        .size:           8
        .value_kind:     hidden_global_offset_z
      - .offset:         296
        .size:           2
        .value_kind:     hidden_grid_dims
      - .offset:         320
        .size:           8
        .value_kind:     hidden_multigrid_sync_arg
      - .offset:         352
        .size:           4
        .value_kind:     hidden_dynamic_lds_size
    .group_segment_fixed_size: 10240
    .kernarg_segment_align: 8
    .kernarg_segment_size: 488
    .language:       OpenCL C
    .language_version:
      - 2
      - 0
    .max_flat_workgroup_size: 512
    .name:           _Z8fwd_mega6Params
    .private_segment_fixed_size: 0
    .sgpr_count:     108
    .sgpr_spill_count: 38
    .symbol:         _Z8fwd_mega6Params.kd
    .uniform_work_group_size: 1
    .uses_dynamic_stack: false
    .vgpr_count:     251
    .vgpr_spill_count: 0
    .wavefront_size: 64
  - .agpr_count:     0
    .args:
      - .offset:         0
        .size:           232
        .value_kind:     by_value
      - .offset:         232
        .size:           4
        .value_kind:     by_value
      - .offset:         240
        .size:           4
        .value_kind:     hidden_block_count_x
      - .offset:         244
        .size:           4
        .value_kind:     hidden_block_count_y
      - .offset:         248
        .size:           4
        .value_kind:     hidden_block_count_z
      - .offset:         252
        .size:           2
        .value_kind:     hidden_group_size_x
      - .offset:         254
        .size:           2
        .value_kind:     hidden_group_size_y
      - .offset:         256
        .size:           2
        .value_kind:     hidden_group_size_z
      - .offset:         258
        .size:           2
        .value_kind:     hidden_remainder_x
      - .offset:         260
        .size:           2
        .value_kind:     hidden_remainder_y
      - .offset:         262
        .size:           2
        .value_kind:     hidden_remainder_z
      - .offset:         280
        .size:           8
        .value_kind:     hidden_global_offset_x
      - .offset:         288
        .size:           8
        .value_kind:     hidden_global_offset_y
      - .offset:         296
        .size:           8
        .value_kind:     hidden_global_offset_z
      - .offset:         304
        .size:           2
        .value_kind:     hidden_grid_dims
      - .offset:         360
        .size:           4
        .value_kind:     hidden_dynamic_lds_size
    .group_segment_fixed_size: 0
    .kernarg_segment_align: 8
    .kernarg_segment_size: 496
    .language:       OpenCL C
    .language_version:
      - 2
      - 0
    .max_flat_workgroup_size: 512
    .name:           _Z9fwd_phase6Paramsi
    .private_segment_fixed_size: 0
    .sgpr_count:     106
    .sgpr_spill_count: 0
    .symbol:         _Z9fwd_phase6Paramsi.kd
    .uniform_work_group_size: 1
    .uses_dynamic_stack: false
    .vgpr_count:     249
    .vgpr_spill_count: 0
    .wavefront_size: 64
